# unrolled scan loop: slot-release flag written every two groups, one pflag check per two groups
# speedup vs baseline: 1.0141x; 1.0116x over previous
.Lc_top:
	v_fma_mix_f32 v84, v84, v4, v100 op_sel:[0,0,0] op_sel_hi:[0,1,0]
	v_fma_mix_f32 v85, v85, v4, v101 op_sel:[0,1,0] op_sel_hi:[0,1,0]
	v_add_f32_dpp v98, v98, v98 row_half_mirror row_mask:0xf bank_mask:0xf bound_ctrl:1
	v_fma_mix_f32 v86, v86, v5, v102 op_sel:[0,0,0] op_sel_hi:[0,1,0]
	v_fma_mix_f32 v87, v87, v5, v103 op_sel:[0,1,0] op_sel_hi:[0,1,0]
	v_add_f32_dpp v98, v98, v98 row_mirror row_mask:0xf bank_mask:0xf bound_ctrl:1
	v_fma_mix_f32 v84, -v98, v12, v84 op_sel:[0,0,0] op_sel_hi:[0,1,0]
	v_fma_mix_f32 v85, -v98, v12, v85 op_sel:[0,1,0] op_sel_hi:[0,1,0]
	v_fma_mix_f32 v86, -v98, v13, v86 op_sel:[0,0,0] op_sel_hi:[0,1,0]
	v_fma_mix_f32 v87, -v98, v13, v87 op_sel:[0,1,0] op_sel_hi:[0,1,0]
	v_fma_mix_f32 v99, v84, v10, 0 op_sel:[0,0,0] op_sel_hi:[0,1,0]
	v_fma_mix_f32 v96, v84, v0, 0 op_sel:[0,0,0] op_sel_hi:[0,1,0]
	v_fma_mix_f32 v99, v85, v10, v99 op_sel:[0,1,0] op_sel_hi:[0,1,0]
	v_fma_mix_f32 v96, v85, v0, v96 op_sel:[0,1,0] op_sel_hi:[0,1,0]
	v_fma_mix_f32 v99, v86, v11, v99 op_sel:[0,0,0] op_sel_hi:[0,1,0]
	v_fma_mix_f32 v96, v86, v1, v96 op_sel:[0,0,0] op_sel_hi:[0,1,0]
	v_fma_mix_f32 v99, v87, v11, v99 op_sel:[0,1,0] op_sel_hi:[0,1,0]
	v_fma_mix_f32 v96, v87, v1, v96 op_sel:[0,1,0] op_sel_hi:[0,1,0]
	v_fma_mix_f32 v101, v88, v18, 0 op_sel:[1,0,0] op_sel_hi:[1,1,0]
	v_fma_mix_f32 v102, v88, v18, 0 op_sel:[1,1,0] op_sel_hi:[1,1,0]
	v_add_f32_dpp v99, v99, v99 quad_perm:[1,0,3,2] row_mask:0xf bank_mask:0xf bound_ctrl:1
	v_fma_mix_f32 v103, v88, v19, 0 op_sel:[1,0,0] op_sel_hi:[1,1,0]
	v_fma_mix_f32 v104, v88, v19, 0 op_sel:[1,1,0] op_sel_hi:[1,1,0]
	v_add_f32_dpp v99, v99, v99 quad_perm:[2,3,0,1] row_mask:0xf bank_mask:0xf bound_ctrl:1
	v_fma_mix_f32 v84, v84, v8, v101 op_sel:[0,0,0] op_sel_hi:[0,1,0]
	v_fma_mix_f32 v85, v85, v8, v102 op_sel:[0,1,0] op_sel_hi:[0,1,0]
	v_add_f32_dpp v99, v99, v99 row_half_mirror row_mask:0xf bank_mask:0xf bound_ctrl:1
	v_fma_mix_f32 v86, v86, v9, v103 op_sel:[0,0,0] op_sel_hi:[0,1,0]
	v_fma_mix_f32 v87, v87, v9, v104 op_sel:[0,1,0] op_sel_hi:[0,1,0]
	v_add_f32_dpp v99, v99, v99 row_mirror row_mask:0xf bank_mask:0xf bound_ctrl:1
	v_fma_mix_f32 v84, -v99, v16, v84 op_sel:[0,0,0] op_sel_hi:[0,1,0]
	v_fma_mix_f32 v85, -v99, v16, v85 op_sel:[0,1,0] op_sel_hi:[0,1,0]
	v_fma_mix_f32 v86, -v99, v17, v86 op_sel:[0,0,0] op_sel_hi:[0,1,0]
	v_fma_mix_f32 v87, -v99, v17, v87 op_sel:[0,1,0] op_sel_hi:[0,1,0]
	v_fma_mix_f32 v100, v84, v26, 0 op_sel:[0,0,0] op_sel_hi:[0,1,0]
	v_fma_mix_f32 v97, v84, v2, 0 op_sel:[0,0,0] op_sel_hi:[0,1,0]
	v_fma_mix_f32 v100, v85, v26, v100 op_sel:[0,1,0] op_sel_hi:[0,1,0]
	v_fma_mix_f32 v97, v85, v2, v97 op_sel:[0,1,0] op_sel_hi:[0,1,0]
	v_fma_mix_f32 v100, v86, v27, v100 op_sel:[0,0,0] op_sel_hi:[0,1,0]
	v_fma_mix_f32 v97, v86, v3, v97 op_sel:[0,0,0] op_sel_hi:[0,1,0]
	v_fma_mix_f32 v100, v87, v27, v100 op_sel:[0,1,0] op_sel_hi:[0,1,0]
	v_fma_mix_f32 v97, v87, v3, v97 op_sel:[0,1,0] op_sel_hi:[0,1,0]
	v_fma_mix_f32 v102, v89, v34, 0 op_sel:[0,0,0] op_sel_hi:[1,1,0]
	v_fma_mix_f32 v103, v89, v34, 0 op_sel:[0,1,0] op_sel_hi:[1,1,0]
	v_add_f32_dpp v100, v100, v100 quad_perm:[1,0,3,2] row_mask:0xf bank_mask:0xf bound_ctrl:1
	v_fma_mix_f32 v104, v89, v35, 0 op_sel:[0,0,0] op_sel_hi:[1,1,0]
	v_fma_mix_f32 v105, v89, v35, 0 op_sel:[0,1,0] op_sel_hi:[1,1,0]
	v_add_f32_dpp v100, v100, v100 quad_perm:[2,3,0,1] row_mask:0xf bank_mask:0xf bound_ctrl:1
	v_fma_mix_f32 v84, v84, v24, v102 op_sel:[0,0,0] op_sel_hi:[0,1,0]
	v_fma_mix_f32 v85, v85, v24, v103 op_sel:[0,1,0] op_sel_hi:[0,1,0]
	v_add_f32_dpp v100, v100, v100 row_half_mirror row_mask:0xf bank_mask:0xf bound_ctrl:1
	v_fma_mix_f32 v86, v86, v25, v104 op_sel:[0,0,0] op_sel_hi:[0,1,0]
	v_fma_mix_f32 v87, v87, v25, v105 op_sel:[0,1,0] op_sel_hi:[0,1,0]
	v_add_f32_dpp v100, v100, v100 row_mirror row_mask:0xf bank_mask:0xf bound_ctrl:1
	v_fma_mix_f32 v84, -v100, v32, v84 op_sel:[0,0,0] op_sel_hi:[0,1,0]
	v_fma_mix_f32 v85, -v100, v32, v85 op_sel:[0,1,0] op_sel_hi:[0,1,0]
	v_fma_mix_f32 v86, -v100, v33, v86 op_sel:[0,0,0] op_sel_hi:[0,1,0]
	v_fma_mix_f32 v87, -v100, v33, v87 op_sel:[0,1,0] op_sel_hi:[0,1,0]
	v_fma_mix_f32 v101, v84, v30, 0 op_sel:[0,0,0] op_sel_hi:[0,1,0]
	v_fma_mix_f32 v98, v84, v20, 0 op_sel:[0,0,0] op_sel_hi:[0,1,0]
	v_fma_mix_f32 v101, v85, v30, v101 op_sel:[0,1,0] op_sel_hi:[0,1,0]
	v_fma_mix_f32 v98, v85, v20, v98 op_sel:[0,1,0] op_sel_hi:[0,1,0]
	v_fma_mix_f32 v101, v86, v31, v101 op_sel:[0,0,0] op_sel_hi:[0,1,0]
	v_fma_mix_f32 v98, v86, v21, v98 op_sel:[0,0,0] op_sel_hi:[0,1,0]
	v_fma_mix_f32 v101, v87, v31, v101 op_sel:[0,1,0] op_sel_hi:[0,1,0]
	v_fma_mix_f32 v98, v87, v21, v98 op_sel:[0,1,0] op_sel_hi:[0,1,0]
	v_fma_mix_f32 v103, v89, v38, 0 op_sel:[1,0,0] op_sel_hi:[1,1,0]
	v_fma_mix_f32 v104, v89, v38, 0 op_sel:[1,1,0] op_sel_hi:[1,1,0]
	v_add_f32_dpp v101, v101, v101 quad_perm:[1,0,3,2] row_mask:0xf bank_mask:0xf bound_ctrl:1
	v_fma_mix_f32 v105, v89, v39, 0 op_sel:[1,0,0] op_sel_hi:[1,1,0]
	v_fma_mix_f32 v119, v89, v39, 0 op_sel:[1,1,0] op_sel_hi:[1,1,0]
	v_add_f32_dpp v101, v101, v101 quad_perm:[2,3,0,1] row_mask:0xf bank_mask:0xf bound_ctrl:1
	v_fma_mix_f32 v84, v84, v28, v103 op_sel:[0,0,0] op_sel_hi:[0,1,0]
	v_fma_mix_f32 v85, v85, v28, v104 op_sel:[0,1,0] op_sel_hi:[0,1,0]
	v_add_f32_dpp v101, v101, v101 row_half_mirror row_mask:0xf bank_mask:0xf bound_ctrl:1
	v_fma_mix_f32 v86, v86, v29, v105 op_sel:[0,0,0] op_sel_hi:[0,1,0]
	v_fma_mix_f32 v87, v87, v29, v119 op_sel:[0,1,0] op_sel_hi:[0,1,0]
	v_add_f32_dpp v101, v101, v101 row_mirror row_mask:0xf bank_mask:0xf bound_ctrl:1
	v_fma_mix_f32 v84, -v101, v36, v84 op_sel:[0,0,0] op_sel_hi:[0,1,0]
	v_fma_mix_f32 v85, -v101, v36, v85 op_sel:[0,1,0] op_sel_hi:[0,1,0]
	v_fma_mix_f32 v86, -v101, v37, v86 op_sel:[0,0,0] op_sel_hi:[0,1,0]
	v_fma_mix_f32 v87, -v101, v37, v87 op_sel:[0,1,0] op_sel_hi:[0,1,0]
	v_fma_mix_f32 v99, v84, v22, 0 op_sel:[0,0,0] op_sel_hi:[0,1,0]
	v_cndmask_b32_e64 v187, v97, v96, s[38:39]
	v_fma_mix_f32 v99, v85, v22, v99 op_sel:[0,1,0] op_sel_hi:[0,1,0]
	v_cndmask_b32_e64 v188, v96, v97, s[38:39]
	v_fma_mix_f32 v99, v86, v23, v99 op_sel:[0,0,0] op_sel_hi:[0,1,0]
	v_fma_mix_f32 v99, v87, v23, v99 op_sel:[0,1,0] op_sel_hi:[0,1,0]
	v_cndmask_b32_e64 v189, v99, v98, s[38:39]
	v_cndmask_b32_e64 v190, v98, v99, s[38:39]
	s_waitcnt lgkmcnt(0)
	v_fma_mix_f32 v98, v84, v74, 0 op_sel:[0,0,0] op_sel_hi:[0,1,0]
	v_fma_mix_f32 v98, v85, v74, v98 op_sel:[0,1,0] op_sel_hi:[0,1,0]
	v_add_f32_dpp v188, v188, v187 quad_perm:[1,0,3,2] row_mask:0xf bank_mask:0xf bound_ctrl:1
	v_add_f32_dpp v189, v190, v189 quad_perm:[1,0,3,2] row_mask:0xf bank_mask:0xf bound_ctrl:1
	v_fma_mix_f32 v98, v86, v75, v98 op_sel:[0,0,0] op_sel_hi:[0,1,0]
	v_fma_mix_f32 v98, v87, v75, v98 op_sel:[0,1,0] op_sel_hi:[0,1,0]
	v_cndmask_b32_e64 v191, v189, v188, s[40:41]
	v_cndmask_b32_e64 v192, v188, v189, s[40:41]
	v_fma_mix_f32 v100, v92, v78, 0 op_sel:[0,0,0] op_sel_hi:[1,1,0]
	v_fma_mix_f32 v101, v92, v78, 0 op_sel:[0,1,0] op_sel_hi:[1,1,0]
	v_add_f32_dpp v192, v192, v191 quad_perm:[2,3,0,1] row_mask:0xf bank_mask:0xf bound_ctrl:1
	v_add_f32_dpp v98, v98, v98 quad_perm:[1,0,3,2] row_mask:0xf bank_mask:0xf bound_ctrl:1
	v_fma_mix_f32 v102, v92, v79, 0 op_sel:[0,0,0] op_sel_hi:[1,1,0]
	v_add_f32_dpp v192, v192, v192 row_ror:4 row_mask:0xf bank_mask:0xf bound_ctrl:1
	v_fma_mix_f32 v103, v92, v79, 0 op_sel:[0,1,0] op_sel_hi:[1,1,0]
	v_add_f32_dpp v98, v98, v98 quad_perm:[2,3,0,1] row_mask:0xf bank_mask:0xf bound_ctrl:1
	v_add_f32_dpp v192, v192, v192 row_ror:8 row_mask:0xf bank_mask:0xf bound_ctrl:1
	v_cvt_f16_f32_e32 v192, v192
	global_store_short v83, v192, s[36:37]
	s_add_u32 s36, s36, s44
	s_addc_u32 s37, s37, s45
	s_cmp_gt_i32 s35, 3
	s_cbranch_scc0 .Lc_poll_A0
.Lc_ret_A0:
	ds_read_b128 v[0:3], v194 offset:8192
	ds_read_b128 v[4:7], v194 offset:6144
	ds_read_b128 v[8:11], v194 offset:6400
	ds_read_b128 v[12:15], v194 offset:7168
	ds_read_b128 v[16:19], v194 offset:7424
	ds_read_b128 v[20:23], v194 offset:8448
	ds_read_b128 v[24:27], v194 offset:6656
	ds_read_b128 v[28:31], v194 offset:6912
	ds_read_b128 v[32:35], v194 offset:7680
	ds_read_b128 v[36:39], v194 offset:7936
	ds_read_b64 v[88:89], v195 offset:8704
	v_fma_mix_f32 v84, v84, v72, v100 op_sel:[0,0,0] op_sel_hi:[0,1,0]
	v_fma_mix_f32 v85, v85, v72, v101 op_sel:[0,1,0] op_sel_hi:[0,1,0]
	v_add_f32_dpp v98, v98, v98 row_half_mirror row_mask:0xf bank_mask:0xf bound_ctrl:1
	v_fma_mix_f32 v86, v86, v73, v102 op_sel:[0,0,0] op_sel_hi:[0,1,0]
	v_fma_mix_f32 v87, v87, v73, v103 op_sel:[0,1,0] op_sel_hi:[0,1,0]
	v_add_f32_dpp v98, v98, v98 row_mirror row_mask:0xf bank_mask:0xf bound_ctrl:1
	v_fma_mix_f32 v84, -v98, v76, v84 op_sel:[0,0,0] op_sel_hi:[0,1,0]
	v_fma_mix_f32 v85, -v98, v76, v85 op_sel:[0,1,0] op_sel_hi:[0,1,0]
	v_fma_mix_f32 v86, -v98, v77, v86 op_sel:[0,0,0] op_sel_hi:[0,1,0]
	v_fma_mix_f32 v87, -v98, v77, v87 op_sel:[0,1,0] op_sel_hi:[0,1,0]
	v_fma_mix_f32 v73, v84, v66, 0 op_sel:[0,0,0] op_sel_hi:[0,1,0]
	v_fma_mix_f32 v97, v84, v56, 0 op_sel:[0,0,0] op_sel_hi:[0,1,0]
	v_fma_mix_f32 v73, v85, v66, v73 op_sel:[0,1,0] op_sel_hi:[0,1,0]
	v_fma_mix_f32 v56, v85, v56, v97 op_sel:[0,1,0] op_sel_hi:[0,1,0]
	v_fma_mix_f32 v73, v86, v67, v73 op_sel:[0,0,0] op_sel_hi:[0,1,0]
	v_fma_mix_f32 v56, v86, v57, v56 op_sel:[0,0,0] op_sel_hi:[0,1,0]
	v_fma_mix_f32 v73, v87, v67, v73 op_sel:[0,1,0] op_sel_hi:[0,1,0]
	v_fma_mix_f32 v56, v87, v57, v56 op_sel:[0,1,0] op_sel_hi:[0,1,0]
	v_fma_mix_f32 v75, v92, v70, 0 op_sel:[1,0,0] op_sel_hi:[1,1,0]
	v_fma_mix_f32 v76, v92, v70, 0 op_sel:[1,1,0] op_sel_hi:[1,1,0]
	v_add_f32_dpp v73, v73, v73 quad_perm:[1,0,3,2] row_mask:0xf bank_mask:0xf bound_ctrl:1
	v_fma_mix_f32 v77, v92, v71, 0 op_sel:[1,0,0] op_sel_hi:[1,1,0]
	v_fma_mix_f32 v78, v92, v71, 0 op_sel:[1,1,0] op_sel_hi:[1,1,0]
	v_add_f32_dpp v73, v73, v73 quad_perm:[2,3,0,1] row_mask:0xf bank_mask:0xf bound_ctrl:1
	v_fma_mix_f32 v84, v84, v64, v75 op_sel:[0,0,0] op_sel_hi:[0,1,0]
	v_fma_mix_f32 v85, v85, v64, v76 op_sel:[0,1,0] op_sel_hi:[0,1,0]
	v_add_f32_dpp v73, v73, v73 row_half_mirror row_mask:0xf bank_mask:0xf bound_ctrl:1
	v_fma_mix_f32 v86, v86, v65, v77 op_sel:[0,0,0] op_sel_hi:[0,1,0]
	v_fma_mix_f32 v87, v87, v65, v78 op_sel:[0,1,0] op_sel_hi:[0,1,0]
	v_add_f32_dpp v73, v73, v73 row_mirror row_mask:0xf bank_mask:0xf bound_ctrl:1
	v_fma_mix_f32 v84, -v73, v68, v84 op_sel:[0,0,0] op_sel_hi:[0,1,0]
	v_fma_mix_f32 v85, -v73, v68, v85 op_sel:[0,1,0] op_sel_hi:[0,1,0]
	v_fma_mix_f32 v86, -v73, v69, v86 op_sel:[0,0,0] op_sel_hi:[0,1,0]
	v_fma_mix_f32 v87, -v73, v69, v87 op_sel:[0,1,0] op_sel_hi:[0,1,0]
	v_fma_mix_f32 v64, v84, v54, 0 op_sel:[0,0,0] op_sel_hi:[0,1,0]
	v_fma_mix_f32 v57, v84, v58, 0 op_sel:[0,0,0] op_sel_hi:[0,1,0]
	v_fma_mix_f32 v64, v85, v54, v64 op_sel:[0,1,0] op_sel_hi:[0,1,0]
	v_fma_mix_f32 v57, v85, v58, v57 op_sel:[0,1,0] op_sel_hi:[0,1,0]
	v_fma_mix_f32 v64, v86, v55, v64 op_sel:[0,0,0] op_sel_hi:[0,1,0]
	v_fma_mix_f32 v57, v86, v59, v57 op_sel:[0,0,0] op_sel_hi:[0,1,0]
	v_fma_mix_f32 v64, v87, v55, v64 op_sel:[0,1,0] op_sel_hi:[0,1,0]
	v_fma_mix_f32 v57, v87, v59, v57 op_sel:[0,1,0] op_sel_hi:[0,1,0]
	v_fma_mix_f32 v66, v93, v62, 0 op_sel:[0,0,0] op_sel_hi:[1,1,0]
	v_fma_mix_f32 v67, v93, v62, 0 op_sel:[0,1,0] op_sel_hi:[1,1,0]
	v_add_f32_dpp v64, v64, v64 quad_perm:[1,0,3,2] row_mask:0xf bank_mask:0xf bound_ctrl:1
	v_fma_mix_f32 v68, v93, v63, 0 op_sel:[0,0,0] op_sel_hi:[1,1,0]
	v_fma_mix_f32 v69, v93, v63, 0 op_sel:[0,1,0] op_sel_hi:[1,1,0]
	v_add_f32_dpp v64, v64, v64 quad_perm:[2,3,0,1] row_mask:0xf bank_mask:0xf bound_ctrl:1
	v_fma_mix_f32 v84, v84, v52, v66 op_sel:[0,0,0] op_sel_hi:[0,1,0]
	v_fma_mix_f32 v85, v85, v52, v67 op_sel:[0,1,0] op_sel_hi:[0,1,0]
	v_add_f32_dpp v64, v64, v64 row_half_mirror row_mask:0xf bank_mask:0xf bound_ctrl:1
	v_fma_mix_f32 v86, v86, v53, v68 op_sel:[0,0,0] op_sel_hi:[0,1,0]
	v_fma_mix_f32 v87, v87, v53, v69 op_sel:[0,1,0] op_sel_hi:[0,1,0]
	v_add_f32_dpp v64, v64, v64 row_mirror row_mask:0xf bank_mask:0xf bound_ctrl:1
	v_fma_mix_f32 v84, -v64, v60, v84 op_sel:[0,0,0] op_sel_hi:[0,1,0]
	v_fma_mix_f32 v85, -v64, v60, v85 op_sel:[0,1,0] op_sel_hi:[0,1,0]
	v_fma_mix_f32 v86, -v64, v61, v86 op_sel:[0,0,0] op_sel_hi:[0,1,0]
	v_fma_mix_f32 v87, -v64, v61, v87 op_sel:[0,1,0] op_sel_hi:[0,1,0]
	v_fma_mix_f32 v53, v84, v46, 0 op_sel:[0,0,0] op_sel_hi:[0,1,0]
	v_fma_mix_f32 v59, v84, v40, 0 op_sel:[0,0,0] op_sel_hi:[0,1,0]
	v_fma_mix_f32 v53, v85, v46, v53 op_sel:[0,1,0] op_sel_hi:[0,1,0]
	v_fma_mix_f32 v40, v85, v40, v59 op_sel:[0,1,0] op_sel_hi:[0,1,0]
	v_fma_mix_f32 v53, v86, v47, v53 op_sel:[0,0,0] op_sel_hi:[0,1,0]
	v_fma_mix_f32 v40, v86, v41, v40 op_sel:[0,0,0] op_sel_hi:[0,1,0]
	v_fma_mix_f32 v53, v87, v47, v53 op_sel:[0,1,0] op_sel_hi:[0,1,0]
	v_fma_mix_f32 v40, v87, v41, v40 op_sel:[0,1,0] op_sel_hi:[0,1,0]
	v_fma_mix_f32 v55, v93, v50, 0 op_sel:[1,0,0] op_sel_hi:[1,1,0]
	v_fma_mix_f32 v58, v93, v50, 0 op_sel:[1,1,0] op_sel_hi:[1,1,0]
	v_add_f32_dpp v53, v53, v53 quad_perm:[1,0,3,2] row_mask:0xf bank_mask:0xf bound_ctrl:1
	v_fma_mix_f32 v59, v93, v51, 0 op_sel:[1,0,0] op_sel_hi:[1,1,0]
	v_fma_mix_f32 v60, v93, v51, 0 op_sel:[1,1,0] op_sel_hi:[1,1,0]
	v_add_f32_dpp v53, v53, v53 quad_perm:[2,3,0,1] row_mask:0xf bank_mask:0xf bound_ctrl:1
	v_fma_mix_f32 v84, v84, v44, v55 op_sel:[0,0,0] op_sel_hi:[0,1,0]
	v_fma_mix_f32 v85, v85, v44, v58 op_sel:[0,1,0] op_sel_hi:[0,1,0]
	v_add_f32_dpp v53, v53, v53 row_half_mirror row_mask:0xf bank_mask:0xf bound_ctrl:1
	v_fma_mix_f32 v86, v86, v45, v59 op_sel:[0,0,0] op_sel_hi:[0,1,0]
	v_fma_mix_f32 v87, v87, v45, v60 op_sel:[0,1,0] op_sel_hi:[0,1,0]
	v_add_f32_dpp v53, v53, v53 row_mirror row_mask:0xf bank_mask:0xf bound_ctrl:1
	v_fma_mix_f32 v84, -v53, v48, v84 op_sel:[0,0,0] op_sel_hi:[0,1,0]
	v_fma_mix_f32 v85, -v53, v48, v85 op_sel:[0,1,0] op_sel_hi:[0,1,0]
	v_fma_mix_f32 v86, -v53, v49, v86 op_sel:[0,0,0] op_sel_hi:[0,1,0]
	v_fma_mix_f32 v87, -v53, v49, v87 op_sel:[0,1,0] op_sel_hi:[0,1,0]
	v_fma_mix_f32 v41, v84, v42, 0 op_sel:[0,0,0] op_sel_hi:[0,1,0]
	v_add_u32_e32 v173, 2, v193
	v_fma_mix_f32 v41, v85, v42, v41 op_sel:[0,1,0] op_sel_hi:[0,1,0]
	ds_write_b32 v172, v173 offset:49216
	v_fma_mix_f32 v41, v86, v43, v41 op_sel:[0,0,0] op_sel_hi:[0,1,0]
	v_cndmask_b32_e64 v187, v57, v56, s[38:39]
	v_fma_mix_f32 v41, v87, v43, v41 op_sel:[0,1,0] op_sel_hi:[0,1,0]
	v_cndmask_b32_e64 v188, v56, v57, s[38:39]
	v_cndmask_b32_e64 v189, v41, v40, s[38:39]
	v_cndmask_b32_e64 v190, v40, v41, s[38:39]
	s_waitcnt lgkmcnt(1)
	v_fma_mix_f32 v98, v84, v6, 0 op_sel:[0,0,0] op_sel_hi:[0,1,0]
	v_fma_mix_f32 v98, v85, v6, v98 op_sel:[0,1,0] op_sel_hi:[0,1,0]
	v_add_f32_dpp v188, v188, v187 quad_perm:[1,0,3,2] row_mask:0xf bank_mask:0xf bound_ctrl:1
	v_add_f32_dpp v189, v190, v189 quad_perm:[1,0,3,2] row_mask:0xf bank_mask:0xf bound_ctrl:1
	v_fma_mix_f32 v98, v86, v7, v98 op_sel:[0,0,0] op_sel_hi:[0,1,0]
	v_fma_mix_f32 v98, v87, v7, v98 op_sel:[0,1,0] op_sel_hi:[0,1,0]
	v_cndmask_b32_e64 v191, v189, v188, s[40:41]
	v_cndmask_b32_e64 v192, v188, v189, s[40:41]
	v_fma_mix_f32 v100, v88, v14, 0 op_sel:[0,0,0] op_sel_hi:[1,1,0]
	v_fma_mix_f32 v101, v88, v14, 0 op_sel:[0,1,0] op_sel_hi:[1,1,0]
	v_add_f32_dpp v192, v192, v191 quad_perm:[2,3,0,1] row_mask:0xf bank_mask:0xf bound_ctrl:1
	v_add_f32_dpp v98, v98, v98 quad_perm:[1,0,3,2] row_mask:0xf bank_mask:0xf bound_ctrl:1
	v_fma_mix_f32 v102, v88, v15, 0 op_sel:[0,0,0] op_sel_hi:[1,1,0]
	v_add_f32_dpp v192, v192, v192 row_ror:4 row_mask:0xf bank_mask:0xf bound_ctrl:1
	v_fma_mix_f32 v103, v88, v15, 0 op_sel:[0,1,0] op_sel_hi:[1,1,0]
	v_add_f32_dpp v98, v98, v98 quad_perm:[2,3,0,1] row_mask:0xf bank_mask:0xf bound_ctrl:1
	v_add_f32_dpp v192, v192, v192 row_ror:8 row_mask:0xf bank_mask:0xf bound_ctrl:1
	v_cvt_f16_f32_e32 v192, v192
	global_store_short v83, v192, s[36:37]
	s_add_u32 s36, s36, s44
	s_addc_u32 s37, s37, s45
	ds_read_b128 v[56:59], v194 offset:11264
	ds_read_b128 v[72:75], v194 offset:9216
	ds_read_b128 v[64:67], v194 offset:9472
	ds_read_b128 v[76:79], v194 offset:10240
	ds_read_b128 v[68:71], v194 offset:10496
	ds_read_b128 v[40:43], v194 offset:11520
	ds_read_b128 v[52:55], v194 offset:9728
	ds_read_b128 v[44:47], v194 offset:9984
	ds_read_b128 v[60:63], v194 offset:10752
	ds_read_b128 v[48:51], v194 offset:11008
	ds_read_b64 v[92:93], v195 offset:11776
	v_fma_mix_f32 v84, v84, v4, v100 op_sel:[0,0,0] op_sel_hi:[0,1,0]
	v_fma_mix_f32 v85, v85, v4, v101 op_sel:[0,1,0] op_sel_hi:[0,1,0]
	v_add_f32_dpp v98, v98, v98 row_half_mirror row_mask:0xf bank_mask:0xf bound_ctrl:1
	v_fma_mix_f32 v86, v86, v5, v102 op_sel:[0,0,0] op_sel_hi:[0,1,0]
	v_fma_mix_f32 v87, v87, v5, v103 op_sel:[0,1,0] op_sel_hi:[0,1,0]
	v_add_f32_dpp v98, v98, v98 row_mirror row_mask:0xf bank_mask:0xf bound_ctrl:1
	v_fma_mix_f32 v84, -v98, v12, v84 op_sel:[0,0,0] op_sel_hi:[0,1,0]
	v_fma_mix_f32 v85, -v98, v12, v85 op_sel:[0,1,0] op_sel_hi:[0,1,0]
	v_fma_mix_f32 v86, -v98, v13, v86 op_sel:[0,0,0] op_sel_hi:[0,1,0]
	v_fma_mix_f32 v87, -v98, v13, v87 op_sel:[0,1,0] op_sel_hi:[0,1,0]
	v_fma_mix_f32 v99, v84, v10, 0 op_sel:[0,0,0] op_sel_hi:[0,1,0]
	v_fma_mix_f32 v96, v84, v0, 0 op_sel:[0,0,0] op_sel_hi:[0,1,0]
	v_fma_mix_f32 v99, v85, v10, v99 op_sel:[0,1,0] op_sel_hi:[0,1,0]
	v_fma_mix_f32 v96, v85, v0, v96 op_sel:[0,1,0] op_sel_hi:[0,1,0]
	v_fma_mix_f32 v99, v86, v11, v99 op_sel:[0,0,0] op_sel_hi:[0,1,0]
	v_fma_mix_f32 v96, v86, v1, v96 op_sel:[0,0,0] op_sel_hi:[0,1,0]
	v_fma_mix_f32 v99, v87, v11, v99 op_sel:[0,1,0] op_sel_hi:[0,1,0]
	v_fma_mix_f32 v96, v87, v1, v96 op_sel:[0,1,0] op_sel_hi:[0,1,0]
	v_fma_mix_f32 v101, v88, v18, 0 op_sel:[1,0,0] op_sel_hi:[1,1,0]
	v_fma_mix_f32 v102, v88, v18, 0 op_sel:[1,1,0] op_sel_hi:[1,1,0]
	v_add_f32_dpp v99, v99, v99 quad_perm:[1,0,3,2] row_mask:0xf bank_mask:0xf bound_ctrl:1
	v_fma_mix_f32 v103, v88, v19, 0 op_sel:[1,0,0] op_sel_hi:[1,1,0]
	v_fma_mix_f32 v104, v88, v19, 0 op_sel:[1,1,0] op_sel_hi:[1,1,0]
	v_add_f32_dpp v99, v99, v99 quad_perm:[2,3,0,1] row_mask:0xf bank_mask:0xf bound_ctrl:1
	v_fma_mix_f32 v84, v84, v8, v101 op_sel:[0,0,0] op_sel_hi:[0,1,0]
	v_fma_mix_f32 v85, v85, v8, v102 op_sel:[0,1,0] op_sel_hi:[0,1,0]
	v_add_f32_dpp v99, v99, v99 row_half_mirror row_mask:0xf bank_mask:0xf bound_ctrl:1
	v_fma_mix_f32 v86, v86, v9, v103 op_sel:[0,0,0] op_sel_hi:[0,1,0]
	v_fma_mix_f32 v87, v87, v9, v104 op_sel:[0,1,0] op_sel_hi:[0,1,0]
	v_add_f32_dpp v99, v99, v99 row_mirror row_mask:0xf bank_mask:0xf bound_ctrl:1
	v_fma_mix_f32 v84, -v99, v16, v84 op_sel:[0,0,0] op_sel_hi:[0,1,0]
	v_fma_mix_f32 v85, -v99, v16, v85 op_sel:[0,1,0] op_sel_hi:[0,1,0]
	v_fma_mix_f32 v86, -v99, v17, v86 op_sel:[0,0,0] op_sel_hi:[0,1,0]
	v_fma_mix_f32 v87, -v99, v17, v87 op_sel:[0,1,0] op_sel_hi:[0,1,0]
	v_fma_mix_f32 v100, v84, v26, 0 op_sel:[0,0,0] op_sel_hi:[0,1,0]
	v_fma_mix_f32 v97, v84, v2, 0 op_sel:[0,0,0] op_sel_hi:[0,1,0]
	v_fma_mix_f32 v100, v85, v26, v100 op_sel:[0,1,0] op_sel_hi:[0,1,0]
	v_fma_mix_f32 v97, v85, v2, v97 op_sel:[0,1,0] op_sel_hi:[0,1,0]
	v_fma_mix_f32 v100, v86, v27, v100 op_sel:[0,0,0] op_sel_hi:[0,1,0]
	v_fma_mix_f32 v97, v86, v3, v97 op_sel:[0,0,0] op_sel_hi:[0,1,0]
	v_fma_mix_f32 v100, v87, v27, v100 op_sel:[0,1,0] op_sel_hi:[0,1,0]
	v_fma_mix_f32 v97, v87, v3, v97 op_sel:[0,1,0] op_sel_hi:[0,1,0]
	v_fma_mix_f32 v102, v89, v34, 0 op_sel:[0,0,0] op_sel_hi:[1,1,0]
	v_fma_mix_f32 v103, v89, v34, 0 op_sel:[0,1,0] op_sel_hi:[1,1,0]
	v_add_f32_dpp v100, v100, v100 quad_perm:[1,0,3,2] row_mask:0xf bank_mask:0xf bound_ctrl:1
	v_fma_mix_f32 v104, v89, v35, 0 op_sel:[0,0,0] op_sel_hi:[1,1,0]
	v_fma_mix_f32 v105, v89, v35, 0 op_sel:[0,1,0] op_sel_hi:[1,1,0]
	v_add_f32_dpp v100, v100, v100 quad_perm:[2,3,0,1] row_mask:0xf bank_mask:0xf bound_ctrl:1
	v_fma_mix_f32 v84, v84, v24, v102 op_sel:[0,0,0] op_sel_hi:[0,1,0]
	v_fma_mix_f32 v85, v85, v24, v103 op_sel:[0,1,0] op_sel_hi:[0,1,0]
	v_add_f32_dpp v100, v100, v100 row_half_mirror row_mask:0xf bank_mask:0xf bound_ctrl:1
	v_fma_mix_f32 v86, v86, v25, v104 op_sel:[0,0,0] op_sel_hi:[0,1,0]
	v_fma_mix_f32 v87, v87, v25, v105 op_sel:[0,1,0] op_sel_hi:[0,1,0]
	v_add_f32_dpp v100, v100, v100 row_mirror row_mask:0xf bank_mask:0xf bound_ctrl:1
	v_fma_mix_f32 v84, -v100, v32, v84 op_sel:[0,0,0] op_sel_hi:[0,1,0]
	v_fma_mix_f32 v85, -v100, v32, v85 op_sel:[0,1,0] op_sel_hi:[0,1,0]
	v_fma_mix_f32 v86, -v100, v33, v86 op_sel:[0,0,0] op_sel_hi:[0,1,0]
	v_fma_mix_f32 v87, -v100, v33, v87 op_sel:[0,1,0] op_sel_hi:[0,1,0]
	v_fma_mix_f32 v101, v84, v30, 0 op_sel:[0,0,0] op_sel_hi:[0,1,0]
	v_fma_mix_f32 v98, v84, v20, 0 op_sel:[0,0,0] op_sel_hi:[0,1,0]
	v_fma_mix_f32 v101, v85, v30, v101 op_sel:[0,1,0] op_sel_hi:[0,1,0]
	v_fma_mix_f32 v98, v85, v20, v98 op_sel:[0,1,0] op_sel_hi:[0,1,0]
	v_fma_mix_f32 v101, v86, v31, v101 op_sel:[0,0,0] op_sel_hi:[0,1,0]
	v_fma_mix_f32 v98, v86, v21, v98 op_sel:[0,0,0] op_sel_hi:[0,1,0]
	v_fma_mix_f32 v101, v87, v31, v101 op_sel:[0,1,0] op_sel_hi:[0,1,0]
	v_fma_mix_f32 v98, v87, v21, v98 op_sel:[0,1,0] op_sel_hi:[0,1,0]
	v_fma_mix_f32 v103, v89, v38, 0 op_sel:[1,0,0] op_sel_hi:[1,1,0]
	v_fma_mix_f32 v104, v89, v38, 0 op_sel:[1,1,0] op_sel_hi:[1,1,0]
	v_add_f32_dpp v101, v101, v101 quad_perm:[1,0,3,2] row_mask:0xf bank_mask:0xf bound_ctrl:1
	v_fma_mix_f32 v105, v89, v39, 0 op_sel:[1,0,0] op_sel_hi:[1,1,0]
	v_fma_mix_f32 v119, v89, v39, 0 op_sel:[1,1,0] op_sel_hi:[1,1,0]
	v_add_f32_dpp v101, v101, v101 quad_perm:[2,3,0,1] row_mask:0xf bank_mask:0xf bound_ctrl:1
	v_fma_mix_f32 v84, v84, v28, v103 op_sel:[0,0,0] op_sel_hi:[0,1,0]
	v_fma_mix_f32 v85, v85, v28, v104 op_sel:[0,1,0] op_sel_hi:[0,1,0]
	v_add_f32_dpp v101, v101, v101 row_half_mirror row_mask:0xf bank_mask:0xf bound_ctrl:1
	v_fma_mix_f32 v86, v86, v29, v105 op_sel:[0,0,0] op_sel_hi:[0,1,0]
	v_fma_mix_f32 v87, v87, v29, v119 op_sel:[0,1,0] op_sel_hi:[0,1,0]
	v_add_f32_dpp v101, v101, v101 row_mirror row_mask:0xf bank_mask:0xf bound_ctrl:1
	v_fma_mix_f32 v84, -v101, v36, v84 op_sel:[0,0,0] op_sel_hi:[0,1,0]
	v_fma_mix_f32 v85, -v101, v36, v85 op_sel:[0,1,0] op_sel_hi:[0,1,0]
	v_fma_mix_f32 v86, -v101, v37, v86 op_sel:[0,0,0] op_sel_hi:[0,1,0]
	v_fma_mix_f32 v87, -v101, v37, v87 op_sel:[0,1,0] op_sel_hi:[0,1,0]
	v_fma_mix_f32 v99, v84, v22, 0 op_sel:[0,0,0] op_sel_hi:[0,1,0]
	v_cndmask_b32_e64 v187, v97, v96, s[38:39]
	v_fma_mix_f32 v99, v85, v22, v99 op_sel:[0,1,0] op_sel_hi:[0,1,0]
	v_cndmask_b32_e64 v188, v96, v97, s[38:39]
	v_fma_mix_f32 v99, v86, v23, v99 op_sel:[0,0,0] op_sel_hi:[0,1,0]
	v_fma_mix_f32 v99, v87, v23, v99 op_sel:[0,1,0] op_sel_hi:[0,1,0]
	v_cndmask_b32_e64 v189, v99, v98, s[38:39]
	v_cndmask_b32_e64 v190, v98, v99, s[38:39]
	s_waitcnt lgkmcnt(0)
	v_fma_mix_f32 v98, v84, v74, 0 op_sel:[0,0,0] op_sel_hi:[0,1,0]
	v_fma_mix_f32 v98, v85, v74, v98 op_sel:[0,1,0] op_sel_hi:[0,1,0]
	v_add_f32_dpp v188, v188, v187 quad_perm:[1,0,3,2] row_mask:0xf bank_mask:0xf bound_ctrl:1
	v_add_f32_dpp v189, v190, v189 quad_perm:[1,0,3,2] row_mask:0xf bank_mask:0xf bound_ctrl:1
	v_fma_mix_f32 v98, v86, v75, v98 op_sel:[0,0,0] op_sel_hi:[0,1,0]
	v_fma_mix_f32 v98, v87, v75, v98 op_sel:[0,1,0] op_sel_hi:[0,1,0]
	v_cndmask_b32_e64 v191, v189, v188, s[40:41]
	v_cndmask_b32_e64 v192, v188, v189, s[40:41]
	v_fma_mix_f32 v100, v92, v78, 0 op_sel:[0,0,0] op_sel_hi:[1,1,0]
	v_fma_mix_f32 v101, v92, v78, 0 op_sel:[0,1,0] op_sel_hi:[1,1,0]
	v_add_f32_dpp v192, v192, v191 quad_perm:[2,3,0,1] row_mask:0xf bank_mask:0xf bound_ctrl:1
	v_add_f32_dpp v98, v98, v98 quad_perm:[1,0,3,2] row_mask:0xf bank_mask:0xf bound_ctrl:1
	v_fma_mix_f32 v102, v92, v79, 0 op_sel:[0,0,0] op_sel_hi:[1,1,0]
	v_add_f32_dpp v192, v192, v192 row_ror:4 row_mask:0xf bank_mask:0xf bound_ctrl:1
	v_fma_mix_f32 v103, v92, v79, 0 op_sel:[0,1,0] op_sel_hi:[1,1,0]
	v_add_f32_dpp v98, v98, v98 quad_perm:[2,3,0,1] row_mask:0xf bank_mask:0xf bound_ctrl:1
	v_add_f32_dpp v192, v192, v192 row_ror:8 row_mask:0xf bank_mask:0xf bound_ctrl:1
	v_cvt_f16_f32_e32 v192, v192
	global_store_short v83, v192, s[36:37]
	s_add_u32 s36, s36, s44
	s_addc_u32 s37, s37, s45
	s_cmp_gt_i32 s35, 5
	s_cbranch_scc0 .Lc_poll_A1
.Lc_ret_A1:
	ds_read_b128 v[0:3], v194 offset:14336
	ds_read_b128 v[4:7], v194 offset:12288
	ds_read_b128 v[8:11], v194 offset:12544
	ds_read_b128 v[12:15], v194 offset:13312
	ds_read_b128 v[16:19], v194 offset:13568
	ds_read_b128 v[20:23], v194 offset:14592
	ds_read_b128 v[24:27], v194 offset:12800
	ds_read_b128 v[28:31], v194 offset:13056
	ds_read_b128 v[32:35], v194 offset:13824
	ds_read_b128 v[36:39], v194 offset:14080
	ds_read_b64 v[88:89], v195 offset:14848
	v_fma_mix_f32 v84, v84, v72, v100 op_sel:[0,0,0] op_sel_hi:[0,1,0]
	v_fma_mix_f32 v85, v85, v72, v101 op_sel:[0,1,0] op_sel_hi:[0,1,0]
	v_add_f32_dpp v98, v98, v98 row_half_mirror row_mask:0xf bank_mask:0xf bound_ctrl:1
	v_fma_mix_f32 v86, v86, v73, v102 op_sel:[0,0,0] op_sel_hi:[0,1,0]
	v_fma_mix_f32 v87, v87, v73, v103 op_sel:[0,1,0] op_sel_hi:[0,1,0]
	v_add_f32_dpp v98, v98, v98 row_mirror row_mask:0xf bank_mask:0xf bound_ctrl:1
	v_fma_mix_f32 v84, -v98, v76, v84 op_sel:[0,0,0] op_sel_hi:[0,1,0]
	v_fma_mix_f32 v85, -v98, v76, v85 op_sel:[0,1,0] op_sel_hi:[0,1,0]
	v_fma_mix_f32 v86, -v98, v77, v86 op_sel:[0,0,0] op_sel_hi:[0,1,0]
	v_fma_mix_f32 v87, -v98, v77, v87 op_sel:[0,1,0] op_sel_hi:[0,1,0]
	v_fma_mix_f32 v73, v84, v66, 0 op_sel:[0,0,0] op_sel_hi:[0,1,0]
	v_fma_mix_f32 v97, v84, v56, 0 op_sel:[0,0,0] op_sel_hi:[0,1,0]
	v_fma_mix_f32 v73, v85, v66, v73 op_sel:[0,1,0] op_sel_hi:[0,1,0]
	v_fma_mix_f32 v56, v85, v56, v97 op_sel:[0,1,0] op_sel_hi:[0,1,0]
	v_fma_mix_f32 v73, v86, v67, v73 op_sel:[0,0,0] op_sel_hi:[0,1,0]
	v_fma_mix_f32 v56, v86, v57, v56 op_sel:[0,0,0] op_sel_hi:[0,1,0]
	v_fma_mix_f32 v73, v87, v67, v73 op_sel:[0,1,0] op_sel_hi:[0,1,0]
	v_fma_mix_f32 v56, v87, v57, v56 op_sel:[0,1,0] op_sel_hi:[0,1,0]
	v_fma_mix_f32 v75, v92, v70, 0 op_sel:[1,0,0] op_sel_hi:[1,1,0]
	v_fma_mix_f32 v76, v92, v70, 0 op_sel:[1,1,0] op_sel_hi:[1,1,0]
	v_add_f32_dpp v73, v73, v73 quad_perm:[1,0,3,2] row_mask:0xf bank_mask:0xf bound_ctrl:1
	v_fma_mix_f32 v77, v92, v71, 0 op_sel:[1,0,0] op_sel_hi:[1,1,0]
	v_fma_mix_f32 v78, v92, v71, 0 op_sel:[1,1,0] op_sel_hi:[1,1,0]
	v_add_f32_dpp v73, v73, v73 quad_perm:[2,3,0,1] row_mask:0xf bank_mask:0xf bound_ctrl:1
	v_fma_mix_f32 v84, v84, v64, v75 op_sel:[0,0,0] op_sel_hi:[0,1,0]
	v_fma_mix_f32 v85, v85, v64, v76 op_sel:[0,1,0] op_sel_hi:[0,1,0]
	v_add_f32_dpp v73, v73, v73 row_half_mirror row_mask:0xf bank_mask:0xf bound_ctrl:1
	v_fma_mix_f32 v86, v86, v65, v77 op_sel:[0,0,0] op_sel_hi:[0,1,0]
	v_fma_mix_f32 v87, v87, v65, v78 op_sel:[0,1,0] op_sel_hi:[0,1,0]
	v_add_f32_dpp v73, v73, v73 row_mirror row_mask:0xf bank_mask:0xf bound_ctrl:1
	v_fma_mix_f32 v84, -v73, v68, v84 op_sel:[0,0,0] op_sel_hi:[0,1,0]
	v_fma_mix_f32 v85, -v73, v68, v85 op_sel:[0,1,0] op_sel_hi:[0,1,0]
	v_fma_mix_f32 v86, -v73, v69, v86 op_sel:[0,0,0] op_sel_hi:[0,1,0]
	v_fma_mix_f32 v87, -v73, v69, v87 op_sel:[0,1,0] op_sel_hi:[0,1,0]
	v_fma_mix_f32 v64, v84, v54, 0 op_sel:[0,0,0] op_sel_hi:[0,1,0]
	v_fma_mix_f32 v57, v84, v58, 0 op_sel:[0,0,0] op_sel_hi:[0,1,0]
	v_fma_mix_f32 v64, v85, v54, v64 op_sel:[0,1,0] op_sel_hi:[0,1,0]
	v_fma_mix_f32 v57, v85, v58, v57 op_sel:[0,1,0] op_sel_hi:[0,1,0]
	v_fma_mix_f32 v64, v86, v55, v64 op_sel:[0,0,0] op_sel_hi:[0,1,0]
	v_fma_mix_f32 v57, v86, v59, v57 op_sel:[0,0,0] op_sel_hi:[0,1,0]
	v_fma_mix_f32 v64, v87, v55, v64 op_sel:[0,1,0] op_sel_hi:[0,1,0]
	v_fma_mix_f32 v57, v87, v59, v57 op_sel:[0,1,0] op_sel_hi:[0,1,0]
	v_fma_mix_f32 v66, v93, v62, 0 op_sel:[0,0,0] op_sel_hi:[1,1,0]
	v_fma_mix_f32 v67, v93, v62, 0 op_sel:[0,1,0] op_sel_hi:[1,1,0]
	v_add_f32_dpp v64, v64, v64 quad_perm:[1,0,3,2] row_mask:0xf bank_mask:0xf bound_ctrl:1
	v_fma_mix_f32 v68, v93, v63, 0 op_sel:[0,0,0] op_sel_hi:[1,1,0]
	v_fma_mix_f32 v69, v93, v63, 0 op_sel:[0,1,0] op_sel_hi:[1,1,0]
	v_add_f32_dpp v64, v64, v64 quad_perm:[2,3,0,1] row_mask:0xf bank_mask:0xf bound_ctrl:1
	v_fma_mix_f32 v84, v84, v52, v66 op_sel:[0,0,0] op_sel_hi:[0,1,0]
	v_fma_mix_f32 v85, v85, v52, v67 op_sel:[0,1,0] op_sel_hi:[0,1,0]
	v_add_f32_dpp v64, v64, v64 row_half_mirror row_mask:0xf bank_mask:0xf bound_ctrl:1
	v_fma_mix_f32 v86, v86, v53, v68 op_sel:[0,0,0] op_sel_hi:[0,1,0]
	v_fma_mix_f32 v87, v87, v53, v69 op_sel:[0,1,0] op_sel_hi:[0,1,0]
	v_add_f32_dpp v64, v64, v64 row_mirror row_mask:0xf bank_mask:0xf bound_ctrl:1
	v_fma_mix_f32 v84, -v64, v60, v84 op_sel:[0,0,0] op_sel_hi:[0,1,0]
	v_fma_mix_f32 v85, -v64, v60, v85 op_sel:[0,1,0] op_sel_hi:[0,1,0]
	v_fma_mix_f32 v86, -v64, v61, v86 op_sel:[0,0,0] op_sel_hi:[0,1,0]
	v_fma_mix_f32 v87, -v64, v61, v87 op_sel:[0,1,0] op_sel_hi:[0,1,0]
	v_fma_mix_f32 v53, v84, v46, 0 op_sel:[0,0,0] op_sel_hi:[0,1,0]
	v_fma_mix_f32 v59, v84, v40, 0 op_sel:[0,0,0] op_sel_hi:[0,1,0]
	v_fma_mix_f32 v53, v85, v46, v53 op_sel:[0,1,0] op_sel_hi:[0,1,0]
	v_fma_mix_f32 v40, v85, v40, v59 op_sel:[0,1,0] op_sel_hi:[0,1,0]
	v_fma_mix_f32 v53, v86, v47, v53 op_sel:[0,0,0] op_sel_hi:[0,1,0]
	v_fma_mix_f32 v40, v86, v41, v40 op_sel:[0,0,0] op_sel_hi:[0,1,0]
	v_fma_mix_f32 v53, v87, v47, v53 op_sel:[0,1,0] op_sel_hi:[0,1,0]
	v_fma_mix_f32 v40, v87, v41, v40 op_sel:[0,1,0] op_sel_hi:[0,1,0]
	v_fma_mix_f32 v55, v93, v50, 0 op_sel:[1,0,0] op_sel_hi:[1,1,0]
	v_fma_mix_f32 v58, v93, v50, 0 op_sel:[1,1,0] op_sel_hi:[1,1,0]
	v_add_f32_dpp v53, v53, v53 quad_perm:[1,0,3,2] row_mask:0xf bank_mask:0xf bound_ctrl:1
	v_fma_mix_f32 v59, v93, v51, 0 op_sel:[1,0,0] op_sel_hi:[1,1,0]
	v_fma_mix_f32 v60, v93, v51, 0 op_sel:[1,1,0] op_sel_hi:[1,1,0]
	v_add_f32_dpp v53, v53, v53 quad_perm:[2,3,0,1] row_mask:0xf bank_mask:0xf bound_ctrl:1
	v_fma_mix_f32 v84, v84, v44, v55 op_sel:[0,0,0] op_sel_hi:[0,1,0]
	v_fma_mix_f32 v85, v85, v44, v58 op_sel:[0,1,0] op_sel_hi:[0,1,0]
	v_add_f32_dpp v53, v53, v53 row_half_mirror row_mask:0xf bank_mask:0xf bound_ctrl:1
	v_fma_mix_f32 v86, v86, v45, v59 op_sel:[0,0,0] op_sel_hi:[0,1,0]
	v_fma_mix_f32 v87, v87, v45, v60 op_sel:[0,1,0] op_sel_hi:[0,1,0]
	v_add_f32_dpp v53, v53, v53 row_mirror row_mask:0xf bank_mask:0xf bound_ctrl:1
	v_fma_mix_f32 v84, -v53, v48, v84 op_sel:[0,0,0] op_sel_hi:[0,1,0]
	v_fma_mix_f32 v85, -v53, v48, v85 op_sel:[0,1,0] op_sel_hi:[0,1,0]
	v_fma_mix_f32 v86, -v53, v49, v86 op_sel:[0,0,0] op_sel_hi:[0,1,0]
	v_fma_mix_f32 v87, -v53, v49, v87 op_sel:[0,1,0] op_sel_hi:[0,1,0]
	v_fma_mix_f32 v41, v84, v42, 0 op_sel:[0,0,0] op_sel_hi:[0,1,0]
	v_add_u32_e32 v173, 4, v193
	v_fma_mix_f32 v41, v85, v42, v41 op_sel:[0,1,0] op_sel_hi:[0,1,0]
	ds_write_b32 v172, v173 offset:49216
	v_fma_mix_f32 v41, v86, v43, v41 op_sel:[0,0,0] op_sel_hi:[0,1,0]
	v_cndmask_b32_e64 v187, v57, v56, s[38:39]
	v_fma_mix_f32 v41, v87, v43, v41 op_sel:[0,1,0] op_sel_hi:[0,1,0]
	v_cndmask_b32_e64 v188, v56, v57, s[38:39]
	v_cndmask_b32_e64 v189, v41, v40, s[38:39]
	v_cndmask_b32_e64 v190, v40, v41, s[38:39]
	s_waitcnt lgkmcnt(1)
	v_fma_mix_f32 v98, v84, v6, 0 op_sel:[0,0,0] op_sel_hi:[0,1,0]
	v_fma_mix_f32 v98, v85, v6, v98 op_sel:[0,1,0] op_sel_hi:[0,1,0]
	v_add_f32_dpp v188, v188, v187 quad_perm:[1,0,3,2] row_mask:0xf bank_mask:0xf bound_ctrl:1
	v_add_f32_dpp v189, v190, v189 quad_perm:[1,0,3,2] row_mask:0xf bank_mask:0xf bound_ctrl:1
	v_fma_mix_f32 v98, v86, v7, v98 op_sel:[0,0,0] op_sel_hi:[0,1,0]
	v_fma_mix_f32 v98, v87, v7, v98 op_sel:[0,1,0] op_sel_hi:[0,1,0]
	v_cndmask_b32_e64 v191, v189, v188, s[40:41]
	v_cndmask_b32_e64 v192, v188, v189, s[40:41]
	v_fma_mix_f32 v100, v88, v14, 0 op_sel:[0,0,0] op_sel_hi:[1,1,0]
	v_fma_mix_f32 v101, v88, v14, 0 op_sel:[0,1,0] op_sel_hi:[1,1,0]
	v_add_f32_dpp v192, v192, v191 quad_perm:[2,3,0,1] row_mask:0xf bank_mask:0xf bound_ctrl:1
	v_add_f32_dpp v98, v98, v98 quad_perm:[1,0,3,2] row_mask:0xf bank_mask:0xf bound_ctrl:1
	v_fma_mix_f32 v102, v88, v15, 0 op_sel:[0,0,0] op_sel_hi:[1,1,0]
	v_add_f32_dpp v192, v192, v192 row_ror:4 row_mask:0xf bank_mask:0xf bound_ctrl:1
	v_fma_mix_f32 v103, v88, v15, 0 op_sel:[0,1,0] op_sel_hi:[1,1,0]
	v_add_f32_dpp v98, v98, v98 quad_perm:[2,3,0,1] row_mask:0xf bank_mask:0xf bound_ctrl:1
	v_add_f32_dpp v192, v192, v192 row_ror:8 row_mask:0xf bank_mask:0xf bound_ctrl:1
	v_cvt_f16_f32_e32 v192, v192
	global_store_short v83, v192, s[36:37]
	s_add_u32 s36, s36, s44
	s_addc_u32 s37, s37, s45
	ds_read_b128 v[56:59], v194 offset:17408
	ds_read_b128 v[72:75], v194 offset:15360
	ds_read_b128 v[64:67], v194 offset:15616
	ds_read_b128 v[76:79], v194 offset:16384
	ds_read_b128 v[68:71], v194 offset:16640
	ds_read_b128 v[40:43], v194 offset:17664
	ds_read_b128 v[52:55], v194 offset:15872
	ds_read_b128 v[44:47], v194 offset:16128
	ds_read_b128 v[60:63], v194 offset:16896
	ds_read_b128 v[48:51], v194 offset:17152
	ds_read_b64 v[92:93], v195 offset:17920
	v_fma_mix_f32 v84, v84, v4, v100 op_sel:[0,0,0] op_sel_hi:[0,1,0]
	v_fma_mix_f32 v85, v85, v4, v101 op_sel:[0,1,0] op_sel_hi:[0,1,0]
	v_add_f32_dpp v98, v98, v98 row_half_mirror row_mask:0xf bank_mask:0xf bound_ctrl:1
	v_fma_mix_f32 v86, v86, v5, v102 op_sel:[0,0,0] op_sel_hi:[0,1,0]
	v_fma_mix_f32 v87, v87, v5, v103 op_sel:[0,1,0] op_sel_hi:[0,1,0]
	v_add_f32_dpp v98, v98, v98 row_mirror row_mask:0xf bank_mask:0xf bound_ctrl:1
	v_fma_mix_f32 v84, -v98, v12, v84 op_sel:[0,0,0] op_sel_hi:[0,1,0]
	v_fma_mix_f32 v85, -v98, v12, v85 op_sel:[0,1,0] op_sel_hi:[0,1,0]
	v_fma_mix_f32 v86, -v98, v13, v86 op_sel:[0,0,0] op_sel_hi:[0,1,0]
	v_fma_mix_f32 v87, -v98, v13, v87 op_sel:[0,1,0] op_sel_hi:[0,1,0]
	v_fma_mix_f32 v99, v84, v10, 0 op_sel:[0,0,0] op_sel_hi:[0,1,0]
	v_fma_mix_f32 v96, v84, v0, 0 op_sel:[0,0,0] op_sel_hi:[0,1,0]
	v_fma_mix_f32 v99, v85, v10, v99 op_sel:[0,1,0] op_sel_hi:[0,1,0]
	v_fma_mix_f32 v96, v85, v0, v96 op_sel:[0,1,0] op_sel_hi:[0,1,0]
	v_fma_mix_f32 v99, v86, v11, v99 op_sel:[0,0,0] op_sel_hi:[0,1,0]
	v_fma_mix_f32 v96, v86, v1, v96 op_sel:[0,0,0] op_sel_hi:[0,1,0]
	v_fma_mix_f32 v99, v87, v11, v99 op_sel:[0,1,0] op_sel_hi:[0,1,0]
	v_fma_mix_f32 v96, v87, v1, v96 op_sel:[0,1,0] op_sel_hi:[0,1,0]
	v_fma_mix_f32 v101, v88, v18, 0 op_sel:[1,0,0] op_sel_hi:[1,1,0]
	v_fma_mix_f32 v102, v88, v18, 0 op_sel:[1,1,0] op_sel_hi:[1,1,0]
	v_add_f32_dpp v99, v99, v99 quad_perm:[1,0,3,2] row_mask:0xf bank_mask:0xf bound_ctrl:1
	v_fma_mix_f32 v103, v88, v19, 0 op_sel:[1,0,0] op_sel_hi:[1,1,0]
	v_fma_mix_f32 v104, v88, v19, 0 op_sel:[1,1,0] op_sel_hi:[1,1,0]
	v_add_f32_dpp v99, v99, v99 quad_perm:[2,3,0,1] row_mask:0xf bank_mask:0xf bound_ctrl:1
	v_fma_mix_f32 v84, v84, v8, v101 op_sel:[0,0,0] op_sel_hi:[0,1,0]
	v_fma_mix_f32 v85, v85, v8, v102 op_sel:[0,1,0] op_sel_hi:[0,1,0]
	v_add_f32_dpp v99, v99, v99 row_half_mirror row_mask:0xf bank_mask:0xf bound_ctrl:1
	v_fma_mix_f32 v86, v86, v9, v103 op_sel:[0,0,0] op_sel_hi:[0,1,0]
	v_fma_mix_f32 v87, v87, v9, v104 op_sel:[0,1,0] op_sel_hi:[0,1,0]
	v_add_f32_dpp v99, v99, v99 row_mirror row_mask:0xf bank_mask:0xf bound_ctrl:1
	v_fma_mix_f32 v84, -v99, v16, v84 op_sel:[0,0,0] op_sel_hi:[0,1,0]
	v_fma_mix_f32 v85, -v99, v16, v85 op_sel:[0,1,0] op_sel_hi:[0,1,0]
	v_fma_mix_f32 v86, -v99, v17, v86 op_sel:[0,0,0] op_sel_hi:[0,1,0]
	v_fma_mix_f32 v87, -v99, v17, v87 op_sel:[0,1,0] op_sel_hi:[0,1,0]
	v_fma_mix_f32 v100, v84, v26, 0 op_sel:[0,0,0] op_sel_hi:[0,1,0]
	v_fma_mix_f32 v97, v84, v2, 0 op_sel:[0,0,0] op_sel_hi:[0,1,0]
	v_fma_mix_f32 v100, v85, v26, v100 op_sel:[0,1,0] op_sel_hi:[0,1,0]
	v_fma_mix_f32 v97, v85, v2, v97 op_sel:[0,1,0] op_sel_hi:[0,1,0]
	v_fma_mix_f32 v100, v86, v27, v100 op_sel:[0,0,0] op_sel_hi:[0,1,0]
	v_fma_mix_f32 v97, v86, v3, v97 op_sel:[0,0,0] op_sel_hi:[0,1,0]
	v_fma_mix_f32 v100, v87, v27, v100 op_sel:[0,1,0] op_sel_hi:[0,1,0]
	v_fma_mix_f32 v97, v87, v3, v97 op_sel:[0,1,0] op_sel_hi:[0,1,0]
	v_fma_mix_f32 v102, v89, v34, 0 op_sel:[0,0,0] op_sel_hi:[1,1,0]
	v_fma_mix_f32 v103, v89, v34, 0 op_sel:[0,1,0] op_sel_hi:[1,1,0]
	v_add_f32_dpp v100, v100, v100 quad_perm:[1,0,3,2] row_mask:0xf bank_mask:0xf bound_ctrl:1
	v_fma_mix_f32 v104, v89, v35, 0 op_sel:[0,0,0] op_sel_hi:[1,1,0]
	v_fma_mix_f32 v105, v89, v35, 0 op_sel:[0,1,0] op_sel_hi:[1,1,0]
	v_add_f32_dpp v100, v100, v100 quad_perm:[2,3,0,1] row_mask:0xf bank_mask:0xf bound_ctrl:1
	v_fma_mix_f32 v84, v84, v24, v102 op_sel:[0,0,0] op_sel_hi:[0,1,0]
	v_fma_mix_f32 v85, v85, v24, v103 op_sel:[0,1,0] op_sel_hi:[0,1,0]
	v_add_f32_dpp v100, v100, v100 row_half_mirror row_mask:0xf bank_mask:0xf bound_ctrl:1
	v_fma_mix_f32 v86, v86, v25, v104 op_sel:[0,0,0] op_sel_hi:[0,1,0]
	v_fma_mix_f32 v87, v87, v25, v105 op_sel:[0,1,0] op_sel_hi:[0,1,0]
	v_add_f32_dpp v100, v100, v100 row_mirror row_mask:0xf bank_mask:0xf bound_ctrl:1
	v_fma_mix_f32 v84, -v100, v32, v84 op_sel:[0,0,0] op_sel_hi:[0,1,0]
	v_fma_mix_f32 v85, -v100, v32, v85 op_sel:[0,1,0] op_sel_hi:[0,1,0]
	v_fma_mix_f32 v86, -v100, v33, v86 op_sel:[0,0,0] op_sel_hi:[0,1,0]
	v_fma_mix_f32 v87, -v100, v33, v87 op_sel:[0,1,0] op_sel_hi:[0,1,0]
	v_fma_mix_f32 v101, v84, v30, 0 op_sel:[0,0,0] op_sel_hi:[0,1,0]
	v_fma_mix_f32 v98, v84, v20, 0 op_sel:[0,0,0] op_sel_hi:[0,1,0]
	v_fma_mix_f32 v101, v85, v30, v101 op_sel:[0,1,0] op_sel_hi:[0,1,0]
	v_fma_mix_f32 v98, v85, v20, v98 op_sel:[0,1,0] op_sel_hi:[0,1,0]
	v_fma_mix_f32 v101, v86, v31, v101 op_sel:[0,0,0] op_sel_hi:[0,1,0]
	v_fma_mix_f32 v98, v86, v21, v98 op_sel:[0,0,0] op_sel_hi:[0,1,0]
	v_fma_mix_f32 v101, v87, v31, v101 op_sel:[0,1,0] op_sel_hi:[0,1,0]
	v_fma_mix_f32 v98, v87, v21, v98 op_sel:[0,1,0] op_sel_hi:[0,1,0]
	v_fma_mix_f32 v103, v89, v38, 0 op_sel:[1,0,0] op_sel_hi:[1,1,0]
	v_fma_mix_f32 v104, v89, v38, 0 op_sel:[1,1,0] op_sel_hi:[1,1,0]
	v_add_f32_dpp v101, v101, v101 quad_perm:[1,0,3,2] row_mask:0xf bank_mask:0xf bound_ctrl:1
	v_fma_mix_f32 v105, v89, v39, 0 op_sel:[1,0,0] op_sel_hi:[1,1,0]
	v_fma_mix_f32 v119, v89, v39, 0 op_sel:[1,1,0] op_sel_hi:[1,1,0]
	v_add_f32_dpp v101, v101, v101 quad_perm:[2,3,0,1] row_mask:0xf bank_mask:0xf bound_ctrl:1
	v_fma_mix_f32 v84, v84, v28, v103 op_sel:[0,0,0] op_sel_hi:[0,1,0]
	v_fma_mix_f32 v85, v85, v28, v104 op_sel:[0,1,0] op_sel_hi:[0,1,0]
	v_add_f32_dpp v101, v101, v101 row_half_mirror row_mask:0xf bank_mask:0xf bound_ctrl:1
	v_fma_mix_f32 v86, v86, v29, v105 op_sel:[0,0,0] op_sel_hi:[0,1,0]
	v_fma_mix_f32 v87, v87, v29, v119 op_sel:[0,1,0] op_sel_hi:[0,1,0]
	v_add_f32_dpp v101, v101, v101 row_mirror row_mask:0xf bank_mask:0xf bound_ctrl:1
	v_fma_mix_f32 v84, -v101, v36, v84 op_sel:[0,0,0] op_sel_hi:[0,1,0]
	v_fma_mix_f32 v85, -v101, v36, v85 op_sel:[0,1,0] op_sel_hi:[0,1,0]
	v_fma_mix_f32 v86, -v101, v37, v86 op_sel:[0,0,0] op_sel_hi:[0,1,0]
	v_fma_mix_f32 v87, -v101, v37, v87 op_sel:[0,1,0] op_sel_hi:[0,1,0]
	v_fma_mix_f32 v99, v84, v22, 0 op_sel:[0,0,0] op_sel_hi:[0,1,0]
	v_cndmask_b32_e64 v187, v97, v96, s[38:39]
	v_fma_mix_f32 v99, v85, v22, v99 op_sel:[0,1,0] op_sel_hi:[0,1,0]
	v_cndmask_b32_e64 v188, v96, v97, s[38:39]
	v_fma_mix_f32 v99, v86, v23, v99 op_sel:[0,0,0] op_sel_hi:[0,1,0]
	v_fma_mix_f32 v99, v87, v23, v99 op_sel:[0,1,0] op_sel_hi:[0,1,0]
	v_cndmask_b32_e64 v189, v99, v98, s[38:39]
	v_cndmask_b32_e64 v190, v98, v99, s[38:39]
	s_waitcnt lgkmcnt(0)
	v_fma_mix_f32 v98, v84, v74, 0 op_sel:[0,0,0] op_sel_hi:[0,1,0]
	v_fma_mix_f32 v98, v85, v74, v98 op_sel:[0,1,0] op_sel_hi:[0,1,0]
	v_add_f32_dpp v188, v188, v187 quad_perm:[1,0,3,2] row_mask:0xf bank_mask:0xf bound_ctrl:1
	v_add_f32_dpp v189, v190, v189 quad_perm:[1,0,3,2] row_mask:0xf bank_mask:0xf bound_ctrl:1
	v_fma_mix_f32 v98, v86, v75, v98 op_sel:[0,0,0] op_sel_hi:[0,1,0]
	v_fma_mix_f32 v98, v87, v75, v98 op_sel:[0,1,0] op_sel_hi:[0,1,0]
	v_cndmask_b32_e64 v191, v189, v188, s[40:41]
	v_cndmask_b32_e64 v192, v188, v189, s[40:41]
	v_fma_mix_f32 v100, v92, v78, 0 op_sel:[0,0,0] op_sel_hi:[1,1,0]
	v_fma_mix_f32 v101, v92, v78, 0 op_sel:[0,1,0] op_sel_hi:[1,1,0]
	v_add_f32_dpp v192, v192, v191 quad_perm:[2,3,0,1] row_mask:0xf bank_mask:0xf bound_ctrl:1
	v_add_f32_dpp v98, v98, v98 quad_perm:[1,0,3,2] row_mask:0xf bank_mask:0xf bound_ctrl:1
	v_fma_mix_f32 v102, v92, v79, 0 op_sel:[0,0,0] op_sel_hi:[1,1,0]
	v_add_f32_dpp v192, v192, v192 row_ror:4 row_mask:0xf bank_mask:0xf bound_ctrl:1
	v_fma_mix_f32 v103, v92, v79, 0 op_sel:[0,1,0] op_sel_hi:[1,1,0]
	v_add_f32_dpp v98, v98, v98 quad_perm:[2,3,0,1] row_mask:0xf bank_mask:0xf bound_ctrl:1
	v_add_f32_dpp v192, v192, v192 row_ror:8 row_mask:0xf bank_mask:0xf bound_ctrl:1
	v_cvt_f16_f32_e32 v192, v192
	global_store_short v83, v192, s[36:37]
	s_add_u32 s36, s36, s44
	s_addc_u32 s37, s37, s45
	s_cmp_gt_i32 s35, 7
	s_cbranch_scc0 .Lc_poll_A2
.Lc_ret_A2:
	ds_read_b128 v[0:3], v194 offset:20480
	ds_read_b128 v[4:7], v194 offset:18432
	ds_read_b128 v[8:11], v194 offset:18688
	ds_read_b128 v[12:15], v194 offset:19456
	ds_read_b128 v[16:19], v194 offset:19712
	ds_read_b128 v[20:23], v194 offset:20736
	ds_read_b128 v[24:27], v194 offset:18944
	ds_read_b128 v[28:31], v194 offset:19200
	ds_read_b128 v[32:35], v194 offset:19968
	ds_read_b128 v[36:39], v194 offset:20224
	ds_read_b64 v[88:89], v195 offset:20992
	v_fma_mix_f32 v84, v84, v72, v100 op_sel:[0,0,0] op_sel_hi:[0,1,0]
	v_fma_mix_f32 v85, v85, v72, v101 op_sel:[0,1,0] op_sel_hi:[0,1,0]
	v_add_f32_dpp v98, v98, v98 row_half_mirror row_mask:0xf bank_mask:0xf bound_ctrl:1
	v_fma_mix_f32 v86, v86, v73, v102 op_sel:[0,0,0] op_sel_hi:[0,1,0]
	v_fma_mix_f32 v87, v87, v73, v103 op_sel:[0,1,0] op_sel_hi:[0,1,0]
	v_add_f32_dpp v98, v98, v98 row_mirror row_mask:0xf bank_mask:0xf bound_ctrl:1
	v_fma_mix_f32 v84, -v98, v76, v84 op_sel:[0,0,0] op_sel_hi:[0,1,0]
	v_fma_mix_f32 v85, -v98, v76, v85 op_sel:[0,1,0] op_sel_hi:[0,1,0]
	v_fma_mix_f32 v86, -v98, v77, v86 op_sel:[0,0,0] op_sel_hi:[0,1,0]
	v_fma_mix_f32 v87, -v98, v77, v87 op_sel:[0,1,0] op_sel_hi:[0,1,0]
	v_fma_mix_f32 v73, v84, v66, 0 op_sel:[0,0,0] op_sel_hi:[0,1,0]
	v_fma_mix_f32 v97, v84, v56, 0 op_sel:[0,0,0] op_sel_hi:[0,1,0]
	v_fma_mix_f32 v73, v85, v66, v73 op_sel:[0,1,0] op_sel_hi:[0,1,0]
	v_fma_mix_f32 v56, v85, v56, v97 op_sel:[0,1,0] op_sel_hi:[0,1,0]
	v_fma_mix_f32 v73, v86, v67, v73 op_sel:[0,0,0] op_sel_hi:[0,1,0]
	v_fma_mix_f32 v56, v86, v57, v56 op_sel:[0,0,0] op_sel_hi:[0,1,0]
	v_fma_mix_f32 v73, v87, v67, v73 op_sel:[0,1,0] op_sel_hi:[0,1,0]
	v_fma_mix_f32 v56, v87, v57, v56 op_sel:[0,1,0] op_sel_hi:[0,1,0]
	v_fma_mix_f32 v75, v92, v70, 0 op_sel:[1,0,0] op_sel_hi:[1,1,0]
	v_fma_mix_f32 v76, v92, v70, 0 op_sel:[1,1,0] op_sel_hi:[1,1,0]
	v_add_f32_dpp v73, v73, v73 quad_perm:[1,0,3,2] row_mask:0xf bank_mask:0xf bound_ctrl:1
	v_fma_mix_f32 v77, v92, v71, 0 op_sel:[1,0,0] op_sel_hi:[1,1,0]
	v_fma_mix_f32 v78, v92, v71, 0 op_sel:[1,1,0] op_sel_hi:[1,1,0]
	v_add_f32_dpp v73, v73, v73 quad_perm:[2,3,0,1] row_mask:0xf bank_mask:0xf bound_ctrl:1
	v_fma_mix_f32 v84, v84, v64, v75 op_sel:[0,0,0] op_sel_hi:[0,1,0]
	v_fma_mix_f32 v85, v85, v64, v76 op_sel:[0,1,0] op_sel_hi:[0,1,0]
	v_add_f32_dpp v73, v73, v73 row_half_mirror row_mask:0xf bank_mask:0xf bound_ctrl:1
	v_fma_mix_f32 v86, v86, v65, v77 op_sel:[0,0,0] op_sel_hi:[0,1,0]
	v_fma_mix_f32 v87, v87, v65, v78 op_sel:[0,1,0] op_sel_hi:[0,1,0]
	v_add_f32_dpp v73, v73, v73 row_mirror row_mask:0xf bank_mask:0xf bound_ctrl:1
	v_fma_mix_f32 v84, -v73, v68, v84 op_sel:[0,0,0] op_sel_hi:[0,1,0]
	v_fma_mix_f32 v85, -v73, v68, v85 op_sel:[0,1,0] op_sel_hi:[0,1,0]
	v_fma_mix_f32 v86, -v73, v69, v86 op_sel:[0,0,0] op_sel_hi:[0,1,0]
	v_fma_mix_f32 v87, -v73, v69, v87 op_sel:[0,1,0] op_sel_hi:[0,1,0]
	v_fma_mix_f32 v64, v84, v54, 0 op_sel:[0,0,0] op_sel_hi:[0,1,0]
	v_fma_mix_f32 v57, v84, v58, 0 op_sel:[0,0,0] op_sel_hi:[0,1,0]
	v_fma_mix_f32 v64, v85, v54, v64 op_sel:[0,1,0] op_sel_hi:[0,1,0]
	v_fma_mix_f32 v57, v85, v58, v57 op_sel:[0,1,0] op_sel_hi:[0,1,0]
	v_fma_mix_f32 v64, v86, v55, v64 op_sel:[0,0,0] op_sel_hi:[0,1,0]
	v_fma_mix_f32 v57, v86, v59, v57 op_sel:[0,0,0] op_sel_hi:[0,1,0]
	v_fma_mix_f32 v64, v87, v55, v64 op_sel:[0,1,0] op_sel_hi:[0,1,0]
	v_fma_mix_f32 v57, v87, v59, v57 op_sel:[0,1,0] op_sel_hi:[0,1,0]
	v_fma_mix_f32 v66, v93, v62, 0 op_sel:[0,0,0] op_sel_hi:[1,1,0]
	v_fma_mix_f32 v67, v93, v62, 0 op_sel:[0,1,0] op_sel_hi:[1,1,0]
	v_add_f32_dpp v64, v64, v64 quad_perm:[1,0,3,2] row_mask:0xf bank_mask:0xf bound_ctrl:1
	v_fma_mix_f32 v68, v93, v63, 0 op_sel:[0,0,0] op_sel_hi:[1,1,0]
	v_fma_mix_f32 v69, v93, v63, 0 op_sel:[0,1,0] op_sel_hi:[1,1,0]
	v_add_f32_dpp v64, v64, v64 quad_perm:[2,3,0,1] row_mask:0xf bank_mask:0xf bound_ctrl:1
	v_fma_mix_f32 v84, v84, v52, v66 op_sel:[0,0,0] op_sel_hi:[0,1,0]
	v_fma_mix_f32 v85, v85, v52, v67 op_sel:[0,1,0] op_sel_hi:[0,1,0]
	v_add_f32_dpp v64, v64, v64 row_half_mirror row_mask:0xf bank_mask:0xf bound_ctrl:1
	v_fma_mix_f32 v86, v86, v53, v68 op_sel:[0,0,0] op_sel_hi:[0,1,0]
	v_fma_mix_f32 v87, v87, v53, v69 op_sel:[0,1,0] op_sel_hi:[0,1,0]
	v_add_f32_dpp v64, v64, v64 row_mirror row_mask:0xf bank_mask:0xf bound_ctrl:1
	v_fma_mix_f32 v84, -v64, v60, v84 op_sel:[0,0,0] op_sel_hi:[0,1,0]
	v_fma_mix_f32 v85, -v64, v60, v85 op_sel:[0,1,0] op_sel_hi:[0,1,0]
	v_fma_mix_f32 v86, -v64, v61, v86 op_sel:[0,0,0] op_sel_hi:[0,1,0]
	v_fma_mix_f32 v87, -v64, v61, v87 op_sel:[0,1,0] op_sel_hi:[0,1,0]
	v_fma_mix_f32 v53, v84, v46, 0 op_sel:[0,0,0] op_sel_hi:[0,1,0]
	v_fma_mix_f32 v59, v84, v40, 0 op_sel:[0,0,0] op_sel_hi:[0,1,0]
	v_fma_mix_f32 v53, v85, v46, v53 op_sel:[0,1,0] op_sel_hi:[0,1,0]
	v_fma_mix_f32 v40, v85, v40, v59 op_sel:[0,1,0] op_sel_hi:[0,1,0]
	v_fma_mix_f32 v53, v86, v47, v53 op_sel:[0,0,0] op_sel_hi:[0,1,0]
	v_fma_mix_f32 v40, v86, v41, v40 op_sel:[0,0,0] op_sel_hi:[0,1,0]
	v_fma_mix_f32 v53, v87, v47, v53 op_sel:[0,1,0] op_sel_hi:[0,1,0]
	v_fma_mix_f32 v40, v87, v41, v40 op_sel:[0,1,0] op_sel_hi:[0,1,0]
	v_fma_mix_f32 v55, v93, v50, 0 op_sel:[1,0,0] op_sel_hi:[1,1,0]
	v_fma_mix_f32 v58, v93, v50, 0 op_sel:[1,1,0] op_sel_hi:[1,1,0]
	v_add_f32_dpp v53, v53, v53 quad_perm:[1,0,3,2] row_mask:0xf bank_mask:0xf bound_ctrl:1
	v_fma_mix_f32 v59, v93, v51, 0 op_sel:[1,0,0] op_sel_hi:[1,1,0]
	v_fma_mix_f32 v60, v93, v51, 0 op_sel:[1,1,0] op_sel_hi:[1,1,0]
	v_add_f32_dpp v53, v53, v53 quad_perm:[2,3,0,1] row_mask:0xf bank_mask:0xf bound_ctrl:1
	v_fma_mix_f32 v84, v84, v44, v55 op_sel:[0,0,0] op_sel_hi:[0,1,0]
	v_fma_mix_f32 v85, v85, v44, v58 op_sel:[0,1,0] op_sel_hi:[0,1,0]
	v_add_f32_dpp v53, v53, v53 row_half_mirror row_mask:0xf bank_mask:0xf bound_ctrl:1
	v_fma_mix_f32 v86, v86, v45, v59 op_sel:[0,0,0] op_sel_hi:[0,1,0]
	v_fma_mix_f32 v87, v87, v45, v60 op_sel:[0,1,0] op_sel_hi:[0,1,0]
	v_add_f32_dpp v53, v53, v53 row_mirror row_mask:0xf bank_mask:0xf bound_ctrl:1
	v_fma_mix_f32 v84, -v53, v48, v84 op_sel:[0,0,0] op_sel_hi:[0,1,0]
	v_fma_mix_f32 v85, -v53, v48, v85 op_sel:[0,1,0] op_sel_hi:[0,1,0]
	v_fma_mix_f32 v86, -v53, v49, v86 op_sel:[0,0,0] op_sel_hi:[0,1,0]
	v_fma_mix_f32 v87, -v53, v49, v87 op_sel:[0,1,0] op_sel_hi:[0,1,0]
	v_fma_mix_f32 v41, v84, v42, 0 op_sel:[0,0,0] op_sel_hi:[0,1,0]
	v_add_u32_e32 v173, 6, v193
	v_fma_mix_f32 v41, v85, v42, v41 op_sel:[0,1,0] op_sel_hi:[0,1,0]
	ds_write_b32 v172, v173 offset:49216
	v_fma_mix_f32 v41, v86, v43, v41 op_sel:[0,0,0] op_sel_hi:[0,1,0]
	v_cndmask_b32_e64 v187, v57, v56, s[38:39]
	v_fma_mix_f32 v41, v87, v43, v41 op_sel:[0,1,0] op_sel_hi:[0,1,0]
	v_cndmask_b32_e64 v188, v56, v57, s[38:39]
	v_cndmask_b32_e64 v189, v41, v40, s[38:39]
	v_cndmask_b32_e64 v190, v40, v41, s[38:39]
	s_waitcnt lgkmcnt(1)
	v_fma_mix_f32 v98, v84, v6, 0 op_sel:[0,0,0] op_sel_hi:[0,1,0]
	v_fma_mix_f32 v98, v85, v6, v98 op_sel:[0,1,0] op_sel_hi:[0,1,0]
	v_add_f32_dpp v188, v188, v187 quad_perm:[1,0,3,2] row_mask:0xf bank_mask:0xf bound_ctrl:1
	v_add_f32_dpp v189, v190, v189 quad_perm:[1,0,3,2] row_mask:0xf bank_mask:0xf bound_ctrl:1
	v_fma_mix_f32 v98, v86, v7, v98 op_sel:[0,0,0] op_sel_hi:[0,1,0]
	v_fma_mix_f32 v98, v87, v7, v98 op_sel:[0,1,0] op_sel_hi:[0,1,0]
	v_cndmask_b32_e64 v191, v189, v188, s[40:41]
	v_cndmask_b32_e64 v192, v188, v189, s[40:41]
	v_fma_mix_f32 v100, v88, v14, 0 op_sel:[0,0,0] op_sel_hi:[1,1,0]
	v_fma_mix_f32 v101, v88, v14, 0 op_sel:[0,1,0] op_sel_hi:[1,1,0]
	v_add_f32_dpp v192, v192, v191 quad_perm:[2,3,0,1] row_mask:0xf bank_mask:0xf bound_ctrl:1
	v_add_f32_dpp v98, v98, v98 quad_perm:[1,0,3,2] row_mask:0xf bank_mask:0xf bound_ctrl:1
	v_fma_mix_f32 v102, v88, v15, 0 op_sel:[0,0,0] op_sel_hi:[1,1,0]
	v_add_f32_dpp v192, v192, v192 row_ror:4 row_mask:0xf bank_mask:0xf bound_ctrl:1
	v_fma_mix_f32 v103, v88, v15, 0 op_sel:[0,1,0] op_sel_hi:[1,1,0]
	v_add_f32_dpp v98, v98, v98 quad_perm:[2,3,0,1] row_mask:0xf bank_mask:0xf bound_ctrl:1
	v_add_f32_dpp v192, v192, v192 row_ror:8 row_mask:0xf bank_mask:0xf bound_ctrl:1
	v_cvt_f16_f32_e32 v192, v192
	global_store_short v83, v192, s[36:37]
	s_add_u32 s36, s36, s44
	s_addc_u32 s37, s37, s45
	ds_read_b128 v[56:59], v194 offset:23552
	ds_read_b128 v[72:75], v194 offset:21504
	ds_read_b128 v[64:67], v194 offset:21760
	ds_read_b128 v[76:79], v194 offset:22528
	ds_read_b128 v[68:71], v194 offset:22784
	ds_read_b128 v[40:43], v194 offset:23808
	ds_read_b128 v[52:55], v194 offset:22016
	ds_read_b128 v[44:47], v194 offset:22272
	ds_read_b128 v[60:63], v194 offset:23040
	ds_read_b128 v[48:51], v194 offset:23296
	ds_read_b64 v[92:93], v195 offset:24064
	v_fma_mix_f32 v84, v84, v4, v100 op_sel:[0,0,0] op_sel_hi:[0,1,0]
	v_fma_mix_f32 v85, v85, v4, v101 op_sel:[0,1,0] op_sel_hi:[0,1,0]
	v_add_f32_dpp v98, v98, v98 row_half_mirror row_mask:0xf bank_mask:0xf bound_ctrl:1
	v_fma_mix_f32 v86, v86, v5, v102 op_sel:[0,0,0] op_sel_hi:[0,1,0]
	v_fma_mix_f32 v87, v87, v5, v103 op_sel:[0,1,0] op_sel_hi:[0,1,0]
	v_add_f32_dpp v98, v98, v98 row_mirror row_mask:0xf bank_mask:0xf bound_ctrl:1
	v_fma_mix_f32 v84, -v98, v12, v84 op_sel:[0,0,0] op_sel_hi:[0,1,0]
	v_fma_mix_f32 v85, -v98, v12, v85 op_sel:[0,1,0] op_sel_hi:[0,1,0]
	v_fma_mix_f32 v86, -v98, v13, v86 op_sel:[0,0,0] op_sel_hi:[0,1,0]
	v_fma_mix_f32 v87, -v98, v13, v87 op_sel:[0,1,0] op_sel_hi:[0,1,0]
	v_fma_mix_f32 v99, v84, v10, 0 op_sel:[0,0,0] op_sel_hi:[0,1,0]
	v_fma_mix_f32 v96, v84, v0, 0 op_sel:[0,0,0] op_sel_hi:[0,1,0]
	v_fma_mix_f32 v99, v85, v10, v99 op_sel:[0,1,0] op_sel_hi:[0,1,0]
	v_fma_mix_f32 v96, v85, v0, v96 op_sel:[0,1,0] op_sel_hi:[0,1,0]
	v_fma_mix_f32 v99, v86, v11, v99 op_sel:[0,0,0] op_sel_hi:[0,1,0]
	v_fma_mix_f32 v96, v86, v1, v96 op_sel:[0,0,0] op_sel_hi:[0,1,0]
	v_fma_mix_f32 v99, v87, v11, v99 op_sel:[0,1,0] op_sel_hi:[0,1,0]
	v_fma_mix_f32 v96, v87, v1, v96 op_sel:[0,1,0] op_sel_hi:[0,1,0]
	v_fma_mix_f32 v101, v88, v18, 0 op_sel:[1,0,0] op_sel_hi:[1,1,0]
	v_fma_mix_f32 v102, v88, v18, 0 op_sel:[1,1,0] op_sel_hi:[1,1,0]
	v_add_f32_dpp v99, v99, v99 quad_perm:[1,0,3,2] row_mask:0xf bank_mask:0xf bound_ctrl:1
	v_fma_mix_f32 v103, v88, v19, 0 op_sel:[1,0,0] op_sel_hi:[1,1,0]
	v_fma_mix_f32 v104, v88, v19, 0 op_sel:[1,1,0] op_sel_hi:[1,1,0]
	v_add_f32_dpp v99, v99, v99 quad_perm:[2,3,0,1] row_mask:0xf bank_mask:0xf bound_ctrl:1
	v_fma_mix_f32 v84, v84, v8, v101 op_sel:[0,0,0] op_sel_hi:[0,1,0]
	v_fma_mix_f32 v85, v85, v8, v102 op_sel:[0,1,0] op_sel_hi:[0,1,0]
	v_add_f32_dpp v99, v99, v99 row_half_mirror row_mask:0xf bank_mask:0xf bound_ctrl:1
	v_fma_mix_f32 v86, v86, v9, v103 op_sel:[0,0,0] op_sel_hi:[0,1,0]
	v_fma_mix_f32 v87, v87, v9, v104 op_sel:[0,1,0] op_sel_hi:[0,1,0]
	v_add_f32_dpp v99, v99, v99 row_mirror row_mask:0xf bank_mask:0xf bound_ctrl:1
	v_fma_mix_f32 v84, -v99, v16, v84 op_sel:[0,0,0] op_sel_hi:[0,1,0]
	v_fma_mix_f32 v85, -v99, v16, v85 op_sel:[0,1,0] op_sel_hi:[0,1,0]
	v_fma_mix_f32 v86, -v99, v17, v86 op_sel:[0,0,0] op_sel_hi:[0,1,0]
	v_fma_mix_f32 v87, -v99, v17, v87 op_sel:[0,1,0] op_sel_hi:[0,1,0]
	v_fma_mix_f32 v100, v84, v26, 0 op_sel:[0,0,0] op_sel_hi:[0,1,0]
	v_fma_mix_f32 v97, v84, v2, 0 op_sel:[0,0,0] op_sel_hi:[0,1,0]
	v_fma_mix_f32 v100, v85, v26, v100 op_sel:[0,1,0] op_sel_hi:[0,1,0]
	v_fma_mix_f32 v97, v85, v2, v97 op_sel:[0,1,0] op_sel_hi:[0,1,0]
	v_fma_mix_f32 v100, v86, v27, v100 op_sel:[0,0,0] op_sel_hi:[0,1,0]
	v_fma_mix_f32 v97, v86, v3, v97 op_sel:[0,0,0] op_sel_hi:[0,1,0]
	v_fma_mix_f32 v100, v87, v27, v100 op_sel:[0,1,0] op_sel_hi:[0,1,0]
	v_fma_mix_f32 v97, v87, v3, v97 op_sel:[0,1,0] op_sel_hi:[0,1,0]
	v_fma_mix_f32 v102, v89, v34, 0 op_sel:[0,0,0] op_sel_hi:[1,1,0]
	v_fma_mix_f32 v103, v89, v34, 0 op_sel:[0,1,0] op_sel_hi:[1,1,0]
	v_add_f32_dpp v100, v100, v100 quad_perm:[1,0,3,2] row_mask:0xf bank_mask:0xf bound_ctrl:1
	v_fma_mix_f32 v104, v89, v35, 0 op_sel:[0,0,0] op_sel_hi:[1,1,0]
	v_fma_mix_f32 v105, v89, v35, 0 op_sel:[0,1,0] op_sel_hi:[1,1,0]
	v_add_f32_dpp v100, v100, v100 quad_perm:[2,3,0,1] row_mask:0xf bank_mask:0xf bound_ctrl:1
	v_fma_mix_f32 v84, v84, v24, v102 op_sel:[0,0,0] op_sel_hi:[0,1,0]
	v_fma_mix_f32 v85, v85, v24, v103 op_sel:[0,1,0] op_sel_hi:[0,1,0]
	v_add_f32_dpp v100, v100, v100 row_half_mirror row_mask:0xf bank_mask:0xf bound_ctrl:1
	v_fma_mix_f32 v86, v86, v25, v104 op_sel:[0,0,0] op_sel_hi:[0,1,0]
	v_fma_mix_f32 v87, v87, v25, v105 op_sel:[0,1,0] op_sel_hi:[0,1,0]
	v_add_f32_dpp v100, v100, v100 row_mirror row_mask:0xf bank_mask:0xf bound_ctrl:1
	v_fma_mix_f32 v84, -v100, v32, v84 op_sel:[0,0,0] op_sel_hi:[0,1,0]
	v_fma_mix_f32 v85, -v100, v32, v85 op_sel:[0,1,0] op_sel_hi:[0,1,0]
	v_fma_mix_f32 v86, -v100, v33, v86 op_sel:[0,0,0] op_sel_hi:[0,1,0]
	v_fma_mix_f32 v87, -v100, v33, v87 op_sel:[0,1,0] op_sel_hi:[0,1,0]
	v_fma_mix_f32 v101, v84, v30, 0 op_sel:[0,0,0] op_sel_hi:[0,1,0]
	v_fma_mix_f32 v98, v84, v20, 0 op_sel:[0,0,0] op_sel_hi:[0,1,0]
	v_fma_mix_f32 v101, v85, v30, v101 op_sel:[0,1,0] op_sel_hi:[0,1,0]
	v_fma_mix_f32 v98, v85, v20, v98 op_sel:[0,1,0] op_sel_hi:[0,1,0]
	v_fma_mix_f32 v101, v86, v31, v101 op_sel:[0,0,0] op_sel_hi:[0,1,0]
	v_fma_mix_f32 v98, v86, v21, v98 op_sel:[0,0,0] op_sel_hi:[0,1,0]
	v_fma_mix_f32 v101, v87, v31, v101 op_sel:[0,1,0] op_sel_hi:[0,1,0]
	v_fma_mix_f32 v98, v87, v21, v98 op_sel:[0,1,0] op_sel_hi:[0,1,0]
	v_fma_mix_f32 v103, v89, v38, 0 op_sel:[1,0,0] op_sel_hi:[1,1,0]
	v_fma_mix_f32 v104, v89, v38, 0 op_sel:[1,1,0] op_sel_hi:[1,1,0]
	v_add_f32_dpp v101, v101, v101 quad_perm:[1,0,3,2] row_mask:0xf bank_mask:0xf bound_ctrl:1
	v_fma_mix_f32 v105, v89, v39, 0 op_sel:[1,0,0] op_sel_hi:[1,1,0]
	v_fma_mix_f32 v119, v89, v39, 0 op_sel:[1,1,0] op_sel_hi:[1,1,0]
	v_add_f32_dpp v101, v101, v101 quad_perm:[2,3,0,1] row_mask:0xf bank_mask:0xf bound_ctrl:1
	v_fma_mix_f32 v84, v84, v28, v103 op_sel:[0,0,0] op_sel_hi:[0,1,0]
	v_fma_mix_f32 v85, v85, v28, v104 op_sel:[0,1,0] op_sel_hi:[0,1,0]
	v_add_f32_dpp v101, v101, v101 row_half_mirror row_mask:0xf bank_mask:0xf bound_ctrl:1
	v_fma_mix_f32 v86, v86, v29, v105 op_sel:[0,0,0] op_sel_hi:[0,1,0]
	v_fma_mix_f32 v87, v87, v29, v119 op_sel:[0,1,0] op_sel_hi:[0,1,0]
	v_add_f32_dpp v101, v101, v101 row_mirror row_mask:0xf bank_mask:0xf bound_ctrl:1
	v_fma_mix_f32 v84, -v101, v36, v84 op_sel:[0,0,0] op_sel_hi:[0,1,0]
	v_fma_mix_f32 v85, -v101, v36, v85 op_sel:[0,1,0] op_sel_hi:[0,1,0]
	v_fma_mix_f32 v86, -v101, v37, v86 op_sel:[0,0,0] op_sel_hi:[0,1,0]
	v_fma_mix_f32 v87, -v101, v37, v87 op_sel:[0,1,0] op_sel_hi:[0,1,0]
	v_fma_mix_f32 v99, v84, v22, 0 op_sel:[0,0,0] op_sel_hi:[0,1,0]
	v_cndmask_b32_e64 v187, v97, v96, s[38:39]
	v_fma_mix_f32 v99, v85, v22, v99 op_sel:[0,1,0] op_sel_hi:[0,1,0]
	v_cndmask_b32_e64 v188, v96, v97, s[38:39]
	v_fma_mix_f32 v99, v86, v23, v99 op_sel:[0,0,0] op_sel_hi:[0,1,0]
	v_fma_mix_f32 v99, v87, v23, v99 op_sel:[0,1,0] op_sel_hi:[0,1,0]
	v_cndmask_b32_e64 v189, v99, v98, s[38:39]
	v_cndmask_b32_e64 v190, v98, v99, s[38:39]
	s_waitcnt lgkmcnt(0)
	v_fma_mix_f32 v98, v84, v74, 0 op_sel:[0,0,0] op_sel_hi:[0,1,0]
	v_fma_mix_f32 v98, v85, v74, v98 op_sel:[0,1,0] op_sel_hi:[0,1,0]
	v_add_f32_dpp v188, v188, v187 quad_perm:[1,0,3,2] row_mask:0xf bank_mask:0xf bound_ctrl:1
	v_add_f32_dpp v189, v190, v189 quad_perm:[1,0,3,2] row_mask:0xf bank_mask:0xf bound_ctrl:1
	v_fma_mix_f32 v98, v86, v75, v98 op_sel:[0,0,0] op_sel_hi:[0,1,0]
	v_fma_mix_f32 v98, v87, v75, v98 op_sel:[0,1,0] op_sel_hi:[0,1,0]
	v_cndmask_b32_e64 v191, v189, v188, s[40:41]
	v_cndmask_b32_e64 v192, v188, v189, s[40:41]
	v_fma_mix_f32 v100, v92, v78, 0 op_sel:[0,0,0] op_sel_hi:[1,1,0]
	v_fma_mix_f32 v101, v92, v78, 0 op_sel:[0,1,0] op_sel_hi:[1,1,0]
	v_add_f32_dpp v192, v192, v191 quad_perm:[2,3,0,1] row_mask:0xf bank_mask:0xf bound_ctrl:1
	v_add_f32_dpp v98, v98, v98 quad_perm:[1,0,3,2] row_mask:0xf bank_mask:0xf bound_ctrl:1
	v_fma_mix_f32 v102, v92, v79, 0 op_sel:[0,0,0] op_sel_hi:[1,1,0]
	v_add_f32_dpp v192, v192, v192 row_ror:4 row_mask:0xf bank_mask:0xf bound_ctrl:1
	v_fma_mix_f32 v103, v92, v79, 0 op_sel:[0,1,0] op_sel_hi:[1,1,0]
	v_add_f32_dpp v98, v98, v98 quad_perm:[2,3,0,1] row_mask:0xf bank_mask:0xf bound_ctrl:1
	v_add_f32_dpp v192, v192, v192 row_ror:8 row_mask:0xf bank_mask:0xf bound_ctrl:1
	v_cvt_f16_f32_e32 v192, v192
	global_store_short v83, v192, s[36:37]
	s_add_u32 s36, s36, s44
	s_addc_u32 s37, s37, s45
	s_cmp_gt_i32 s35, 9
	s_cbranch_scc0 .Lc_poll_A3
.Lc_ret_A3:
	ds_read_b128 v[0:3], v194 offset:26624
	ds_read_b128 v[4:7], v194 offset:24576
	ds_read_b128 v[8:11], v194 offset:24832
	ds_read_b128 v[12:15], v194 offset:25600
	ds_read_b128 v[16:19], v194 offset:25856
	ds_read_b128 v[20:23], v194 offset:26880
	ds_read_b128 v[24:27], v194 offset:25088
	ds_read_b128 v[28:31], v194 offset:25344
	ds_read_b128 v[32:35], v194 offset:26112
	ds_read_b128 v[36:39], v194 offset:26368
	ds_read_b64 v[88:89], v195 offset:27136
	v_fma_mix_f32 v84, v84, v72, v100 op_sel:[0,0,0] op_sel_hi:[0,1,0]
	v_fma_mix_f32 v85, v85, v72, v101 op_sel:[0,1,0] op_sel_hi:[0,1,0]
	v_add_f32_dpp v98, v98, v98 row_half_mirror row_mask:0xf bank_mask:0xf bound_ctrl:1
	v_fma_mix_f32 v86, v86, v73, v102 op_sel:[0,0,0] op_sel_hi:[0,1,0]
	v_fma_mix_f32 v87, v87, v73, v103 op_sel:[0,1,0] op_sel_hi:[0,1,0]
	v_add_f32_dpp v98, v98, v98 row_mirror row_mask:0xf bank_mask:0xf bound_ctrl:1
	v_fma_mix_f32 v84, -v98, v76, v84 op_sel:[0,0,0] op_sel_hi:[0,1,0]
	v_fma_mix_f32 v85, -v98, v76, v85 op_sel:[0,1,0] op_sel_hi:[0,1,0]
	v_fma_mix_f32 v86, -v98, v77, v86 op_sel:[0,0,0] op_sel_hi:[0,1,0]
	v_fma_mix_f32 v87, -v98, v77, v87 op_sel:[0,1,0] op_sel_hi:[0,1,0]
	v_fma_mix_f32 v73, v84, v66, 0 op_sel:[0,0,0] op_sel_hi:[0,1,0]
	v_fma_mix_f32 v97, v84, v56, 0 op_sel:[0,0,0] op_sel_hi:[0,1,0]
	v_fma_mix_f32 v73, v85, v66, v73 op_sel:[0,1,0] op_sel_hi:[0,1,0]
	v_fma_mix_f32 v56, v85, v56, v97 op_sel:[0,1,0] op_sel_hi:[0,1,0]
	v_fma_mix_f32 v73, v86, v67, v73 op_sel:[0,0,0] op_sel_hi:[0,1,0]
	v_fma_mix_f32 v56, v86, v57, v56 op_sel:[0,0,0] op_sel_hi:[0,1,0]
	v_fma_mix_f32 v73, v87, v67, v73 op_sel:[0,1,0] op_sel_hi:[0,1,0]
	v_fma_mix_f32 v56, v87, v57, v56 op_sel:[0,1,0] op_sel_hi:[0,1,0]
	v_fma_mix_f32 v75, v92, v70, 0 op_sel:[1,0,0] op_sel_hi:[1,1,0]
	v_fma_mix_f32 v76, v92, v70, 0 op_sel:[1,1,0] op_sel_hi:[1,1,0]
	v_add_f32_dpp v73, v73, v73 quad_perm:[1,0,3,2] row_mask:0xf bank_mask:0xf bound_ctrl:1
	v_fma_mix_f32 v77, v92, v71, 0 op_sel:[1,0,0] op_sel_hi:[1,1,0]
	v_fma_mix_f32 v78, v92, v71, 0 op_sel:[1,1,0] op_sel_hi:[1,1,0]
	v_add_f32_dpp v73, v73, v73 quad_perm:[2,3,0,1] row_mask:0xf bank_mask:0xf bound_ctrl:1
	v_fma_mix_f32 v84, v84, v64, v75 op_sel:[0,0,0] op_sel_hi:[0,1,0]
	v_fma_mix_f32 v85, v85, v64, v76 op_sel:[0,1,0] op_sel_hi:[0,1,0]
	v_add_f32_dpp v73, v73, v73 row_half_mirror row_mask:0xf bank_mask:0xf bound_ctrl:1
	v_fma_mix_f32 v86, v86, v65, v77 op_sel:[0,0,0] op_sel_hi:[0,1,0]
	v_fma_mix_f32 v87, v87, v65, v78 op_sel:[0,1,0] op_sel_hi:[0,1,0]
	v_add_f32_dpp v73, v73, v73 row_mirror row_mask:0xf bank_mask:0xf bound_ctrl:1
	v_fma_mix_f32 v84, -v73, v68, v84 op_sel:[0,0,0] op_sel_hi:[0,1,0]
	v_fma_mix_f32 v85, -v73, v68, v85 op_sel:[0,1,0] op_sel_hi:[0,1,0]
	v_fma_mix_f32 v86, -v73, v69, v86 op_sel:[0,0,0] op_sel_hi:[0,1,0]
	v_fma_mix_f32 v87, -v73, v69, v87 op_sel:[0,1,0] op_sel_hi:[0,1,0]
	v_fma_mix_f32 v64, v84, v54, 0 op_sel:[0,0,0] op_sel_hi:[0,1,0]
	v_fma_mix_f32 v57, v84, v58, 0 op_sel:[0,0,0] op_sel_hi:[0,1,0]
	v_fma_mix_f32 v64, v85, v54, v64 op_sel:[0,1,0] op_sel_hi:[0,1,0]
	v_fma_mix_f32 v57, v85, v58, v57 op_sel:[0,1,0] op_sel_hi:[0,1,0]
	v_fma_mix_f32 v64, v86, v55, v64 op_sel:[0,0,0] op_sel_hi:[0,1,0]
	v_fma_mix_f32 v57, v86, v59, v57 op_sel:[0,0,0] op_sel_hi:[0,1,0]
	v_fma_mix_f32 v64, v87, v55, v64 op_sel:[0,1,0] op_sel_hi:[0,1,0]
	v_fma_mix_f32 v57, v87, v59, v57 op_sel:[0,1,0] op_sel_hi:[0,1,0]
	v_fma_mix_f32 v66, v93, v62, 0 op_sel:[0,0,0] op_sel_hi:[1,1,0]
	v_fma_mix_f32 v67, v93, v62, 0 op_sel:[0,1,0] op_sel_hi:[1,1,0]
	v_add_f32_dpp v64, v64, v64 quad_perm:[1,0,3,2] row_mask:0xf bank_mask:0xf bound_ctrl:1
	v_fma_mix_f32 v68, v93, v63, 0 op_sel:[0,0,0] op_sel_hi:[1,1,0]
	v_fma_mix_f32 v69, v93, v63, 0 op_sel:[0,1,0] op_sel_hi:[1,1,0]
	v_add_f32_dpp v64, v64, v64 quad_perm:[2,3,0,1] row_mask:0xf bank_mask:0xf bound_ctrl:1
	v_fma_mix_f32 v84, v84, v52, v66 op_sel:[0,0,0] op_sel_hi:[0,1,0]
	v_fma_mix_f32 v85, v85, v52, v67 op_sel:[0,1,0] op_sel_hi:[0,1,0]
	v_add_f32_dpp v64, v64, v64 row_half_mirror row_mask:0xf bank_mask:0xf bound_ctrl:1
	v_fma_mix_f32 v86, v86, v53, v68 op_sel:[0,0,0] op_sel_hi:[0,1,0]
	v_fma_mix_f32 v87, v87, v53, v69 op_sel:[0,1,0] op_sel_hi:[0,1,0]
	v_add_f32_dpp v64, v64, v64 row_mirror row_mask:0xf bank_mask:0xf bound_ctrl:1
	v_fma_mix_f32 v84, -v64, v60, v84 op_sel:[0,0,0] op_sel_hi:[0,1,0]
	v_fma_mix_f32 v85, -v64, v60, v85 op_sel:[0,1,0] op_sel_hi:[0,1,0]
	v_fma_mix_f32 v86, -v64, v61, v86 op_sel:[0,0,0] op_sel_hi:[0,1,0]
	v_fma_mix_f32 v87, -v64, v61, v87 op_sel:[0,1,0] op_sel_hi:[0,1,0]
	v_fma_mix_f32 v53, v84, v46, 0 op_sel:[0,0,0] op_sel_hi:[0,1,0]
	v_fma_mix_f32 v59, v84, v40, 0 op_sel:[0,0,0] op_sel_hi:[0,1,0]
	v_fma_mix_f32 v53, v85, v46, v53 op_sel:[0,1,0] op_sel_hi:[0,1,0]
	v_fma_mix_f32 v40, v85, v40, v59 op_sel:[0,1,0] op_sel_hi:[0,1,0]
	v_fma_mix_f32 v53, v86, v47, v53 op_sel:[0,0,0] op_sel_hi:[0,1,0]
	v_fma_mix_f32 v40, v86, v41, v40 op_sel:[0,0,0] op_sel_hi:[0,1,0]
	v_fma_mix_f32 v53, v87, v47, v53 op_sel:[0,1,0] op_sel_hi:[0,1,0]
	v_fma_mix_f32 v40, v87, v41, v40 op_sel:[0,1,0] op_sel_hi:[0,1,0]
	v_fma_mix_f32 v55, v93, v50, 0 op_sel:[1,0,0] op_sel_hi:[1,1,0]
	v_fma_mix_f32 v58, v93, v50, 0 op_sel:[1,1,0] op_sel_hi:[1,1,0]
	v_add_f32_dpp v53, v53, v53 quad_perm:[1,0,3,2] row_mask:0xf bank_mask:0xf bound_ctrl:1
	v_fma_mix_f32 v59, v93, v51, 0 op_sel:[1,0,0] op_sel_hi:[1,1,0]
	v_fma_mix_f32 v60, v93, v51, 0 op_sel:[1,1,0] op_sel_hi:[1,1,0]
	v_add_f32_dpp v53, v53, v53 quad_perm:[2,3,0,1] row_mask:0xf bank_mask:0xf bound_ctrl:1
	v_fma_mix_f32 v84, v84, v44, v55 op_sel:[0,0,0] op_sel_hi:[0,1,0]
	v_fma_mix_f32 v85, v85, v44, v58 op_sel:[0,1,0] op_sel_hi:[0,1,0]
	v_add_f32_dpp v53, v53, v53 row_half_mirror row_mask:0xf bank_mask:0xf bound_ctrl:1
	v_fma_mix_f32 v86, v86, v45, v59 op_sel:[0,0,0] op_sel_hi:[0,1,0]
	v_fma_mix_f32 v87, v87, v45, v60 op_sel:[0,1,0] op_sel_hi:[0,1,0]
	v_add_f32_dpp v53, v53, v53 row_mirror row_mask:0xf bank_mask:0xf bound_ctrl:1
	v_fma_mix_f32 v84, -v53, v48, v84 op_sel:[0,0,0] op_sel_hi:[0,1,0]
	v_fma_mix_f32 v85, -v53, v48, v85 op_sel:[0,1,0] op_sel_hi:[0,1,0]
	v_fma_mix_f32 v86, -v53, v49, v86 op_sel:[0,0,0] op_sel_hi:[0,1,0]
	v_fma_mix_f32 v87, -v53, v49, v87 op_sel:[0,1,0] op_sel_hi:[0,1,0]
	v_fma_mix_f32 v41, v84, v42, 0 op_sel:[0,0,0] op_sel_hi:[0,1,0]
	v_add_u32_e32 v173, 8, v193
	v_fma_mix_f32 v41, v85, v42, v41 op_sel:[0,1,0] op_sel_hi:[0,1,0]
	ds_write_b32 v172, v173 offset:49216
	v_fma_mix_f32 v41, v86, v43, v41 op_sel:[0,0,0] op_sel_hi:[0,1,0]
	v_cndmask_b32_e64 v187, v57, v56, s[38:39]
	v_fma_mix_f32 v41, v87, v43, v41 op_sel:[0,1,0] op_sel_hi:[0,1,0]
	v_cndmask_b32_e64 v188, v56, v57, s[38:39]
	v_cndmask_b32_e64 v189, v41, v40, s[38:39]
	v_cndmask_b32_e64 v190, v40, v41, s[38:39]
	s_waitcnt lgkmcnt(1)
	v_fma_mix_f32 v98, v84, v6, 0 op_sel:[0,0,0] op_sel_hi:[0,1,0]
	v_fma_mix_f32 v98, v85, v6, v98 op_sel:[0,1,0] op_sel_hi:[0,1,0]
	v_add_f32_dpp v188, v188, v187 quad_perm:[1,0,3,2] row_mask:0xf bank_mask:0xf bound_ctrl:1
	v_add_f32_dpp v189, v190, v189 quad_perm:[1,0,3,2] row_mask:0xf bank_mask:0xf bound_ctrl:1
	v_fma_mix_f32 v98, v86, v7, v98 op_sel:[0,0,0] op_sel_hi:[0,1,0]
	v_fma_mix_f32 v98, v87, v7, v98 op_sel:[0,1,0] op_sel_hi:[0,1,0]
	v_cndmask_b32_e64 v191, v189, v188, s[40:41]
	v_cndmask_b32_e64 v192, v188, v189, s[40:41]
	v_fma_mix_f32 v100, v88, v14, 0 op_sel:[0,0,0] op_sel_hi:[1,1,0]
	v_fma_mix_f32 v101, v88, v14, 0 op_sel:[0,1,0] op_sel_hi:[1,1,0]
	v_add_f32_dpp v192, v192, v191 quad_perm:[2,3,0,1] row_mask:0xf bank_mask:0xf bound_ctrl:1
	v_add_f32_dpp v98, v98, v98 quad_perm:[1,0,3,2] row_mask:0xf bank_mask:0xf bound_ctrl:1
	v_fma_mix_f32 v102, v88, v15, 0 op_sel:[0,0,0] op_sel_hi:[1,1,0]
	v_add_f32_dpp v192, v192, v192 row_ror:4 row_mask:0xf bank_mask:0xf bound_ctrl:1
	v_fma_mix_f32 v103, v88, v15, 0 op_sel:[0,1,0] op_sel_hi:[1,1,0]
	v_add_f32_dpp v98, v98, v98 quad_perm:[2,3,0,1] row_mask:0xf bank_mask:0xf bound_ctrl:1
	v_add_f32_dpp v192, v192, v192 row_ror:8 row_mask:0xf bank_mask:0xf bound_ctrl:1
	v_cvt_f16_f32_e32 v192, v192
	global_store_short v83, v192, s[36:37]
	s_add_u32 s36, s36, s44
	s_addc_u32 s37, s37, s45
	ds_read_b128 v[56:59], v194 offset:29696
	ds_read_b128 v[72:75], v194 offset:27648
	ds_read_b128 v[64:67], v194 offset:27904
	ds_read_b128 v[76:79], v194 offset:28672
	ds_read_b128 v[68:71], v194 offset:28928
	ds_read_b128 v[40:43], v194 offset:29952
	ds_read_b128 v[52:55], v194 offset:28160
	ds_read_b128 v[44:47], v194 offset:28416
	ds_read_b128 v[60:63], v194 offset:29184
	ds_read_b128 v[48:51], v194 offset:29440
	ds_read_b64 v[92:93], v195 offset:30208
	v_fma_mix_f32 v84, v84, v4, v100 op_sel:[0,0,0] op_sel_hi:[0,1,0]
	v_fma_mix_f32 v85, v85, v4, v101 op_sel:[0,1,0] op_sel_hi:[0,1,0]
	v_add_f32_dpp v98, v98, v98 row_half_mirror row_mask:0xf bank_mask:0xf bound_ctrl:1
	v_fma_mix_f32 v86, v86, v5, v102 op_sel:[0,0,0] op_sel_hi:[0,1,0]
	v_fma_mix_f32 v87, v87, v5, v103 op_sel:[0,1,0] op_sel_hi:[0,1,0]
	v_add_f32_dpp v98, v98, v98 row_mirror row_mask:0xf bank_mask:0xf bound_ctrl:1
	v_fma_mix_f32 v84, -v98, v12, v84 op_sel:[0,0,0] op_sel_hi:[0,1,0]
	v_fma_mix_f32 v85, -v98, v12, v85 op_sel:[0,1,0] op_sel_hi:[0,1,0]
	v_fma_mix_f32 v86, -v98, v13, v86 op_sel:[0,0,0] op_sel_hi:[0,1,0]
	v_fma_mix_f32 v87, -v98, v13, v87 op_sel:[0,1,0] op_sel_hi:[0,1,0]
	v_fma_mix_f32 v99, v84, v10, 0 op_sel:[0,0,0] op_sel_hi:[0,1,0]
	v_fma_mix_f32 v96, v84, v0, 0 op_sel:[0,0,0] op_sel_hi:[0,1,0]
	v_fma_mix_f32 v99, v85, v10, v99 op_sel:[0,1,0] op_sel_hi:[0,1,0]
	v_fma_mix_f32 v96, v85, v0, v96 op_sel:[0,1,0] op_sel_hi:[0,1,0]
	v_fma_mix_f32 v99, v86, v11, v99 op_sel:[0,0,0] op_sel_hi:[0,1,0]
	v_fma_mix_f32 v96, v86, v1, v96 op_sel:[0,0,0] op_sel_hi:[0,1,0]
	v_fma_mix_f32 v99, v87, v11, v99 op_sel:[0,1,0] op_sel_hi:[0,1,0]
	v_fma_mix_f32 v96, v87, v1, v96 op_sel:[0,1,0] op_sel_hi:[0,1,0]
	v_fma_mix_f32 v101, v88, v18, 0 op_sel:[1,0,0] op_sel_hi:[1,1,0]
	v_fma_mix_f32 v102, v88, v18, 0 op_sel:[1,1,0] op_sel_hi:[1,1,0]
	v_add_f32_dpp v99, v99, v99 quad_perm:[1,0,3,2] row_mask:0xf bank_mask:0xf bound_ctrl:1
	v_fma_mix_f32 v103, v88, v19, 0 op_sel:[1,0,0] op_sel_hi:[1,1,0]
	v_fma_mix_f32 v104, v88, v19, 0 op_sel:[1,1,0] op_sel_hi:[1,1,0]
	v_add_f32_dpp v99, v99, v99 quad_perm:[2,3,0,1] row_mask:0xf bank_mask:0xf bound_ctrl:1
	v_fma_mix_f32 v84, v84, v8, v101 op_sel:[0,0,0] op_sel_hi:[0,1,0]
	v_fma_mix_f32 v85, v85, v8, v102 op_sel:[0,1,0] op_sel_hi:[0,1,0]
	v_add_f32_dpp v99, v99, v99 row_half_mirror row_mask:0xf bank_mask:0xf bound_ctrl:1
	v_fma_mix_f32 v86, v86, v9, v103 op_sel:[0,0,0] op_sel_hi:[0,1,0]
	v_fma_mix_f32 v87, v87, v9, v104 op_sel:[0,1,0] op_sel_hi:[0,1,0]
	v_add_f32_dpp v99, v99, v99 row_mirror row_mask:0xf bank_mask:0xf bound_ctrl:1
	v_fma_mix_f32 v84, -v99, v16, v84 op_sel:[0,0,0] op_sel_hi:[0,1,0]
	v_fma_mix_f32 v85, -v99, v16, v85 op_sel:[0,1,0] op_sel_hi:[0,1,0]
	v_fma_mix_f32 v86, -v99, v17, v86 op_sel:[0,0,0] op_sel_hi:[0,1,0]
	v_fma_mix_f32 v87, -v99, v17, v87 op_sel:[0,1,0] op_sel_hi:[0,1,0]
	v_fma_mix_f32 v100, v84, v26, 0 op_sel:[0,0,0] op_sel_hi:[0,1,0]
	v_fma_mix_f32 v97, v84, v2, 0 op_sel:[0,0,0] op_sel_hi:[0,1,0]
	v_fma_mix_f32 v100, v85, v26, v100 op_sel:[0,1,0] op_sel_hi:[0,1,0]
	v_fma_mix_f32 v97, v85, v2, v97 op_sel:[0,1,0] op_sel_hi:[0,1,0]
	v_fma_mix_f32 v100, v86, v27, v100 op_sel:[0,0,0] op_sel_hi:[0,1,0]
	v_fma_mix_f32 v97, v86, v3, v97 op_sel:[0,0,0] op_sel_hi:[0,1,0]
	v_fma_mix_f32 v100, v87, v27, v100 op_sel:[0,1,0] op_sel_hi:[0,1,0]
	v_fma_mix_f32 v97, v87, v3, v97 op_sel:[0,1,0] op_sel_hi:[0,1,0]
	v_fma_mix_f32 v102, v89, v34, 0 op_sel:[0,0,0] op_sel_hi:[1,1,0]
	v_fma_mix_f32 v103, v89, v34, 0 op_sel:[0,1,0] op_sel_hi:[1,1,0]
	v_add_f32_dpp v100, v100, v100 quad_perm:[1,0,3,2] row_mask:0xf bank_mask:0xf bound_ctrl:1
	v_fma_mix_f32 v104, v89, v35, 0 op_sel:[0,0,0] op_sel_hi:[1,1,0]
	v_fma_mix_f32 v105, v89, v35, 0 op_sel:[0,1,0] op_sel_hi:[1,1,0]
	v_add_f32_dpp v100, v100, v100 quad_perm:[2,3,0,1] row_mask:0xf bank_mask:0xf bound_ctrl:1
	v_fma_mix_f32 v84, v84, v24, v102 op_sel:[0,0,0] op_sel_hi:[0,1,0]
	v_fma_mix_f32 v85, v85, v24, v103 op_sel:[0,1,0] op_sel_hi:[0,1,0]
	v_add_f32_dpp v100, v100, v100 row_half_mirror row_mask:0xf bank_mask:0xf bound_ctrl:1
	v_fma_mix_f32 v86, v86, v25, v104 op_sel:[0,0,0] op_sel_hi:[0,1,0]
	v_fma_mix_f32 v87, v87, v25, v105 op_sel:[0,1,0] op_sel_hi:[0,1,0]
	v_add_f32_dpp v100, v100, v100 row_mirror row_mask:0xf bank_mask:0xf bound_ctrl:1
	v_fma_mix_f32 v84, -v100, v32, v84 op_sel:[0,0,0] op_sel_hi:[0,1,0]
	v_fma_mix_f32 v85, -v100, v32, v85 op_sel:[0,1,0] op_sel_hi:[0,1,0]
	v_fma_mix_f32 v86, -v100, v33, v86 op_sel:[0,0,0] op_sel_hi:[0,1,0]
	v_fma_mix_f32 v87, -v100, v33, v87 op_sel:[0,1,0] op_sel_hi:[0,1,0]
	v_fma_mix_f32 v101, v84, v30, 0 op_sel:[0,0,0] op_sel_hi:[0,1,0]
	v_fma_mix_f32 v98, v84, v20, 0 op_sel:[0,0,0] op_sel_hi:[0,1,0]
	v_fma_mix_f32 v101, v85, v30, v101 op_sel:[0,1,0] op_sel_hi:[0,1,0]
	v_fma_mix_f32 v98, v85, v20, v98 op_sel:[0,1,0] op_sel_hi:[0,1,0]
	v_fma_mix_f32 v101, v86, v31, v101 op_sel:[0,0,0] op_sel_hi:[0,1,0]
	v_fma_mix_f32 v98, v86, v21, v98 op_sel:[0,0,0] op_sel_hi:[0,1,0]
	v_fma_mix_f32 v101, v87, v31, v101 op_sel:[0,1,0] op_sel_hi:[0,1,0]
	v_fma_mix_f32 v98, v87, v21, v98 op_sel:[0,1,0] op_sel_hi:[0,1,0]
	v_fma_mix_f32 v103, v89, v38, 0 op_sel:[1,0,0] op_sel_hi:[1,1,0]
	v_fma_mix_f32 v104, v89, v38, 0 op_sel:[1,1,0] op_sel_hi:[1,1,0]
	v_add_f32_dpp v101, v101, v101 quad_perm:[1,0,3,2] row_mask:0xf bank_mask:0xf bound_ctrl:1
	v_fma_mix_f32 v105, v89, v39, 0 op_sel:[1,0,0] op_sel_hi:[1,1,0]
	v_fma_mix_f32 v119, v89, v39, 0 op_sel:[1,1,0] op_sel_hi:[1,1,0]
	v_add_f32_dpp v101, v101, v101 quad_perm:[2,3,0,1] row_mask:0xf bank_mask:0xf bound_ctrl:1
	v_fma_mix_f32 v84, v84, v28, v103 op_sel:[0,0,0] op_sel_hi:[0,1,0]
	v_fma_mix_f32 v85, v85, v28, v104 op_sel:[0,1,0] op_sel_hi:[0,1,0]
	v_add_f32_dpp v101, v101, v101 row_half_mirror row_mask:0xf bank_mask:0xf bound_ctrl:1
	v_fma_mix_f32 v86, v86, v29, v105 op_sel:[0,0,0] op_sel_hi:[0,1,0]
	v_fma_mix_f32 v87, v87, v29, v119 op_sel:[0,1,0] op_sel_hi:[0,1,0]
	v_add_f32_dpp v101, v101, v101 row_mirror row_mask:0xf bank_mask:0xf bound_ctrl:1
	v_fma_mix_f32 v84, -v101, v36, v84 op_sel:[0,0,0] op_sel_hi:[0,1,0]
	v_fma_mix_f32 v85, -v101, v36, v85 op_sel:[0,1,0] op_sel_hi:[0,1,0]
	v_fma_mix_f32 v86, -v101, v37, v86 op_sel:[0,0,0] op_sel_hi:[0,1,0]
	v_fma_mix_f32 v87, -v101, v37, v87 op_sel:[0,1,0] op_sel_hi:[0,1,0]
	v_fma_mix_f32 v99, v84, v22, 0 op_sel:[0,0,0] op_sel_hi:[0,1,0]
	v_cndmask_b32_e64 v187, v97, v96, s[38:39]
	v_fma_mix_f32 v99, v85, v22, v99 op_sel:[0,1,0] op_sel_hi:[0,1,0]
	v_cndmask_b32_e64 v188, v96, v97, s[38:39]
	v_fma_mix_f32 v99, v86, v23, v99 op_sel:[0,0,0] op_sel_hi:[0,1,0]
	v_fma_mix_f32 v99, v87, v23, v99 op_sel:[0,1,0] op_sel_hi:[0,1,0]
	v_cndmask_b32_e64 v189, v99, v98, s[38:39]
	v_cndmask_b32_e64 v190, v98, v99, s[38:39]
	s_waitcnt lgkmcnt(0)
	v_fma_mix_f32 v98, v84, v74, 0 op_sel:[0,0,0] op_sel_hi:[0,1,0]
	v_fma_mix_f32 v98, v85, v74, v98 op_sel:[0,1,0] op_sel_hi:[0,1,0]
	v_add_f32_dpp v188, v188, v187 quad_perm:[1,0,3,2] row_mask:0xf bank_mask:0xf bound_ctrl:1
	v_add_f32_dpp v189, v190, v189 quad_perm:[1,0,3,2] row_mask:0xf bank_mask:0xf bound_ctrl:1
	v_fma_mix_f32 v98, v86, v75, v98 op_sel:[0,0,0] op_sel_hi:[0,1,0]
	v_fma_mix_f32 v98, v87, v75, v98 op_sel:[0,1,0] op_sel_hi:[0,1,0]
	v_cndmask_b32_e64 v191, v189, v188, s[40:41]
	v_cndmask_b32_e64 v192, v188, v189, s[40:41]
	v_fma_mix_f32 v100, v92, v78, 0 op_sel:[0,0,0] op_sel_hi:[1,1,0]
	v_fma_mix_f32 v101, v92, v78, 0 op_sel:[0,1,0] op_sel_hi:[1,1,0]
	v_add_f32_dpp v192, v192, v191 quad_perm:[2,3,0,1] row_mask:0xf bank_mask:0xf bound_ctrl:1
	v_add_f32_dpp v98, v98, v98 quad_perm:[1,0,3,2] row_mask:0xf bank_mask:0xf bound_ctrl:1
	v_fma_mix_f32 v102, v92, v79, 0 op_sel:[0,0,0] op_sel_hi:[1,1,0]
	v_add_f32_dpp v192, v192, v192 row_ror:4 row_mask:0xf bank_mask:0xf bound_ctrl:1
	v_fma_mix_f32 v103, v92, v79, 0 op_sel:[0,1,0] op_sel_hi:[1,1,0]
	v_add_f32_dpp v98, v98, v98 quad_perm:[2,3,0,1] row_mask:0xf bank_mask:0xf bound_ctrl:1
	v_add_f32_dpp v192, v192, v192 row_ror:8 row_mask:0xf bank_mask:0xf bound_ctrl:1
	v_cvt_f16_f32_e32 v192, v192
	global_store_short v83, v192, s[36:37]
	s_add_u32 s36, s36, s44
	s_addc_u32 s37, s37, s45
	s_cmp_gt_i32 s35, 11
	s_cbranch_scc0 .Lc_poll_A4
.Lc_ret_A4:
	ds_read_b128 v[0:3], v194 offset:32768
	ds_read_b128 v[4:7], v194 offset:30720
	ds_read_b128 v[8:11], v194 offset:30976
	ds_read_b128 v[12:15], v194 offset:31744
	ds_read_b128 v[16:19], v194 offset:32000
	ds_read_b128 v[20:23], v194 offset:33024
	ds_read_b128 v[24:27], v194 offset:31232
	ds_read_b128 v[28:31], v194 offset:31488
	ds_read_b128 v[32:35], v194 offset:32256
	ds_read_b128 v[36:39], v194 offset:32512
	ds_read_b64 v[88:89], v195 offset:33280
	v_fma_mix_f32 v84, v84, v72, v100 op_sel:[0,0,0] op_sel_hi:[0,1,0]
	v_fma_mix_f32 v85, v85, v72, v101 op_sel:[0,1,0] op_sel_hi:[0,1,0]
	v_add_f32_dpp v98, v98, v98 row_half_mirror row_mask:0xf bank_mask:0xf bound_ctrl:1
	v_fma_mix_f32 v86, v86, v73, v102 op_sel:[0,0,0] op_sel_hi:[0,1,0]
	v_fma_mix_f32 v87, v87, v73, v103 op_sel:[0,1,0] op_sel_hi:[0,1,0]
	v_add_f32_dpp v98, v98, v98 row_mirror row_mask:0xf bank_mask:0xf bound_ctrl:1
	v_fma_mix_f32 v84, -v98, v76, v84 op_sel:[0,0,0] op_sel_hi:[0,1,0]
	v_fma_mix_f32 v85, -v98, v76, v85 op_sel:[0,1,0] op_sel_hi:[0,1,0]
	v_fma_mix_f32 v86, -v98, v77, v86 op_sel:[0,0,0] op_sel_hi:[0,1,0]
	v_fma_mix_f32 v87, -v98, v77, v87 op_sel:[0,1,0] op_sel_hi:[0,1,0]
	v_fma_mix_f32 v73, v84, v66, 0 op_sel:[0,0,0] op_sel_hi:[0,1,0]
	v_fma_mix_f32 v97, v84, v56, 0 op_sel:[0,0,0] op_sel_hi:[0,1,0]
	v_fma_mix_f32 v73, v85, v66, v73 op_sel:[0,1,0] op_sel_hi:[0,1,0]
	v_fma_mix_f32 v56, v85, v56, v97 op_sel:[0,1,0] op_sel_hi:[0,1,0]
	v_fma_mix_f32 v73, v86, v67, v73 op_sel:[0,0,0] op_sel_hi:[0,1,0]
	v_fma_mix_f32 v56, v86, v57, v56 op_sel:[0,0,0] op_sel_hi:[0,1,0]
	v_fma_mix_f32 v73, v87, v67, v73 op_sel:[0,1,0] op_sel_hi:[0,1,0]
	v_fma_mix_f32 v56, v87, v57, v56 op_sel:[0,1,0] op_sel_hi:[0,1,0]
	v_fma_mix_f32 v75, v92, v70, 0 op_sel:[1,0,0] op_sel_hi:[1,1,0]
	v_fma_mix_f32 v76, v92, v70, 0 op_sel:[1,1,0] op_sel_hi:[1,1,0]
	v_add_f32_dpp v73, v73, v73 quad_perm:[1,0,3,2] row_mask:0xf bank_mask:0xf bound_ctrl:1
	v_fma_mix_f32 v77, v92, v71, 0 op_sel:[1,0,0] op_sel_hi:[1,1,0]
	v_fma_mix_f32 v78, v92, v71, 0 op_sel:[1,1,0] op_sel_hi:[1,1,0]
	v_add_f32_dpp v73, v73, v73 quad_perm:[2,3,0,1] row_mask:0xf bank_mask:0xf bound_ctrl:1
	v_fma_mix_f32 v84, v84, v64, v75 op_sel:[0,0,0] op_sel_hi:[0,1,0]
	v_fma_mix_f32 v85, v85, v64, v76 op_sel:[0,1,0] op_sel_hi:[0,1,0]
	v_add_f32_dpp v73, v73, v73 row_half_mirror row_mask:0xf bank_mask:0xf bound_ctrl:1
	v_fma_mix_f32 v86, v86, v65, v77 op_sel:[0,0,0] op_sel_hi:[0,1,0]
	v_fma_mix_f32 v87, v87, v65, v78 op_sel:[0,1,0] op_sel_hi:[0,1,0]
	v_add_f32_dpp v73, v73, v73 row_mirror row_mask:0xf bank_mask:0xf bound_ctrl:1
	v_fma_mix_f32 v84, -v73, v68, v84 op_sel:[0,0,0] op_sel_hi:[0,1,0]
	v_fma_mix_f32 v85, -v73, v68, v85 op_sel:[0,1,0] op_sel_hi:[0,1,0]
	v_fma_mix_f32 v86, -v73, v69, v86 op_sel:[0,0,0] op_sel_hi:[0,1,0]
	v_fma_mix_f32 v87, -v73, v69, v87 op_sel:[0,1,0] op_sel_hi:[0,1,0]
	v_fma_mix_f32 v64, v84, v54, 0 op_sel:[0,0,0] op_sel_hi:[0,1,0]
	v_fma_mix_f32 v57, v84, v58, 0 op_sel:[0,0,0] op_sel_hi:[0,1,0]
	v_fma_mix_f32 v64, v85, v54, v64 op_sel:[0,1,0] op_sel_hi:[0,1,0]
	v_fma_mix_f32 v57, v85, v58, v57 op_sel:[0,1,0] op_sel_hi:[0,1,0]
	v_fma_mix_f32 v64, v86, v55, v64 op_sel:[0,0,0] op_sel_hi:[0,1,0]
	v_fma_mix_f32 v57, v86, v59, v57 op_sel:[0,0,0] op_sel_hi:[0,1,0]
	v_fma_mix_f32 v64, v87, v55, v64 op_sel:[0,1,0] op_sel_hi:[0,1,0]
	v_fma_mix_f32 v57, v87, v59, v57 op_sel:[0,1,0] op_sel_hi:[0,1,0]
	v_fma_mix_f32 v66, v93, v62, 0 op_sel:[0,0,0] op_sel_hi:[1,1,0]
	v_fma_mix_f32 v67, v93, v62, 0 op_sel:[0,1,0] op_sel_hi:[1,1,0]
	v_add_f32_dpp v64, v64, v64 quad_perm:[1,0,3,2] row_mask:0xf bank_mask:0xf bound_ctrl:1
	v_fma_mix_f32 v68, v93, v63, 0 op_sel:[0,0,0] op_sel_hi:[1,1,0]
	v_fma_mix_f32 v69, v93, v63, 0 op_sel:[0,1,0] op_sel_hi:[1,1,0]
	v_add_f32_dpp v64, v64, v64 quad_perm:[2,3,0,1] row_mask:0xf bank_mask:0xf bound_ctrl:1
	v_fma_mix_f32 v84, v84, v52, v66 op_sel:[0,0,0] op_sel_hi:[0,1,0]
	v_fma_mix_f32 v85, v85, v52, v67 op_sel:[0,1,0] op_sel_hi:[0,1,0]
	v_add_f32_dpp v64, v64, v64 row_half_mirror row_mask:0xf bank_mask:0xf bound_ctrl:1
	v_fma_mix_f32 v86, v86, v53, v68 op_sel:[0,0,0] op_sel_hi:[0,1,0]
	v_fma_mix_f32 v87, v87, v53, v69 op_sel:[0,1,0] op_sel_hi:[0,1,0]
	v_add_f32_dpp v64, v64, v64 row_mirror row_mask:0xf bank_mask:0xf bound_ctrl:1
	v_fma_mix_f32 v84, -v64, v60, v84 op_sel:[0,0,0] op_sel_hi:[0,1,0]
	v_fma_mix_f32 v85, -v64, v60, v85 op_sel:[0,1,0] op_sel_hi:[0,1,0]
	v_fma_mix_f32 v86, -v64, v61, v86 op_sel:[0,0,0] op_sel_hi:[0,1,0]
	v_fma_mix_f32 v87, -v64, v61, v87 op_sel:[0,1,0] op_sel_hi:[0,1,0]
	v_fma_mix_f32 v53, v84, v46, 0 op_sel:[0,0,0] op_sel_hi:[0,1,0]
	v_fma_mix_f32 v59, v84, v40, 0 op_sel:[0,0,0] op_sel_hi:[0,1,0]
	v_fma_mix_f32 v53, v85, v46, v53 op_sel:[0,1,0] op_sel_hi:[0,1,0]
	v_fma_mix_f32 v40, v85, v40, v59 op_sel:[0,1,0] op_sel_hi:[0,1,0]
	v_fma_mix_f32 v53, v86, v47, v53 op_sel:[0,0,0] op_sel_hi:[0,1,0]
	v_fma_mix_f32 v40, v86, v41, v40 op_sel:[0,0,0] op_sel_hi:[0,1,0]
	v_fma_mix_f32 v53, v87, v47, v53 op_sel:[0,1,0] op_sel_hi:[0,1,0]
	v_fma_mix_f32 v40, v87, v41, v40 op_sel:[0,1,0] op_sel_hi:[0,1,0]
	v_fma_mix_f32 v55, v93, v50, 0 op_sel:[1,0,0] op_sel_hi:[1,1,0]
	v_fma_mix_f32 v58, v93, v50, 0 op_sel:[1,1,0] op_sel_hi:[1,1,0]
	v_add_f32_dpp v53, v53, v53 quad_perm:[1,0,3,2] row_mask:0xf bank_mask:0xf bound_ctrl:1
	v_fma_mix_f32 v59, v93, v51, 0 op_sel:[1,0,0] op_sel_hi:[1,1,0]
	v_fma_mix_f32 v60, v93, v51, 0 op_sel:[1,1,0] op_sel_hi:[1,1,0]
	v_add_f32_dpp v53, v53, v53 quad_perm:[2,3,0,1] row_mask:0xf bank_mask:0xf bound_ctrl:1
	v_fma_mix_f32 v84, v84, v44, v55 op_sel:[0,0,0] op_sel_hi:[0,1,0]
	v_fma_mix_f32 v85, v85, v44, v58 op_sel:[0,1,0] op_sel_hi:[0,1,0]
	v_add_f32_dpp v53, v53, v53 row_half_mirror row_mask:0xf bank_mask:0xf bound_ctrl:1
	v_fma_mix_f32 v86, v86, v45, v59 op_sel:[0,0,0] op_sel_hi:[0,1,0]
	v_fma_mix_f32 v87, v87, v45, v60 op_sel:[0,1,0] op_sel_hi:[0,1,0]
	v_add_f32_dpp v53, v53, v53 row_mirror row_mask:0xf bank_mask:0xf bound_ctrl:1
	v_fma_mix_f32 v84, -v53, v48, v84 op_sel:[0,0,0] op_sel_hi:[0,1,0]
	v_fma_mix_f32 v85, -v53, v48, v85 op_sel:[0,1,0] op_sel_hi:[0,1,0]
	v_fma_mix_f32 v86, -v53, v49, v86 op_sel:[0,0,0] op_sel_hi:[0,1,0]
	v_fma_mix_f32 v87, -v53, v49, v87 op_sel:[0,1,0] op_sel_hi:[0,1,0]
	v_fma_mix_f32 v41, v84, v42, 0 op_sel:[0,0,0] op_sel_hi:[0,1,0]
	v_add_u32_e32 v173, 10, v193
	v_fma_mix_f32 v41, v85, v42, v41 op_sel:[0,1,0] op_sel_hi:[0,1,0]
	ds_write_b32 v172, v173 offset:49216
	v_fma_mix_f32 v41, v86, v43, v41 op_sel:[0,0,0] op_sel_hi:[0,1,0]
	v_cndmask_b32_e64 v187, v57, v56, s[38:39]
	v_fma_mix_f32 v41, v87, v43, v41 op_sel:[0,1,0] op_sel_hi:[0,1,0]
	v_cndmask_b32_e64 v188, v56, v57, s[38:39]
	v_cndmask_b32_e64 v189, v41, v40, s[38:39]
	v_cndmask_b32_e64 v190, v40, v41, s[38:39]
	s_waitcnt lgkmcnt(1)
	v_fma_mix_f32 v98, v84, v6, 0 op_sel:[0,0,0] op_sel_hi:[0,1,0]
	v_fma_mix_f32 v98, v85, v6, v98 op_sel:[0,1,0] op_sel_hi:[0,1,0]
	v_add_f32_dpp v188, v188, v187 quad_perm:[1,0,3,2] row_mask:0xf bank_mask:0xf bound_ctrl:1
	v_add_f32_dpp v189, v190, v189 quad_perm:[1,0,3,2] row_mask:0xf bank_mask:0xf bound_ctrl:1
	v_fma_mix_f32 v98, v86, v7, v98 op_sel:[0,0,0] op_sel_hi:[0,1,0]
	v_fma_mix_f32 v98, v87, v7, v98 op_sel:[0,1,0] op_sel_hi:[0,1,0]
	v_cndmask_b32_e64 v191, v189, v188, s[40:41]
	v_cndmask_b32_e64 v192, v188, v189, s[40:41]
	v_fma_mix_f32 v100, v88, v14, 0 op_sel:[0,0,0] op_sel_hi:[1,1,0]
	v_fma_mix_f32 v101, v88, v14, 0 op_sel:[0,1,0] op_sel_hi:[1,1,0]
	v_add_f32_dpp v192, v192, v191 quad_perm:[2,3,0,1] row_mask:0xf bank_mask:0xf bound_ctrl:1
	v_add_f32_dpp v98, v98, v98 quad_perm:[1,0,3,2] row_mask:0xf bank_mask:0xf bound_ctrl:1
	v_fma_mix_f32 v102, v88, v15, 0 op_sel:[0,0,0] op_sel_hi:[1,1,0]
	v_add_f32_dpp v192, v192, v192 row_ror:4 row_mask:0xf bank_mask:0xf bound_ctrl:1
	v_fma_mix_f32 v103, v88, v15, 0 op_sel:[0,1,0] op_sel_hi:[1,1,0]
	v_add_f32_dpp v98, v98, v98 quad_perm:[2,3,0,1] row_mask:0xf bank_mask:0xf bound_ctrl:1
	v_add_f32_dpp v192, v192, v192 row_ror:8 row_mask:0xf bank_mask:0xf bound_ctrl:1
	v_cvt_f16_f32_e32 v192, v192
	global_store_short v83, v192, s[36:37]
	s_add_u32 s36, s36, s44
	s_addc_u32 s37, s37, s45
	ds_read_b128 v[56:59], v194 offset:35840
	ds_read_b128 v[72:75], v194 offset:33792
	ds_read_b128 v[64:67], v194 offset:34048
	ds_read_b128 v[76:79], v194 offset:34816
	ds_read_b128 v[68:71], v194 offset:35072
	ds_read_b128 v[40:43], v194 offset:36096
	ds_read_b128 v[52:55], v194 offset:34304
	ds_read_b128 v[44:47], v194 offset:34560
	ds_read_b128 v[60:63], v194 offset:35328
	ds_read_b128 v[48:51], v194 offset:35584
	ds_read_b64 v[92:93], v195 offset:36352
	v_fma_mix_f32 v84, v84, v4, v100 op_sel:[0,0,0] op_sel_hi:[0,1,0]
	v_fma_mix_f32 v85, v85, v4, v101 op_sel:[0,1,0] op_sel_hi:[0,1,0]
	v_add_f32_dpp v98, v98, v98 row_half_mirror row_mask:0xf bank_mask:0xf bound_ctrl:1
	v_fma_mix_f32 v86, v86, v5, v102 op_sel:[0,0,0] op_sel_hi:[0,1,0]
	v_fma_mix_f32 v87, v87, v5, v103 op_sel:[0,1,0] op_sel_hi:[0,1,0]
	v_add_f32_dpp v98, v98, v98 row_mirror row_mask:0xf bank_mask:0xf bound_ctrl:1
	v_fma_mix_f32 v84, -v98, v12, v84 op_sel:[0,0,0] op_sel_hi:[0,1,0]
	v_fma_mix_f32 v85, -v98, v12, v85 op_sel:[0,1,0] op_sel_hi:[0,1,0]
	v_fma_mix_f32 v86, -v98, v13, v86 op_sel:[0,0,0] op_sel_hi:[0,1,0]
	v_fma_mix_f32 v87, -v98, v13, v87 op_sel:[0,1,0] op_sel_hi:[0,1,0]
	v_fma_mix_f32 v99, v84, v10, 0 op_sel:[0,0,0] op_sel_hi:[0,1,0]
	v_fma_mix_f32 v96, v84, v0, 0 op_sel:[0,0,0] op_sel_hi:[0,1,0]
	v_fma_mix_f32 v99, v85, v10, v99 op_sel:[0,1,0] op_sel_hi:[0,1,0]
	v_fma_mix_f32 v96, v85, v0, v96 op_sel:[0,1,0] op_sel_hi:[0,1,0]
	v_fma_mix_f32 v99, v86, v11, v99 op_sel:[0,0,0] op_sel_hi:[0,1,0]
	v_fma_mix_f32 v96, v86, v1, v96 op_sel:[0,0,0] op_sel_hi:[0,1,0]
	v_fma_mix_f32 v99, v87, v11, v99 op_sel:[0,1,0] op_sel_hi:[0,1,0]
	v_fma_mix_f32 v96, v87, v1, v96 op_sel:[0,1,0] op_sel_hi:[0,1,0]
	v_fma_mix_f32 v101, v88, v18, 0 op_sel:[1,0,0] op_sel_hi:[1,1,0]
	v_fma_mix_f32 v102, v88, v18, 0 op_sel:[1,1,0] op_sel_hi:[1,1,0]
	v_add_f32_dpp v99, v99, v99 quad_perm:[1,0,3,2] row_mask:0xf bank_mask:0xf bound_ctrl:1
	v_fma_mix_f32 v103, v88, v19, 0 op_sel:[1,0,0] op_sel_hi:[1,1,0]
	v_fma_mix_f32 v104, v88, v19, 0 op_sel:[1,1,0] op_sel_hi:[1,1,0]
	v_add_f32_dpp v99, v99, v99 quad_perm:[2,3,0,1] row_mask:0xf bank_mask:0xf bound_ctrl:1
	v_fma_mix_f32 v84, v84, v8, v101 op_sel:[0,0,0] op_sel_hi:[0,1,0]
	v_fma_mix_f32 v85, v85, v8, v102 op_sel:[0,1,0] op_sel_hi:[0,1,0]
	v_add_f32_dpp v99, v99, v99 row_half_mirror row_mask:0xf bank_mask:0xf bound_ctrl:1
	v_fma_mix_f32 v86, v86, v9, v103 op_sel:[0,0,0] op_sel_hi:[0,1,0]
	v_fma_mix_f32 v87, v87, v9, v104 op_sel:[0,1,0] op_sel_hi:[0,1,0]
	v_add_f32_dpp v99, v99, v99 row_mirror row_mask:0xf bank_mask:0xf bound_ctrl:1
	v_fma_mix_f32 v84, -v99, v16, v84 op_sel:[0,0,0] op_sel_hi:[0,1,0]
	v_fma_mix_f32 v85, -v99, v16, v85 op_sel:[0,1,0] op_sel_hi:[0,1,0]
	v_fma_mix_f32 v86, -v99, v17, v86 op_sel:[0,0,0] op_sel_hi:[0,1,0]
	v_fma_mix_f32 v87, -v99, v17, v87 op_sel:[0,1,0] op_sel_hi:[0,1,0]
	v_fma_mix_f32 v100, v84, v26, 0 op_sel:[0,0,0] op_sel_hi:[0,1,0]
	v_fma_mix_f32 v97, v84, v2, 0 op_sel:[0,0,0] op_sel_hi:[0,1,0]
	v_fma_mix_f32 v100, v85, v26, v100 op_sel:[0,1,0] op_sel_hi:[0,1,0]
	v_fma_mix_f32 v97, v85, v2, v97 op_sel:[0,1,0] op_sel_hi:[0,1,0]
	v_fma_mix_f32 v100, v86, v27, v100 op_sel:[0,0,0] op_sel_hi:[0,1,0]
	v_fma_mix_f32 v97, v86, v3, v97 op_sel:[0,0,0] op_sel_hi:[0,1,0]
	v_fma_mix_f32 v100, v87, v27, v100 op_sel:[0,1,0] op_sel_hi:[0,1,0]
	v_fma_mix_f32 v97, v87, v3, v97 op_sel:[0,1,0] op_sel_hi:[0,1,0]
	v_fma_mix_f32 v102, v89, v34, 0 op_sel:[0,0,0] op_sel_hi:[1,1,0]
	v_fma_mix_f32 v103, v89, v34, 0 op_sel:[0,1,0] op_sel_hi:[1,1,0]
	v_add_f32_dpp v100, v100, v100 quad_perm:[1,0,3,2] row_mask:0xf bank_mask:0xf bound_ctrl:1
	v_fma_mix_f32 v104, v89, v35, 0 op_sel:[0,0,0] op_sel_hi:[1,1,0]
	v_fma_mix_f32 v105, v89, v35, 0 op_sel:[0,1,0] op_sel_hi:[1,1,0]
	v_add_f32_dpp v100, v100, v100 quad_perm:[2,3,0,1] row_mask:0xf bank_mask:0xf bound_ctrl:1
	v_fma_mix_f32 v84, v84, v24, v102 op_sel:[0,0,0] op_sel_hi:[0,1,0]
	v_fma_mix_f32 v85, v85, v24, v103 op_sel:[0,1,0] op_sel_hi:[0,1,0]
	v_add_f32_dpp v100, v100, v100 row_half_mirror row_mask:0xf bank_mask:0xf bound_ctrl:1
	v_fma_mix_f32 v86, v86, v25, v104 op_sel:[0,0,0] op_sel_hi:[0,1,0]
	v_fma_mix_f32 v87, v87, v25, v105 op_sel:[0,1,0] op_sel_hi:[0,1,0]
	v_add_f32_dpp v100, v100, v100 row_mirror row_mask:0xf bank_mask:0xf bound_ctrl:1
	v_fma_mix_f32 v84, -v100, v32, v84 op_sel:[0,0,0] op_sel_hi:[0,1,0]
	v_fma_mix_f32 v85, -v100, v32, v85 op_sel:[0,1,0] op_sel_hi:[0,1,0]
	v_fma_mix_f32 v86, -v100, v33, v86 op_sel:[0,0,0] op_sel_hi:[0,1,0]
	v_fma_mix_f32 v87, -v100, v33, v87 op_sel:[0,1,0] op_sel_hi:[0,1,0]
	v_fma_mix_f32 v101, v84, v30, 0 op_sel:[0,0,0] op_sel_hi:[0,1,0]
	v_fma_mix_f32 v98, v84, v20, 0 op_sel:[0,0,0] op_sel_hi:[0,1,0]
	v_fma_mix_f32 v101, v85, v30, v101 op_sel:[0,1,0] op_sel_hi:[0,1,0]
	v_fma_mix_f32 v98, v85, v20, v98 op_sel:[0,1,0] op_sel_hi:[0,1,0]
	v_fma_mix_f32 v101, v86, v31, v101 op_sel:[0,0,0] op_sel_hi:[0,1,0]
	v_fma_mix_f32 v98, v86, v21, v98 op_sel:[0,0,0] op_sel_hi:[0,1,0]
	v_fma_mix_f32 v101, v87, v31, v101 op_sel:[0,1,0] op_sel_hi:[0,1,0]
	v_fma_mix_f32 v98, v87, v21, v98 op_sel:[0,1,0] op_sel_hi:[0,1,0]
	v_fma_mix_f32 v103, v89, v38, 0 op_sel:[1,0,0] op_sel_hi:[1,1,0]
	v_fma_mix_f32 v104, v89, v38, 0 op_sel:[1,1,0] op_sel_hi:[1,1,0]
	v_add_f32_dpp v101, v101, v101 quad_perm:[1,0,3,2] row_mask:0xf bank_mask:0xf bound_ctrl:1
	v_fma_mix_f32 v105, v89, v39, 0 op_sel:[1,0,0] op_sel_hi:[1,1,0]
	v_fma_mix_f32 v119, v89, v39, 0 op_sel:[1,1,0] op_sel_hi:[1,1,0]
	v_add_f32_dpp v101, v101, v101 quad_perm:[2,3,0,1] row_mask:0xf bank_mask:0xf bound_ctrl:1
	v_fma_mix_f32 v84, v84, v28, v103 op_sel:[0,0,0] op_sel_hi:[0,1,0]
	v_fma_mix_f32 v85, v85, v28, v104 op_sel:[0,1,0] op_sel_hi:[0,1,0]
	v_add_f32_dpp v101, v101, v101 row_half_mirror row_mask:0xf bank_mask:0xf bound_ctrl:1
	v_fma_mix_f32 v86, v86, v29, v105 op_sel:[0,0,0] op_sel_hi:[0,1,0]
	v_fma_mix_f32 v87, v87, v29, v119 op_sel:[0,1,0] op_sel_hi:[0,1,0]
	v_add_f32_dpp v101, v101, v101 row_mirror row_mask:0xf bank_mask:0xf bound_ctrl:1
	v_fma_mix_f32 v84, -v101, v36, v84 op_sel:[0,0,0] op_sel_hi:[0,1,0]
	v_fma_mix_f32 v85, -v101, v36, v85 op_sel:[0,1,0] op_sel_hi:[0,1,0]
	v_fma_mix_f32 v86, -v101, v37, v86 op_sel:[0,0,0] op_sel_hi:[0,1,0]
	v_fma_mix_f32 v87, -v101, v37, v87 op_sel:[0,1,0] op_sel_hi:[0,1,0]
	v_fma_mix_f32 v99, v84, v22, 0 op_sel:[0,0,0] op_sel_hi:[0,1,0]
	v_cndmask_b32_e64 v187, v97, v96, s[38:39]
	v_fma_mix_f32 v99, v85, v22, v99 op_sel:[0,1,0] op_sel_hi:[0,1,0]
	v_cndmask_b32_e64 v188, v96, v97, s[38:39]
	v_fma_mix_f32 v99, v86, v23, v99 op_sel:[0,0,0] op_sel_hi:[0,1,0]
	v_fma_mix_f32 v99, v87, v23, v99 op_sel:[0,1,0] op_sel_hi:[0,1,0]
	v_cndmask_b32_e64 v189, v99, v98, s[38:39]
	v_cndmask_b32_e64 v190, v98, v99, s[38:39]
	s_waitcnt lgkmcnt(0)
	v_fma_mix_f32 v98, v84, v74, 0 op_sel:[0,0,0] op_sel_hi:[0,1,0]
	v_fma_mix_f32 v98, v85, v74, v98 op_sel:[0,1,0] op_sel_hi:[0,1,0]
	v_add_f32_dpp v188, v188, v187 quad_perm:[1,0,3,2] row_mask:0xf bank_mask:0xf bound_ctrl:1
	v_add_f32_dpp v189, v190, v189 quad_perm:[1,0,3,2] row_mask:0xf bank_mask:0xf bound_ctrl:1
	v_fma_mix_f32 v98, v86, v75, v98 op_sel:[0,0,0] op_sel_hi:[0,1,0]
	v_fma_mix_f32 v98, v87, v75, v98 op_sel:[0,1,0] op_sel_hi:[0,1,0]
	v_cndmask_b32_e64 v191, v189, v188, s[40:41]
	v_cndmask_b32_e64 v192, v188, v189, s[40:41]
	v_fma_mix_f32 v100, v92, v78, 0 op_sel:[0,0,0] op_sel_hi:[1,1,0]
	v_fma_mix_f32 v101, v92, v78, 0 op_sel:[0,1,0] op_sel_hi:[1,1,0]
	v_add_f32_dpp v192, v192, v191 quad_perm:[2,3,0,1] row_mask:0xf bank_mask:0xf bound_ctrl:1
	v_add_f32_dpp v98, v98, v98 quad_perm:[1,0,3,2] row_mask:0xf bank_mask:0xf bound_ctrl:1
	v_fma_mix_f32 v102, v92, v79, 0 op_sel:[0,0,0] op_sel_hi:[1,1,0]
	v_add_f32_dpp v192, v192, v192 row_ror:4 row_mask:0xf bank_mask:0xf bound_ctrl:1
	v_fma_mix_f32 v103, v92, v79, 0 op_sel:[0,1,0] op_sel_hi:[1,1,0]
	v_add_f32_dpp v98, v98, v98 quad_perm:[2,3,0,1] row_mask:0xf bank_mask:0xf bound_ctrl:1
	v_add_f32_dpp v192, v192, v192 row_ror:8 row_mask:0xf bank_mask:0xf bound_ctrl:1
	v_cvt_f16_f32_e32 v192, v192
	global_store_short v83, v192, s[36:37]
	s_add_u32 s36, s36, s44
	s_addc_u32 s37, s37, s45
	s_cmp_gt_i32 s35, 13
	s_cbranch_scc0 .Lc_poll_A5
.Lc_ret_A5:
	ds_read_b128 v[0:3], v194 offset:38912
	ds_read_b128 v[4:7], v194 offset:36864
	ds_read_b128 v[8:11], v194 offset:37120
	ds_read_b128 v[12:15], v194 offset:37888
	ds_read_b128 v[16:19], v194 offset:38144
	ds_read_b128 v[20:23], v194 offset:39168
	ds_read_b128 v[24:27], v194 offset:37376
	ds_read_b128 v[28:31], v194 offset:37632
	ds_read_b128 v[32:35], v194 offset:38400
	ds_read_b128 v[36:39], v194 offset:38656
	ds_read_b64 v[88:89], v195 offset:39424
	v_fma_mix_f32 v84, v84, v72, v100 op_sel:[0,0,0] op_sel_hi:[0,1,0]
	v_fma_mix_f32 v85, v85, v72, v101 op_sel:[0,1,0] op_sel_hi:[0,1,0]
	v_add_f32_dpp v98, v98, v98 row_half_mirror row_mask:0xf bank_mask:0xf bound_ctrl:1
	v_fma_mix_f32 v86, v86, v73, v102 op_sel:[0,0,0] op_sel_hi:[0,1,0]
	v_fma_mix_f32 v87, v87, v73, v103 op_sel:[0,1,0] op_sel_hi:[0,1,0]
	v_add_f32_dpp v98, v98, v98 row_mirror row_mask:0xf bank_mask:0xf bound_ctrl:1
	v_fma_mix_f32 v84, -v98, v76, v84 op_sel:[0,0,0] op_sel_hi:[0,1,0]
	v_fma_mix_f32 v85, -v98, v76, v85 op_sel:[0,1,0] op_sel_hi:[0,1,0]
	v_fma_mix_f32 v86, -v98, v77, v86 op_sel:[0,0,0] op_sel_hi:[0,1,0]
	v_fma_mix_f32 v87, -v98, v77, v87 op_sel:[0,1,0] op_sel_hi:[0,1,0]
	v_fma_mix_f32 v73, v84, v66, 0 op_sel:[0,0,0] op_sel_hi:[0,1,0]
	v_fma_mix_f32 v97, v84, v56, 0 op_sel:[0,0,0] op_sel_hi:[0,1,0]
	v_fma_mix_f32 v73, v85, v66, v73 op_sel:[0,1,0] op_sel_hi:[0,1,0]
	v_fma_mix_f32 v56, v85, v56, v97 op_sel:[0,1,0] op_sel_hi:[0,1,0]
	v_fma_mix_f32 v73, v86, v67, v73 op_sel:[0,0,0] op_sel_hi:[0,1,0]
	v_fma_mix_f32 v56, v86, v57, v56 op_sel:[0,0,0] op_sel_hi:[0,1,0]
	v_fma_mix_f32 v73, v87, v67, v73 op_sel:[0,1,0] op_sel_hi:[0,1,0]
	v_fma_mix_f32 v56, v87, v57, v56 op_sel:[0,1,0] op_sel_hi:[0,1,0]
	v_fma_mix_f32 v75, v92, v70, 0 op_sel:[1,0,0] op_sel_hi:[1,1,0]
	v_fma_mix_f32 v76, v92, v70, 0 op_sel:[1,1,0] op_sel_hi:[1,1,0]
	v_add_f32_dpp v73, v73, v73 quad_perm:[1,0,3,2] row_mask:0xf bank_mask:0xf bound_ctrl:1
	v_fma_mix_f32 v77, v92, v71, 0 op_sel:[1,0,0] op_sel_hi:[1,1,0]
	v_fma_mix_f32 v78, v92, v71, 0 op_sel:[1,1,0] op_sel_hi:[1,1,0]
	v_add_f32_dpp v73, v73, v73 quad_perm:[2,3,0,1] row_mask:0xf bank_mask:0xf bound_ctrl:1
	v_fma_mix_f32 v84, v84, v64, v75 op_sel:[0,0,0] op_sel_hi:[0,1,0]
	v_fma_mix_f32 v85, v85, v64, v76 op_sel:[0,1,0] op_sel_hi:[0,1,0]
	v_add_f32_dpp v73, v73, v73 row_half_mirror row_mask:0xf bank_mask:0xf bound_ctrl:1
	v_fma_mix_f32 v86, v86, v65, v77 op_sel:[0,0,0] op_sel_hi:[0,1,0]
	v_fma_mix_f32 v87, v87, v65, v78 op_sel:[0,1,0] op_sel_hi:[0,1,0]
	v_add_f32_dpp v73, v73, v73 row_mirror row_mask:0xf bank_mask:0xf bound_ctrl:1
	v_fma_mix_f32 v84, -v73, v68, v84 op_sel:[0,0,0] op_sel_hi:[0,1,0]
	v_fma_mix_f32 v85, -v73, v68, v85 op_sel:[0,1,0] op_sel_hi:[0,1,0]
	v_fma_mix_f32 v86, -v73, v69, v86 op_sel:[0,0,0] op_sel_hi:[0,1,0]
	v_fma_mix_f32 v87, -v73, v69, v87 op_sel:[0,1,0] op_sel_hi:[0,1,0]
	v_fma_mix_f32 v64, v84, v54, 0 op_sel:[0,0,0] op_sel_hi:[0,1,0]
	v_fma_mix_f32 v57, v84, v58, 0 op_sel:[0,0,0] op_sel_hi:[0,1,0]
	v_fma_mix_f32 v64, v85, v54, v64 op_sel:[0,1,0] op_sel_hi:[0,1,0]
	v_fma_mix_f32 v57, v85, v58, v57 op_sel:[0,1,0] op_sel_hi:[0,1,0]
	v_fma_mix_f32 v64, v86, v55, v64 op_sel:[0,0,0] op_sel_hi:[0,1,0]
	v_fma_mix_f32 v57, v86, v59, v57 op_sel:[0,0,0] op_sel_hi:[0,1,0]
	v_fma_mix_f32 v64, v87, v55, v64 op_sel:[0,1,0] op_sel_hi:[0,1,0]
	v_fma_mix_f32 v57, v87, v59, v57 op_sel:[0,1,0] op_sel_hi:[0,1,0]
	v_fma_mix_f32 v66, v93, v62, 0 op_sel:[0,0,0] op_sel_hi:[1,1,0]
	v_fma_mix_f32 v67, v93, v62, 0 op_sel:[0,1,0] op_sel_hi:[1,1,0]
	v_add_f32_dpp v64, v64, v64 quad_perm:[1,0,3,2] row_mask:0xf bank_mask:0xf bound_ctrl:1
	v_fma_mix_f32 v68, v93, v63, 0 op_sel:[0,0,0] op_sel_hi:[1,1,0]
	v_fma_mix_f32 v69, v93, v63, 0 op_sel:[0,1,0] op_sel_hi:[1,1,0]
	v_add_f32_dpp v64, v64, v64 quad_perm:[2,3,0,1] row_mask:0xf bank_mask:0xf bound_ctrl:1
	v_fma_mix_f32 v84, v84, v52, v66 op_sel:[0,0,0] op_sel_hi:[0,1,0]
	v_fma_mix_f32 v85, v85, v52, v67 op_sel:[0,1,0] op_sel_hi:[0,1,0]
	v_add_f32_dpp v64, v64, v64 row_half_mirror row_mask:0xf bank_mask:0xf bound_ctrl:1
	v_fma_mix_f32 v86, v86, v53, v68 op_sel:[0,0,0] op_sel_hi:[0,1,0]
	v_fma_mix_f32 v87, v87, v53, v69 op_sel:[0,1,0] op_sel_hi:[0,1,0]
	v_add_f32_dpp v64, v64, v64 row_mirror row_mask:0xf bank_mask:0xf bound_ctrl:1
	v_fma_mix_f32 v84, -v64, v60, v84 op_sel:[0,0,0] op_sel_hi:[0,1,0]
	v_fma_mix_f32 v85, -v64, v60, v85 op_sel:[0,1,0] op_sel_hi:[0,1,0]
	v_fma_mix_f32 v86, -v64, v61, v86 op_sel:[0,0,0] op_sel_hi:[0,1,0]
	v_fma_mix_f32 v87, -v64, v61, v87 op_sel:[0,1,0] op_sel_hi:[0,1,0]
	v_fma_mix_f32 v53, v84, v46, 0 op_sel:[0,0,0] op_sel_hi:[0,1,0]
	v_fma_mix_f32 v59, v84, v40, 0 op_sel:[0,0,0] op_sel_hi:[0,1,0]
	v_fma_mix_f32 v53, v85, v46, v53 op_sel:[0,1,0] op_sel_hi:[0,1,0]
	v_fma_mix_f32 v40, v85, v40, v59 op_sel:[0,1,0] op_sel_hi:[0,1,0]
	v_fma_mix_f32 v53, v86, v47, v53 op_sel:[0,0,0] op_sel_hi:[0,1,0]
	v_fma_mix_f32 v40, v86, v41, v40 op_sel:[0,0,0] op_sel_hi:[0,1,0]
	v_fma_mix_f32 v53, v87, v47, v53 op_sel:[0,1,0] op_sel_hi:[0,1,0]
	v_fma_mix_f32 v40, v87, v41, v40 op_sel:[0,1,0] op_sel_hi:[0,1,0]
	v_fma_mix_f32 v55, v93, v50, 0 op_sel:[1,0,0] op_sel_hi:[1,1,0]
	v_fma_mix_f32 v58, v93, v50, 0 op_sel:[1,1,0] op_sel_hi:[1,1,0]
	v_add_f32_dpp v53, v53, v53 quad_perm:[1,0,3,2] row_mask:0xf bank_mask:0xf bound_ctrl:1
	v_fma_mix_f32 v59, v93, v51, 0 op_sel:[1,0,0] op_sel_hi:[1,1,0]
	v_fma_mix_f32 v60, v93, v51, 0 op_sel:[1,1,0] op_sel_hi:[1,1,0]
	v_add_f32_dpp v53, v53, v53 quad_perm:[2,3,0,1] row_mask:0xf bank_mask:0xf bound_ctrl:1
	v_fma_mix_f32 v84, v84, v44, v55 op_sel:[0,0,0] op_sel_hi:[0,1,0]
	v_fma_mix_f32 v85, v85, v44, v58 op_sel:[0,1,0] op_sel_hi:[0,1,0]
	v_add_f32_dpp v53, v53, v53 row_half_mirror row_mask:0xf bank_mask:0xf bound_ctrl:1
	v_fma_mix_f32 v86, v86, v45, v59 op_sel:[0,0,0] op_sel_hi:[0,1,0]
	v_fma_mix_f32 v87, v87, v45, v60 op_sel:[0,1,0] op_sel_hi:[0,1,0]
	v_add_f32_dpp v53, v53, v53 row_mirror row_mask:0xf bank_mask:0xf bound_ctrl:1
	v_fma_mix_f32 v84, -v53, v48, v84 op_sel:[0,0,0] op_sel_hi:[0,1,0]
	v_fma_mix_f32 v85, -v53, v48, v85 op_sel:[0,1,0] op_sel_hi:[0,1,0]
	v_fma_mix_f32 v86, -v53, v49, v86 op_sel:[0,0,0] op_sel_hi:[0,1,0]
	v_fma_mix_f32 v87, -v53, v49, v87 op_sel:[0,1,0] op_sel_hi:[0,1,0]
	v_fma_mix_f32 v41, v84, v42, 0 op_sel:[0,0,0] op_sel_hi:[0,1,0]
	v_add_u32_e32 v173, 12, v193
	v_fma_mix_f32 v41, v85, v42, v41 op_sel:[0,1,0] op_sel_hi:[0,1,0]
	ds_write_b32 v172, v173 offset:49216
	v_fma_mix_f32 v41, v86, v43, v41 op_sel:[0,0,0] op_sel_hi:[0,1,0]
	v_cndmask_b32_e64 v187, v57, v56, s[38:39]
	v_fma_mix_f32 v41, v87, v43, v41 op_sel:[0,1,0] op_sel_hi:[0,1,0]
	v_cndmask_b32_e64 v188, v56, v57, s[38:39]
	v_cndmask_b32_e64 v189, v41, v40, s[38:39]
	v_cndmask_b32_e64 v190, v40, v41, s[38:39]
	s_waitcnt lgkmcnt(1)
	v_fma_mix_f32 v98, v84, v6, 0 op_sel:[0,0,0] op_sel_hi:[0,1,0]
	v_fma_mix_f32 v98, v85, v6, v98 op_sel:[0,1,0] op_sel_hi:[0,1,0]
	v_add_f32_dpp v188, v188, v187 quad_perm:[1,0,3,2] row_mask:0xf bank_mask:0xf bound_ctrl:1
	v_add_f32_dpp v189, v190, v189 quad_perm:[1,0,3,2] row_mask:0xf bank_mask:0xf bound_ctrl:1
	v_fma_mix_f32 v98, v86, v7, v98 op_sel:[0,0,0] op_sel_hi:[0,1,0]
	v_fma_mix_f32 v98, v87, v7, v98 op_sel:[0,1,0] op_sel_hi:[0,1,0]
	v_cndmask_b32_e64 v191, v189, v188, s[40:41]
	v_cndmask_b32_e64 v192, v188, v189, s[40:41]
	v_fma_mix_f32 v100, v88, v14, 0 op_sel:[0,0,0] op_sel_hi:[1,1,0]
	v_fma_mix_f32 v101, v88, v14, 0 op_sel:[0,1,0] op_sel_hi:[1,1,0]
	v_add_f32_dpp v192, v192, v191 quad_perm:[2,3,0,1] row_mask:0xf bank_mask:0xf bound_ctrl:1
	v_add_f32_dpp v98, v98, v98 quad_perm:[1,0,3,2] row_mask:0xf bank_mask:0xf bound_ctrl:1
	v_fma_mix_f32 v102, v88, v15, 0 op_sel:[0,0,0] op_sel_hi:[1,1,0]
	v_add_f32_dpp v192, v192, v192 row_ror:4 row_mask:0xf bank_mask:0xf bound_ctrl:1
	v_fma_mix_f32 v103, v88, v15, 0 op_sel:[0,1,0] op_sel_hi:[1,1,0]
	v_add_f32_dpp v98, v98, v98 quad_perm:[2,3,0,1] row_mask:0xf bank_mask:0xf bound_ctrl:1
	v_add_f32_dpp v192, v192, v192 row_ror:8 row_mask:0xf bank_mask:0xf bound_ctrl:1
	v_cvt_f16_f32_e32 v192, v192
	global_store_short v83, v192, s[36:37]
	s_add_u32 s36, s36, s44
	s_addc_u32 s37, s37, s45
	ds_read_b128 v[56:59], v194 offset:41984
	ds_read_b128 v[72:75], v194 offset:39936
	ds_read_b128 v[64:67], v194 offset:40192
	ds_read_b128 v[76:79], v194 offset:40960
	ds_read_b128 v[68:71], v194 offset:41216
	ds_read_b128 v[40:43], v194 offset:42240
	ds_read_b128 v[52:55], v194 offset:40448
	ds_read_b128 v[44:47], v194 offset:40704
	ds_read_b128 v[60:63], v194 offset:41472
	ds_read_b128 v[48:51], v194 offset:41728
	ds_read_b64 v[92:93], v195 offset:42496
	v_fma_mix_f32 v84, v84, v4, v100 op_sel:[0,0,0] op_sel_hi:[0,1,0]
	v_fma_mix_f32 v85, v85, v4, v101 op_sel:[0,1,0] op_sel_hi:[0,1,0]
	v_add_f32_dpp v98, v98, v98 row_half_mirror row_mask:0xf bank_mask:0xf bound_ctrl:1
	v_fma_mix_f32 v86, v86, v5, v102 op_sel:[0,0,0] op_sel_hi:[0,1,0]
	v_fma_mix_f32 v87, v87, v5, v103 op_sel:[0,1,0] op_sel_hi:[0,1,0]
	v_add_f32_dpp v98, v98, v98 row_mirror row_mask:0xf bank_mask:0xf bound_ctrl:1
	v_fma_mix_f32 v84, -v98, v12, v84 op_sel:[0,0,0] op_sel_hi:[0,1,0]
	v_fma_mix_f32 v85, -v98, v12, v85 op_sel:[0,1,0] op_sel_hi:[0,1,0]
	v_fma_mix_f32 v86, -v98, v13, v86 op_sel:[0,0,0] op_sel_hi:[0,1,0]
	v_fma_mix_f32 v87, -v98, v13, v87 op_sel:[0,1,0] op_sel_hi:[0,1,0]
	v_fma_mix_f32 v99, v84, v10, 0 op_sel:[0,0,0] op_sel_hi:[0,1,0]
	v_fma_mix_f32 v96, v84, v0, 0 op_sel:[0,0,0] op_sel_hi:[0,1,0]
	v_fma_mix_f32 v99, v85, v10, v99 op_sel:[0,1,0] op_sel_hi:[0,1,0]
	v_fma_mix_f32 v96, v85, v0, v96 op_sel:[0,1,0] op_sel_hi:[0,1,0]
	v_fma_mix_f32 v99, v86, v11, v99 op_sel:[0,0,0] op_sel_hi:[0,1,0]
	v_fma_mix_f32 v96, v86, v1, v96 op_sel:[0,0,0] op_sel_hi:[0,1,0]
	v_fma_mix_f32 v99, v87, v11, v99 op_sel:[0,1,0] op_sel_hi:[0,1,0]
	v_fma_mix_f32 v96, v87, v1, v96 op_sel:[0,1,0] op_sel_hi:[0,1,0]
	v_fma_mix_f32 v101, v88, v18, 0 op_sel:[1,0,0] op_sel_hi:[1,1,0]
	v_fma_mix_f32 v102, v88, v18, 0 op_sel:[1,1,0] op_sel_hi:[1,1,0]
	v_add_f32_dpp v99, v99, v99 quad_perm:[1,0,3,2] row_mask:0xf bank_mask:0xf bound_ctrl:1
	v_fma_mix_f32 v103, v88, v19, 0 op_sel:[1,0,0] op_sel_hi:[1,1,0]
	v_fma_mix_f32 v104, v88, v19, 0 op_sel:[1,1,0] op_sel_hi:[1,1,0]
	v_add_f32_dpp v99, v99, v99 quad_perm:[2,3,0,1] row_mask:0xf bank_mask:0xf bound_ctrl:1
	v_fma_mix_f32 v84, v84, v8, v101 op_sel:[0,0,0] op_sel_hi:[0,1,0]
	v_fma_mix_f32 v85, v85, v8, v102 op_sel:[0,1,0] op_sel_hi:[0,1,0]
	v_add_f32_dpp v99, v99, v99 row_half_mirror row_mask:0xf bank_mask:0xf bound_ctrl:1
	v_fma_mix_f32 v86, v86, v9, v103 op_sel:[0,0,0] op_sel_hi:[0,1,0]
	v_fma_mix_f32 v87, v87, v9, v104 op_sel:[0,1,0] op_sel_hi:[0,1,0]
	v_add_f32_dpp v99, v99, v99 row_mirror row_mask:0xf bank_mask:0xf bound_ctrl:1
	v_fma_mix_f32 v84, -v99, v16, v84 op_sel:[0,0,0] op_sel_hi:[0,1,0]
	v_fma_mix_f32 v85, -v99, v16, v85 op_sel:[0,1,0] op_sel_hi:[0,1,0]
	v_fma_mix_f32 v86, -v99, v17, v86 op_sel:[0,0,0] op_sel_hi:[0,1,0]
	v_fma_mix_f32 v87, -v99, v17, v87 op_sel:[0,1,0] op_sel_hi:[0,1,0]
	v_fma_mix_f32 v100, v84, v26, 0 op_sel:[0,0,0] op_sel_hi:[0,1,0]
	v_fma_mix_f32 v97, v84, v2, 0 op_sel:[0,0,0] op_sel_hi:[0,1,0]
	v_fma_mix_f32 v100, v85, v26, v100 op_sel:[0,1,0] op_sel_hi:[0,1,0]
	v_fma_mix_f32 v97, v85, v2, v97 op_sel:[0,1,0] op_sel_hi:[0,1,0]
	v_fma_mix_f32 v100, v86, v27, v100 op_sel:[0,0,0] op_sel_hi:[0,1,0]
	v_fma_mix_f32 v97, v86, v3, v97 op_sel:[0,0,0] op_sel_hi:[0,1,0]
	v_fma_mix_f32 v100, v87, v27, v100 op_sel:[0,1,0] op_sel_hi:[0,1,0]
	v_fma_mix_f32 v97, v87, v3, v97 op_sel:[0,1,0] op_sel_hi:[0,1,0]
	v_fma_mix_f32 v102, v89, v34, 0 op_sel:[0,0,0] op_sel_hi:[1,1,0]
	v_fma_mix_f32 v103, v89, v34, 0 op_sel:[0,1,0] op_sel_hi:[1,1,0]
	v_add_f32_dpp v100, v100, v100 quad_perm:[1,0,3,2] row_mask:0xf bank_mask:0xf bound_ctrl:1
	v_fma_mix_f32 v104, v89, v35, 0 op_sel:[0,0,0] op_sel_hi:[1,1,0]
	v_fma_mix_f32 v105, v89, v35, 0 op_sel:[0,1,0] op_sel_hi:[1,1,0]
	v_add_f32_dpp v100, v100, v100 quad_perm:[2,3,0,1] row_mask:0xf bank_mask:0xf bound_ctrl:1
	v_fma_mix_f32 v84, v84, v24, v102 op_sel:[0,0,0] op_sel_hi:[0,1,0]
	v_fma_mix_f32 v85, v85, v24, v103 op_sel:[0,1,0] op_sel_hi:[0,1,0]
	v_add_f32_dpp v100, v100, v100 row_half_mirror row_mask:0xf bank_mask:0xf bound_ctrl:1
	v_fma_mix_f32 v86, v86, v25, v104 op_sel:[0,0,0] op_sel_hi:[0,1,0]
	v_fma_mix_f32 v87, v87, v25, v105 op_sel:[0,1,0] op_sel_hi:[0,1,0]
	v_add_f32_dpp v100, v100, v100 row_mirror row_mask:0xf bank_mask:0xf bound_ctrl:1
	v_fma_mix_f32 v84, -v100, v32, v84 op_sel:[0,0,0] op_sel_hi:[0,1,0]
	v_fma_mix_f32 v85, -v100, v32, v85 op_sel:[0,1,0] op_sel_hi:[0,1,0]
	v_fma_mix_f32 v86, -v100, v33, v86 op_sel:[0,0,0] op_sel_hi:[0,1,0]
	v_fma_mix_f32 v87, -v100, v33, v87 op_sel:[0,1,0] op_sel_hi:[0,1,0]
	v_fma_mix_f32 v101, v84, v30, 0 op_sel:[0,0,0] op_sel_hi:[0,1,0]
	v_fma_mix_f32 v98, v84, v20, 0 op_sel:[0,0,0] op_sel_hi:[0,1,0]
	v_fma_mix_f32 v101, v85, v30, v101 op_sel:[0,1,0] op_sel_hi:[0,1,0]
	v_fma_mix_f32 v98, v85, v20, v98 op_sel:[0,1,0] op_sel_hi:[0,1,0]
	v_fma_mix_f32 v101, v86, v31, v101 op_sel:[0,0,0] op_sel_hi:[0,1,0]
	v_fma_mix_f32 v98, v86, v21, v98 op_sel:[0,0,0] op_sel_hi:[0,1,0]
	v_fma_mix_f32 v101, v87, v31, v101 op_sel:[0,1,0] op_sel_hi:[0,1,0]
	v_fma_mix_f32 v98, v87, v21, v98 op_sel:[0,1,0] op_sel_hi:[0,1,0]
	v_fma_mix_f32 v103, v89, v38, 0 op_sel:[1,0,0] op_sel_hi:[1,1,0]
	v_fma_mix_f32 v104, v89, v38, 0 op_sel:[1,1,0] op_sel_hi:[1,1,0]
	v_add_f32_dpp v101, v101, v101 quad_perm:[1,0,3,2] row_mask:0xf bank_mask:0xf bound_ctrl:1
	v_fma_mix_f32 v105, v89, v39, 0 op_sel:[1,0,0] op_sel_hi:[1,1,0]
	v_fma_mix_f32 v119, v89, v39, 0 op_sel:[1,1,0] op_sel_hi:[1,1,0]
	v_add_f32_dpp v101, v101, v101 quad_perm:[2,3,0,1] row_mask:0xf bank_mask:0xf bound_ctrl:1
	v_fma_mix_f32 v84, v84, v28, v103 op_sel:[0,0,0] op_sel_hi:[0,1,0]
	v_fma_mix_f32 v85, v85, v28, v104 op_sel:[0,1,0] op_sel_hi:[0,1,0]
	v_add_f32_dpp v101, v101, v101 row_half_mirror row_mask:0xf bank_mask:0xf bound_ctrl:1
	v_fma_mix_f32 v86, v86, v29, v105 op_sel:[0,0,0] op_sel_hi:[0,1,0]
	v_fma_mix_f32 v87, v87, v29, v119 op_sel:[0,1,0] op_sel_hi:[0,1,0]
	v_add_f32_dpp v101, v101, v101 row_mirror row_mask:0xf bank_mask:0xf bound_ctrl:1
	v_fma_mix_f32 v84, -v101, v36, v84 op_sel:[0,0,0] op_sel_hi:[0,1,0]
	v_fma_mix_f32 v85, -v101, v36, v85 op_sel:[0,1,0] op_sel_hi:[0,1,0]
	v_fma_mix_f32 v86, -v101, v37, v86 op_sel:[0,0,0] op_sel_hi:[0,1,0]
	v_fma_mix_f32 v87, -v101, v37, v87 op_sel:[0,1,0] op_sel_hi:[0,1,0]
	v_fma_mix_f32 v99, v84, v22, 0 op_sel:[0,0,0] op_sel_hi:[0,1,0]
	v_cndmask_b32_e64 v187, v97, v96, s[38:39]
	v_fma_mix_f32 v99, v85, v22, v99 op_sel:[0,1,0] op_sel_hi:[0,1,0]
	v_cndmask_b32_e64 v188, v96, v97, s[38:39]
	v_fma_mix_f32 v99, v86, v23, v99 op_sel:[0,0,0] op_sel_hi:[0,1,0]
	v_fma_mix_f32 v99, v87, v23, v99 op_sel:[0,1,0] op_sel_hi:[0,1,0]
	v_cndmask_b32_e64 v189, v99, v98, s[38:39]
	v_cndmask_b32_e64 v190, v98, v99, s[38:39]
	s_waitcnt lgkmcnt(0)
	v_fma_mix_f32 v98, v84, v74, 0 op_sel:[0,0,0] op_sel_hi:[0,1,0]
	v_fma_mix_f32 v98, v85, v74, v98 op_sel:[0,1,0] op_sel_hi:[0,1,0]
	v_add_f32_dpp v188, v188, v187 quad_perm:[1,0,3,2] row_mask:0xf bank_mask:0xf bound_ctrl:1
	v_add_f32_dpp v189, v190, v189 quad_perm:[1,0,3,2] row_mask:0xf bank_mask:0xf bound_ctrl:1
	v_fma_mix_f32 v98, v86, v75, v98 op_sel:[0,0,0] op_sel_hi:[0,1,0]
	v_fma_mix_f32 v98, v87, v75, v98 op_sel:[0,1,0] op_sel_hi:[0,1,0]
	v_cndmask_b32_e64 v191, v189, v188, s[40:41]
	v_cndmask_b32_e64 v192, v188, v189, s[40:41]
	v_fma_mix_f32 v100, v92, v78, 0 op_sel:[0,0,0] op_sel_hi:[1,1,0]
	v_fma_mix_f32 v101, v92, v78, 0 op_sel:[0,1,0] op_sel_hi:[1,1,0]
	v_add_f32_dpp v192, v192, v191 quad_perm:[2,3,0,1] row_mask:0xf bank_mask:0xf bound_ctrl:1
	v_add_f32_dpp v98, v98, v98 quad_perm:[1,0,3,2] row_mask:0xf bank_mask:0xf bound_ctrl:1
	v_fma_mix_f32 v102, v92, v79, 0 op_sel:[0,0,0] op_sel_hi:[1,1,0]
	v_add_f32_dpp v192, v192, v192 row_ror:4 row_mask:0xf bank_mask:0xf bound_ctrl:1
	v_fma_mix_f32 v103, v92, v79, 0 op_sel:[0,1,0] op_sel_hi:[1,1,0]
	v_add_f32_dpp v98, v98, v98 quad_perm:[2,3,0,1] row_mask:0xf bank_mask:0xf bound_ctrl:1
	v_add_f32_dpp v192, v192, v192 row_ror:8 row_mask:0xf bank_mask:0xf bound_ctrl:1
	v_cvt_f16_f32_e32 v192, v192
	global_store_short v83, v192, s[36:37]
	s_add_u32 s36, s36, s44
	s_addc_u32 s37, s37, s45
	s_cmp_gt_i32 s35, 15
	s_cbranch_scc0 .Lc_poll_A6
.Lc_ret_A6:
	ds_read_b128 v[0:3], v194 offset:45056
	ds_read_b128 v[4:7], v194 offset:43008
	ds_read_b128 v[8:11], v194 offset:43264
	ds_read_b128 v[12:15], v194 offset:44032
	ds_read_b128 v[16:19], v194 offset:44288
	ds_read_b128 v[20:23], v194 offset:45312
	ds_read_b128 v[24:27], v194 offset:43520
	ds_read_b128 v[28:31], v194 offset:43776
	ds_read_b128 v[32:35], v194 offset:44544
	ds_read_b128 v[36:39], v194 offset:44800
	ds_read_b64 v[88:89], v195 offset:45568
	v_fma_mix_f32 v84, v84, v72, v100 op_sel:[0,0,0] op_sel_hi:[0,1,0]
	v_fma_mix_f32 v85, v85, v72, v101 op_sel:[0,1,0] op_sel_hi:[0,1,0]
	v_add_f32_dpp v98, v98, v98 row_half_mirror row_mask:0xf bank_mask:0xf bound_ctrl:1
	v_fma_mix_f32 v86, v86, v73, v102 op_sel:[0,0,0] op_sel_hi:[0,1,0]
	v_fma_mix_f32 v87, v87, v73, v103 op_sel:[0,1,0] op_sel_hi:[0,1,0]
	v_add_f32_dpp v98, v98, v98 row_mirror row_mask:0xf bank_mask:0xf bound_ctrl:1
	v_fma_mix_f32 v84, -v98, v76, v84 op_sel:[0,0,0] op_sel_hi:[0,1,0]
	v_fma_mix_f32 v85, -v98, v76, v85 op_sel:[0,1,0] op_sel_hi:[0,1,0]
	v_fma_mix_f32 v86, -v98, v77, v86 op_sel:[0,0,0] op_sel_hi:[0,1,0]
	v_fma_mix_f32 v87, -v98, v77, v87 op_sel:[0,1,0] op_sel_hi:[0,1,0]
	v_fma_mix_f32 v73, v84, v66, 0 op_sel:[0,0,0] op_sel_hi:[0,1,0]
	v_fma_mix_f32 v97, v84, v56, 0 op_sel:[0,0,0] op_sel_hi:[0,1,0]
	v_fma_mix_f32 v73, v85, v66, v73 op_sel:[0,1,0] op_sel_hi:[0,1,0]
	v_fma_mix_f32 v56, v85, v56, v97 op_sel:[0,1,0] op_sel_hi:[0,1,0]
	v_fma_mix_f32 v73, v86, v67, v73 op_sel:[0,0,0] op_sel_hi:[0,1,0]
	v_fma_mix_f32 v56, v86, v57, v56 op_sel:[0,0,0] op_sel_hi:[0,1,0]
	v_fma_mix_f32 v73, v87, v67, v73 op_sel:[0,1,0] op_sel_hi:[0,1,0]
	v_fma_mix_f32 v56, v87, v57, v56 op_sel:[0,1,0] op_sel_hi:[0,1,0]
	v_fma_mix_f32 v75, v92, v70, 0 op_sel:[1,0,0] op_sel_hi:[1,1,0]
	v_fma_mix_f32 v76, v92, v70, 0 op_sel:[1,1,0] op_sel_hi:[1,1,0]
	v_add_f32_dpp v73, v73, v73 quad_perm:[1,0,3,2] row_mask:0xf bank_mask:0xf bound_ctrl:1
	v_fma_mix_f32 v77, v92, v71, 0 op_sel:[1,0,0] op_sel_hi:[1,1,0]
	v_fma_mix_f32 v78, v92, v71, 0 op_sel:[1,1,0] op_sel_hi:[1,1,0]
	v_add_f32_dpp v73, v73, v73 quad_perm:[2,3,0,1] row_mask:0xf bank_mask:0xf bound_ctrl:1
	v_fma_mix_f32 v84, v84, v64, v75 op_sel:[0,0,0] op_sel_hi:[0,1,0]
	v_fma_mix_f32 v85, v85, v64, v76 op_sel:[0,1,0] op_sel_hi:[0,1,0]
	v_add_f32_dpp v73, v73, v73 row_half_mirror row_mask:0xf bank_mask:0xf bound_ctrl:1
	v_fma_mix_f32 v86, v86, v65, v77 op_sel:[0,0,0] op_sel_hi:[0,1,0]
	v_fma_mix_f32 v87, v87, v65, v78 op_sel:[0,1,0] op_sel_hi:[0,1,0]
	v_add_f32_dpp v73, v73, v73 row_mirror row_mask:0xf bank_mask:0xf bound_ctrl:1
	v_fma_mix_f32 v84, -v73, v68, v84 op_sel:[0,0,0] op_sel_hi:[0,1,0]
	v_fma_mix_f32 v85, -v73, v68, v85 op_sel:[0,1,0] op_sel_hi:[0,1,0]
	v_fma_mix_f32 v86, -v73, v69, v86 op_sel:[0,0,0] op_sel_hi:[0,1,0]
	v_fma_mix_f32 v87, -v73, v69, v87 op_sel:[0,1,0] op_sel_hi:[0,1,0]
	v_fma_mix_f32 v64, v84, v54, 0 op_sel:[0,0,0] op_sel_hi:[0,1,0]
	v_fma_mix_f32 v57, v84, v58, 0 op_sel:[0,0,0] op_sel_hi:[0,1,0]
	v_fma_mix_f32 v64, v85, v54, v64 op_sel:[0,1,0] op_sel_hi:[0,1,0]
	v_fma_mix_f32 v57, v85, v58, v57 op_sel:[0,1,0] op_sel_hi:[0,1,0]
	v_fma_mix_f32 v64, v86, v55, v64 op_sel:[0,0,0] op_sel_hi:[0,1,0]
	v_fma_mix_f32 v57, v86, v59, v57 op_sel:[0,0,0] op_sel_hi:[0,1,0]
	v_fma_mix_f32 v64, v87, v55, v64 op_sel:[0,1,0] op_sel_hi:[0,1,0]
	v_fma_mix_f32 v57, v87, v59, v57 op_sel:[0,1,0] op_sel_hi:[0,1,0]
	v_fma_mix_f32 v66, v93, v62, 0 op_sel:[0,0,0] op_sel_hi:[1,1,0]
	v_fma_mix_f32 v67, v93, v62, 0 op_sel:[0,1,0] op_sel_hi:[1,1,0]
	v_add_f32_dpp v64, v64, v64 quad_perm:[1,0,3,2] row_mask:0xf bank_mask:0xf bound_ctrl:1
	v_fma_mix_f32 v68, v93, v63, 0 op_sel:[0,0,0] op_sel_hi:[1,1,0]
	v_fma_mix_f32 v69, v93, v63, 0 op_sel:[0,1,0] op_sel_hi:[1,1,0]
	v_add_f32_dpp v64, v64, v64 quad_perm:[2,3,0,1] row_mask:0xf bank_mask:0xf bound_ctrl:1
	v_fma_mix_f32 v84, v84, v52, v66 op_sel:[0,0,0] op_sel_hi:[0,1,0]
	v_fma_mix_f32 v85, v85, v52, v67 op_sel:[0,1,0] op_sel_hi:[0,1,0]
	v_add_f32_dpp v64, v64, v64 row_half_mirror row_mask:0xf bank_mask:0xf bound_ctrl:1
	v_fma_mix_f32 v86, v86, v53, v68 op_sel:[0,0,0] op_sel_hi:[0,1,0]
	v_fma_mix_f32 v87, v87, v53, v69 op_sel:[0,1,0] op_sel_hi:[0,1,0]
	v_add_f32_dpp v64, v64, v64 row_mirror row_mask:0xf bank_mask:0xf bound_ctrl:1
	v_fma_mix_f32 v84, -v64, v60, v84 op_sel:[0,0,0] op_sel_hi:[0,1,0]
	v_fma_mix_f32 v85, -v64, v60, v85 op_sel:[0,1,0] op_sel_hi:[0,1,0]
	v_fma_mix_f32 v86, -v64, v61, v86 op_sel:[0,0,0] op_sel_hi:[0,1,0]
	v_fma_mix_f32 v87, -v64, v61, v87 op_sel:[0,1,0] op_sel_hi:[0,1,0]
	v_fma_mix_f32 v53, v84, v46, 0 op_sel:[0,0,0] op_sel_hi:[0,1,0]
	v_fma_mix_f32 v59, v84, v40, 0 op_sel:[0,0,0] op_sel_hi:[0,1,0]
	v_fma_mix_f32 v53, v85, v46, v53 op_sel:[0,1,0] op_sel_hi:[0,1,0]
	v_fma_mix_f32 v40, v85, v40, v59 op_sel:[0,1,0] op_sel_hi:[0,1,0]
	v_fma_mix_f32 v53, v86, v47, v53 op_sel:[0,0,0] op_sel_hi:[0,1,0]
	v_fma_mix_f32 v40, v86, v41, v40 op_sel:[0,0,0] op_sel_hi:[0,1,0]
	v_fma_mix_f32 v53, v87, v47, v53 op_sel:[0,1,0] op_sel_hi:[0,1,0]
	v_fma_mix_f32 v40, v87, v41, v40 op_sel:[0,1,0] op_sel_hi:[0,1,0]
	v_fma_mix_f32 v55, v93, v50, 0 op_sel:[1,0,0] op_sel_hi:[1,1,0]
	v_fma_mix_f32 v58, v93, v50, 0 op_sel:[1,1,0] op_sel_hi:[1,1,0]
	v_add_f32_dpp v53, v53, v53 quad_perm:[1,0,3,2] row_mask:0xf bank_mask:0xf bound_ctrl:1
	v_fma_mix_f32 v59, v93, v51, 0 op_sel:[1,0,0] op_sel_hi:[1,1,0]
	v_fma_mix_f32 v60, v93, v51, 0 op_sel:[1,1,0] op_sel_hi:[1,1,0]
	v_add_f32_dpp v53, v53, v53 quad_perm:[2,3,0,1] row_mask:0xf bank_mask:0xf bound_ctrl:1
	v_fma_mix_f32 v84, v84, v44, v55 op_sel:[0,0,0] op_sel_hi:[0,1,0]
	v_fma_mix_f32 v85, v85, v44, v58 op_sel:[0,1,0] op_sel_hi:[0,1,0]
	v_add_f32_dpp v53, v53, v53 row_half_mirror row_mask:0xf bank_mask:0xf bound_ctrl:1
	v_fma_mix_f32 v86, v86, v45, v59 op_sel:[0,0,0] op_sel_hi:[0,1,0]
	v_fma_mix_f32 v87, v87, v45, v60 op_sel:[0,1,0] op_sel_hi:[0,1,0]
	v_add_f32_dpp v53, v53, v53 row_mirror row_mask:0xf bank_mask:0xf bound_ctrl:1
	v_fma_mix_f32 v84, -v53, v48, v84 op_sel:[0,0,0] op_sel_hi:[0,1,0]
	v_fma_mix_f32 v85, -v53, v48, v85 op_sel:[0,1,0] op_sel_hi:[0,1,0]
	v_fma_mix_f32 v86, -v53, v49, v86 op_sel:[0,0,0] op_sel_hi:[0,1,0]
	v_fma_mix_f32 v87, -v53, v49, v87 op_sel:[0,1,0] op_sel_hi:[0,1,0]
	v_fma_mix_f32 v41, v84, v42, 0 op_sel:[0,0,0] op_sel_hi:[0,1,0]
	v_add_u32_e32 v173, 14, v193
	v_fma_mix_f32 v41, v85, v42, v41 op_sel:[0,1,0] op_sel_hi:[0,1,0]
	ds_write_b32 v172, v173 offset:49216
	v_fma_mix_f32 v41, v86, v43, v41 op_sel:[0,0,0] op_sel_hi:[0,1,0]
	v_cndmask_b32_e64 v187, v57, v56, s[38:39]
	v_fma_mix_f32 v41, v87, v43, v41 op_sel:[0,1,0] op_sel_hi:[0,1,0]
	v_cndmask_b32_e64 v188, v56, v57, s[38:39]
	v_cndmask_b32_e64 v189, v41, v40, s[38:39]
	v_cndmask_b32_e64 v190, v40, v41, s[38:39]
	s_waitcnt lgkmcnt(1)
	v_fma_mix_f32 v98, v84, v6, 0 op_sel:[0,0,0] op_sel_hi:[0,1,0]
	v_fma_mix_f32 v98, v85, v6, v98 op_sel:[0,1,0] op_sel_hi:[0,1,0]
	v_add_f32_dpp v188, v188, v187 quad_perm:[1,0,3,2] row_mask:0xf bank_mask:0xf bound_ctrl:1
	v_add_f32_dpp v189, v190, v189 quad_perm:[1,0,3,2] row_mask:0xf bank_mask:0xf bound_ctrl:1
	v_fma_mix_f32 v98, v86, v7, v98 op_sel:[0,0,0] op_sel_hi:[0,1,0]
	v_fma_mix_f32 v98, v87, v7, v98 op_sel:[0,1,0] op_sel_hi:[0,1,0]
	v_cndmask_b32_e64 v191, v189, v188, s[40:41]
	v_cndmask_b32_e64 v192, v188, v189, s[40:41]
	v_fma_mix_f32 v100, v88, v14, 0 op_sel:[0,0,0] op_sel_hi:[1,1,0]
	v_fma_mix_f32 v101, v88, v14, 0 op_sel:[0,1,0] op_sel_hi:[1,1,0]
	v_add_f32_dpp v192, v192, v191 quad_perm:[2,3,0,1] row_mask:0xf bank_mask:0xf bound_ctrl:1
	v_add_f32_dpp v98, v98, v98 quad_perm:[1,0,3,2] row_mask:0xf bank_mask:0xf bound_ctrl:1
	v_fma_mix_f32 v102, v88, v15, 0 op_sel:[0,0,0] op_sel_hi:[1,1,0]
	v_add_f32_dpp v192, v192, v192 row_ror:4 row_mask:0xf bank_mask:0xf bound_ctrl:1
	v_fma_mix_f32 v103, v88, v15, 0 op_sel:[0,1,0] op_sel_hi:[1,1,0]
	v_add_f32_dpp v98, v98, v98 quad_perm:[2,3,0,1] row_mask:0xf bank_mask:0xf bound_ctrl:1
	v_add_f32_dpp v192, v192, v192 row_ror:8 row_mask:0xf bank_mask:0xf bound_ctrl:1
	v_cvt_f16_f32_e32 v192, v192
	global_store_short v83, v192, s[36:37]
	s_add_u32 s36, s36, s44
	s_addc_u32 s37, s37, s45
	ds_read_b128 v[56:59], v194 offset:48128
	ds_read_b128 v[72:75], v194 offset:46080
	ds_read_b128 v[64:67], v194 offset:46336
	ds_read_b128 v[76:79], v194 offset:47104
	ds_read_b128 v[68:71], v194 offset:47360
	ds_read_b128 v[40:43], v194 offset:48384
	ds_read_b128 v[52:55], v194 offset:46592
	ds_read_b128 v[44:47], v194 offset:46848
	ds_read_b128 v[60:63], v194 offset:47616
	ds_read_b128 v[48:51], v194 offset:47872
	ds_read_b64 v[92:93], v195 offset:48640
	v_fma_mix_f32 v84, v84, v4, v100 op_sel:[0,0,0] op_sel_hi:[0,1,0]
	v_fma_mix_f32 v85, v85, v4, v101 op_sel:[0,1,0] op_sel_hi:[0,1,0]
	v_add_f32_dpp v98, v98, v98 row_half_mirror row_mask:0xf bank_mask:0xf bound_ctrl:1
	v_fma_mix_f32 v86, v86, v5, v102 op_sel:[0,0,0] op_sel_hi:[0,1,0]
	v_fma_mix_f32 v87, v87, v5, v103 op_sel:[0,1,0] op_sel_hi:[0,1,0]
	v_add_f32_dpp v98, v98, v98 row_mirror row_mask:0xf bank_mask:0xf bound_ctrl:1
	v_fma_mix_f32 v84, -v98, v12, v84 op_sel:[0,0,0] op_sel_hi:[0,1,0]
	v_fma_mix_f32 v85, -v98, v12, v85 op_sel:[0,1,0] op_sel_hi:[0,1,0]
	v_fma_mix_f32 v86, -v98, v13, v86 op_sel:[0,0,0] op_sel_hi:[0,1,0]
	v_fma_mix_f32 v87, -v98, v13, v87 op_sel:[0,1,0] op_sel_hi:[0,1,0]
	v_fma_mix_f32 v99, v84, v10, 0 op_sel:[0,0,0] op_sel_hi:[0,1,0]
	v_fma_mix_f32 v96, v84, v0, 0 op_sel:[0,0,0] op_sel_hi:[0,1,0]
	v_fma_mix_f32 v99, v85, v10, v99 op_sel:[0,1,0] op_sel_hi:[0,1,0]
	v_fma_mix_f32 v96, v85, v0, v96 op_sel:[0,1,0] op_sel_hi:[0,1,0]
	v_fma_mix_f32 v99, v86, v11, v99 op_sel:[0,0,0] op_sel_hi:[0,1,0]
	v_fma_mix_f32 v96, v86, v1, v96 op_sel:[0,0,0] op_sel_hi:[0,1,0]
	v_fma_mix_f32 v99, v87, v11, v99 op_sel:[0,1,0] op_sel_hi:[0,1,0]
	v_fma_mix_f32 v96, v87, v1, v96 op_sel:[0,1,0] op_sel_hi:[0,1,0]
	v_fma_mix_f32 v101, v88, v18, 0 op_sel:[1,0,0] op_sel_hi:[1,1,0]
	v_fma_mix_f32 v102, v88, v18, 0 op_sel:[1,1,0] op_sel_hi:[1,1,0]
	v_add_f32_dpp v99, v99, v99 quad_perm:[1,0,3,2] row_mask:0xf bank_mask:0xf bound_ctrl:1
	v_fma_mix_f32 v103, v88, v19, 0 op_sel:[1,0,0] op_sel_hi:[1,1,0]
	v_fma_mix_f32 v104, v88, v19, 0 op_sel:[1,1,0] op_sel_hi:[1,1,0]
	v_add_f32_dpp v99, v99, v99 quad_perm:[2,3,0,1] row_mask:0xf bank_mask:0xf bound_ctrl:1
	v_fma_mix_f32 v84, v84, v8, v101 op_sel:[0,0,0] op_sel_hi:[0,1,0]
	v_fma_mix_f32 v85, v85, v8, v102 op_sel:[0,1,0] op_sel_hi:[0,1,0]
	v_add_f32_dpp v99, v99, v99 row_half_mirror row_mask:0xf bank_mask:0xf bound_ctrl:1
	v_fma_mix_f32 v86, v86, v9, v103 op_sel:[0,0,0] op_sel_hi:[0,1,0]
	v_fma_mix_f32 v87, v87, v9, v104 op_sel:[0,1,0] op_sel_hi:[0,1,0]
	v_add_f32_dpp v99, v99, v99 row_mirror row_mask:0xf bank_mask:0xf bound_ctrl:1
	v_fma_mix_f32 v84, -v99, v16, v84 op_sel:[0,0,0] op_sel_hi:[0,1,0]
	v_fma_mix_f32 v85, -v99, v16, v85 op_sel:[0,1,0] op_sel_hi:[0,1,0]
	v_fma_mix_f32 v86, -v99, v17, v86 op_sel:[0,0,0] op_sel_hi:[0,1,0]
	v_fma_mix_f32 v87, -v99, v17, v87 op_sel:[0,1,0] op_sel_hi:[0,1,0]
	v_fma_mix_f32 v100, v84, v26, 0 op_sel:[0,0,0] op_sel_hi:[0,1,0]
	v_fma_mix_f32 v97, v84, v2, 0 op_sel:[0,0,0] op_sel_hi:[0,1,0]
	v_fma_mix_f32 v100, v85, v26, v100 op_sel:[0,1,0] op_sel_hi:[0,1,0]
	v_fma_mix_f32 v97, v85, v2, v97 op_sel:[0,1,0] op_sel_hi:[0,1,0]
	v_fma_mix_f32 v100, v86, v27, v100 op_sel:[0,0,0] op_sel_hi:[0,1,0]
	v_fma_mix_f32 v97, v86, v3, v97 op_sel:[0,0,0] op_sel_hi:[0,1,0]
	v_fma_mix_f32 v100, v87, v27, v100 op_sel:[0,1,0] op_sel_hi:[0,1,0]
	v_fma_mix_f32 v97, v87, v3, v97 op_sel:[0,1,0] op_sel_hi:[0,1,0]
	v_fma_mix_f32 v102, v89, v34, 0 op_sel:[0,0,0] op_sel_hi:[1,1,0]
	v_fma_mix_f32 v103, v89, v34, 0 op_sel:[0,1,0] op_sel_hi:[1,1,0]
	v_add_f32_dpp v100, v100, v100 quad_perm:[1,0,3,2] row_mask:0xf bank_mask:0xf bound_ctrl:1
	v_fma_mix_f32 v104, v89, v35, 0 op_sel:[0,0,0] op_sel_hi:[1,1,0]
	v_fma_mix_f32 v105, v89, v35, 0 op_sel:[0,1,0] op_sel_hi:[1,1,0]
	v_add_f32_dpp v100, v100, v100 quad_perm:[2,3,0,1] row_mask:0xf bank_mask:0xf bound_ctrl:1
	v_fma_mix_f32 v84, v84, v24, v102 op_sel:[0,0,0] op_sel_hi:[0,1,0]
	v_fma_mix_f32 v85, v85, v24, v103 op_sel:[0,1,0] op_sel_hi:[0,1,0]
	v_add_f32_dpp v100, v100, v100 row_half_mirror row_mask:0xf bank_mask:0xf bound_ctrl:1
	v_fma_mix_f32 v86, v86, v25, v104 op_sel:[0,0,0] op_sel_hi:[0,1,0]
	v_fma_mix_f32 v87, v87, v25, v105 op_sel:[0,1,0] op_sel_hi:[0,1,0]
	v_add_f32_dpp v100, v100, v100 row_mirror row_mask:0xf bank_mask:0xf bound_ctrl:1
	v_fma_mix_f32 v84, -v100, v32, v84 op_sel:[0,0,0] op_sel_hi:[0,1,0]
	v_fma_mix_f32 v85, -v100, v32, v85 op_sel:[0,1,0] op_sel_hi:[0,1,0]
	v_fma_mix_f32 v86, -v100, v33, v86 op_sel:[0,0,0] op_sel_hi:[0,1,0]
	v_fma_mix_f32 v87, -v100, v33, v87 op_sel:[0,1,0] op_sel_hi:[0,1,0]
	v_fma_mix_f32 v101, v84, v30, 0 op_sel:[0,0,0] op_sel_hi:[0,1,0]
	v_fma_mix_f32 v98, v84, v20, 0 op_sel:[0,0,0] op_sel_hi:[0,1,0]
	v_fma_mix_f32 v101, v85, v30, v101 op_sel:[0,1,0] op_sel_hi:[0,1,0]
	v_fma_mix_f32 v98, v85, v20, v98 op_sel:[0,1,0] op_sel_hi:[0,1,0]
	v_fma_mix_f32 v101, v86, v31, v101 op_sel:[0,0,0] op_sel_hi:[0,1,0]
	v_fma_mix_f32 v98, v86, v21, v98 op_sel:[0,0,0] op_sel_hi:[0,1,0]
	v_fma_mix_f32 v101, v87, v31, v101 op_sel:[0,1,0] op_sel_hi:[0,1,0]
	v_fma_mix_f32 v98, v87, v21, v98 op_sel:[0,1,0] op_sel_hi:[0,1,0]
	v_fma_mix_f32 v103, v89, v38, 0 op_sel:[1,0,0] op_sel_hi:[1,1,0]
	v_fma_mix_f32 v104, v89, v38, 0 op_sel:[1,1,0] op_sel_hi:[1,1,0]
	v_add_f32_dpp v101, v101, v101 quad_perm:[1,0,3,2] row_mask:0xf bank_mask:0xf bound_ctrl:1
	v_fma_mix_f32 v105, v89, v39, 0 op_sel:[1,0,0] op_sel_hi:[1,1,0]
	v_fma_mix_f32 v119, v89, v39, 0 op_sel:[1,1,0] op_sel_hi:[1,1,0]
	v_add_f32_dpp v101, v101, v101 quad_perm:[2,3,0,1] row_mask:0xf bank_mask:0xf bound_ctrl:1
	v_fma_mix_f32 v84, v84, v28, v103 op_sel:[0,0,0] op_sel_hi:[0,1,0]
	v_fma_mix_f32 v85, v85, v28, v104 op_sel:[0,1,0] op_sel_hi:[0,1,0]
	v_add_f32_dpp v101, v101, v101 row_half_mirror row_mask:0xf bank_mask:0xf bound_ctrl:1
	v_fma_mix_f32 v86, v86, v29, v105 op_sel:[0,0,0] op_sel_hi:[0,1,0]
	v_fma_mix_f32 v87, v87, v29, v119 op_sel:[0,1,0] op_sel_hi:[0,1,0]
	v_add_f32_dpp v101, v101, v101 row_mirror row_mask:0xf bank_mask:0xf bound_ctrl:1
	v_fma_mix_f32 v84, -v101, v36, v84 op_sel:[0,0,0] op_sel_hi:[0,1,0]
	v_fma_mix_f32 v85, -v101, v36, v85 op_sel:[0,1,0] op_sel_hi:[0,1,0]
	v_fma_mix_f32 v86, -v101, v37, v86 op_sel:[0,0,0] op_sel_hi:[0,1,0]
	v_fma_mix_f32 v87, -v101, v37, v87 op_sel:[0,1,0] op_sel_hi:[0,1,0]
	v_fma_mix_f32 v99, v84, v22, 0 op_sel:[0,0,0] op_sel_hi:[0,1,0]
	v_cndmask_b32_e64 v187, v97, v96, s[38:39]
	v_fma_mix_f32 v99, v85, v22, v99 op_sel:[0,1,0] op_sel_hi:[0,1,0]
	v_cndmask_b32_e64 v188, v96, v97, s[38:39]
	v_fma_mix_f32 v99, v86, v23, v99 op_sel:[0,0,0] op_sel_hi:[0,1,0]
	v_fma_mix_f32 v99, v87, v23, v99 op_sel:[0,1,0] op_sel_hi:[0,1,0]
	v_cndmask_b32_e64 v189, v99, v98, s[38:39]
	v_cndmask_b32_e64 v190, v98, v99, s[38:39]
	s_waitcnt lgkmcnt(0)
	v_fma_mix_f32 v98, v84, v74, 0 op_sel:[0,0,0] op_sel_hi:[0,1,0]
	v_fma_mix_f32 v98, v85, v74, v98 op_sel:[0,1,0] op_sel_hi:[0,1,0]
	v_add_f32_dpp v188, v188, v187 quad_perm:[1,0,3,2] row_mask:0xf bank_mask:0xf bound_ctrl:1
	v_add_f32_dpp v189, v190, v189 quad_perm:[1,0,3,2] row_mask:0xf bank_mask:0xf bound_ctrl:1
	v_fma_mix_f32 v98, v86, v75, v98 op_sel:[0,0,0] op_sel_hi:[0,1,0]
	v_fma_mix_f32 v98, v87, v75, v98 op_sel:[0,1,0] op_sel_hi:[0,1,0]
	v_cndmask_b32_e64 v191, v189, v188, s[40:41]
	v_cndmask_b32_e64 v192, v188, v189, s[40:41]
	v_fma_mix_f32 v100, v92, v78, 0 op_sel:[0,0,0] op_sel_hi:[1,1,0]
	v_fma_mix_f32 v101, v92, v78, 0 op_sel:[0,1,0] op_sel_hi:[1,1,0]
	v_add_f32_dpp v192, v192, v191 quad_perm:[2,3,0,1] row_mask:0xf bank_mask:0xf bound_ctrl:1
	v_add_f32_dpp v98, v98, v98 quad_perm:[1,0,3,2] row_mask:0xf bank_mask:0xf bound_ctrl:1
	v_fma_mix_f32 v102, v92, v79, 0 op_sel:[0,0,0] op_sel_hi:[1,1,0]
	v_add_f32_dpp v192, v192, v192 row_ror:4 row_mask:0xf bank_mask:0xf bound_ctrl:1
	v_fma_mix_f32 v103, v92, v79, 0 op_sel:[0,1,0] op_sel_hi:[1,1,0]
	v_add_f32_dpp v98, v98, v98 quad_perm:[2,3,0,1] row_mask:0xf bank_mask:0xf bound_ctrl:1
	v_add_f32_dpp v192, v192, v192 row_ror:8 row_mask:0xf bank_mask:0xf bound_ctrl:1
	v_cvt_f16_f32_e32 v192, v192
	global_store_short v83, v192, s[36:37]
	s_add_u32 s36, s36, s44
	s_addc_u32 s37, s37, s45
	s_cmp_gt_i32 s35, 17
	s_cbranch_scc0 .Lc_poll_A7
.Lc_ret_A7:
	ds_read_b128 v[0:3], v194 offset:2048
	ds_read_b128 v[4:7], v194 offset:0
	ds_read_b128 v[8:11], v194 offset:256
	ds_read_b128 v[12:15], v194 offset:1024
	ds_read_b128 v[16:19], v194 offset:1280
	ds_read_b128 v[20:23], v194 offset:2304
	ds_read_b128 v[24:27], v194 offset:512
	ds_read_b128 v[28:31], v194 offset:768
	ds_read_b128 v[32:35], v194 offset:1536
	ds_read_b128 v[36:39], v194 offset:1792
	ds_read_b64 v[88:89], v195 offset:2560
	v_fma_mix_f32 v84, v84, v72, v100 op_sel:[0,0,0] op_sel_hi:[0,1,0]
	v_fma_mix_f32 v85, v85, v72, v101 op_sel:[0,1,0] op_sel_hi:[0,1,0]
	v_add_f32_dpp v98, v98, v98 row_half_mirror row_mask:0xf bank_mask:0xf bound_ctrl:1
	v_fma_mix_f32 v86, v86, v73, v102 op_sel:[0,0,0] op_sel_hi:[0,1,0]
	v_fma_mix_f32 v87, v87, v73, v103 op_sel:[0,1,0] op_sel_hi:[0,1,0]
	v_add_f32_dpp v98, v98, v98 row_mirror row_mask:0xf bank_mask:0xf bound_ctrl:1
	v_fma_mix_f32 v84, -v98, v76, v84 op_sel:[0,0,0] op_sel_hi:[0,1,0]
	v_fma_mix_f32 v85, -v98, v76, v85 op_sel:[0,1,0] op_sel_hi:[0,1,0]
	v_fma_mix_f32 v86, -v98, v77, v86 op_sel:[0,0,0] op_sel_hi:[0,1,0]
	v_fma_mix_f32 v87, -v98, v77, v87 op_sel:[0,1,0] op_sel_hi:[0,1,0]
	v_fma_mix_f32 v73, v84, v66, 0 op_sel:[0,0,0] op_sel_hi:[0,1,0]
	v_fma_mix_f32 v97, v84, v56, 0 op_sel:[0,0,0] op_sel_hi:[0,1,0]
	v_fma_mix_f32 v73, v85, v66, v73 op_sel:[0,1,0] op_sel_hi:[0,1,0]
	v_fma_mix_f32 v56, v85, v56, v97 op_sel:[0,1,0] op_sel_hi:[0,1,0]
	v_fma_mix_f32 v73, v86, v67, v73 op_sel:[0,0,0] op_sel_hi:[0,1,0]
	v_fma_mix_f32 v56, v86, v57, v56 op_sel:[0,0,0] op_sel_hi:[0,1,0]
	v_fma_mix_f32 v73, v87, v67, v73 op_sel:[0,1,0] op_sel_hi:[0,1,0]
	v_fma_mix_f32 v56, v87, v57, v56 op_sel:[0,1,0] op_sel_hi:[0,1,0]
	v_fma_mix_f32 v75, v92, v70, 0 op_sel:[1,0,0] op_sel_hi:[1,1,0]
; #define RC_WAIT(gq) { if (pseen <= (gq)) { do { pseen = __builtin_amdgcn_readfirstlane(*pflag); if (pseen <= (gq)) __builtin_amdgcn_s_sleep(1); } while (pseen <= (gq)); } asm volatile("" ::: "memory"); }
; DEV void rwkv_consumer(const Params& p, const Ctx& cx, int l, int task, int lane, const char* ring, int widx) {
;     ...
;   RC_WAIT(0); RC_LOAD(A, 0);
; #pragma unroll 1
;   for (int g = 0; g < RW_NG; g += 2) {
;     RC_WAIT(g + 1); RC_LOAD(B, g + 1);
;     RC_COMP(A, g);
;     if (g + 2 < RW_NG) { RC_WAIT(g + 2); RC_LOAD(A, g + 2); }
;     RC_COMP(B, g + 1);
;   }
	v_fma_mix_f32 v76, v92, v70, 0 op_sel:[1,1,0] op_sel_hi:[1,1,0]
	v_add_f32_dpp v73, v73, v73 quad_perm:[1,0,3,2] row_mask:0xf bank_mask:0xf bound_ctrl:1
	v_fma_mix_f32 v77, v92, v71, 0 op_sel:[1,0,0] op_sel_hi:[1,1,0]
	v_fma_mix_f32 v78, v92, v71, 0 op_sel:[1,1,0] op_sel_hi:[1,1,0]
	v_add_f32_dpp v73, v73, v73 quad_perm:[2,3,0,1] row_mask:0xf bank_mask:0xf bound_ctrl:1
	v_fma_mix_f32 v84, v84, v64, v75 op_sel:[0,0,0] op_sel_hi:[0,1,0]
	v_fma_mix_f32 v85, v85, v64, v76 op_sel:[0,1,0] op_sel_hi:[0,1,0]
	v_add_f32_dpp v73, v73, v73 row_half_mirror row_mask:0xf bank_mask:0xf bound_ctrl:1
	v_fma_mix_f32 v86, v86, v65, v77 op_sel:[0,0,0] op_sel_hi:[0,1,0]
	v_fma_mix_f32 v87, v87, v65, v78 op_sel:[0,1,0] op_sel_hi:[0,1,0]
	v_add_f32_dpp v73, v73, v73 row_mirror row_mask:0xf bank_mask:0xf bound_ctrl:1
	v_fma_mix_f32 v84, -v73, v68, v84 op_sel:[0,0,0] op_sel_hi:[0,1,0]
	v_fma_mix_f32 v85, -v73, v68, v85 op_sel:[0,1,0] op_sel_hi:[0,1,0]
	v_fma_mix_f32 v86, -v73, v69, v86 op_sel:[0,0,0] op_sel_hi:[0,1,0]
	v_fma_mix_f32 v87, -v73, v69, v87 op_sel:[0,1,0] op_sel_hi:[0,1,0]
	v_fma_mix_f32 v64, v84, v54, 0 op_sel:[0,0,0] op_sel_hi:[0,1,0]
	v_fma_mix_f32 v57, v84, v58, 0 op_sel:[0,0,0] op_sel_hi:[0,1,0]
	v_fma_mix_f32 v64, v85, v54, v64 op_sel:[0,1,0] op_sel_hi:[0,1,0]
	v_fma_mix_f32 v57, v85, v58, v57 op_sel:[0,1,0] op_sel_hi:[0,1,0]
	v_fma_mix_f32 v64, v86, v55, v64 op_sel:[0,0,0] op_sel_hi:[0,1,0]
	v_fma_mix_f32 v57, v86, v59, v57 op_sel:[0,0,0] op_sel_hi:[0,1,0]
	v_fma_mix_f32 v64, v87, v55, v64 op_sel:[0,1,0] op_sel_hi:[0,1,0]
	v_fma_mix_f32 v57, v87, v59, v57 op_sel:[0,1,0] op_sel_hi:[0,1,0]
	v_fma_mix_f32 v66, v93, v62, 0 op_sel:[0,0,0] op_sel_hi:[1,1,0]
	v_fma_mix_f32 v67, v93, v62, 0 op_sel:[0,1,0] op_sel_hi:[1,1,0]
	v_add_f32_dpp v64, v64, v64 quad_perm:[1,0,3,2] row_mask:0xf bank_mask:0xf bound_ctrl:1
	v_fma_mix_f32 v68, v93, v63, 0 op_sel:[0,0,0] op_sel_hi:[1,1,0]
	v_fma_mix_f32 v69, v93, v63, 0 op_sel:[0,1,0] op_sel_hi:[1,1,0]
	v_add_f32_dpp v64, v64, v64 quad_perm:[2,3,0,1] row_mask:0xf bank_mask:0xf bound_ctrl:1
	v_fma_mix_f32 v84, v84, v52, v66 op_sel:[0,0,0] op_sel_hi:[0,1,0]
	v_fma_mix_f32 v85, v85, v52, v67 op_sel:[0,1,0] op_sel_hi:[0,1,0]
	v_add_f32_dpp v64, v64, v64 row_half_mirror row_mask:0xf bank_mask:0xf bound_ctrl:1
	v_fma_mix_f32 v86, v86, v53, v68 op_sel:[0,0,0] op_sel_hi:[0,1,0]
	v_fma_mix_f32 v87, v87, v53, v69 op_sel:[0,1,0] op_sel_hi:[0,1,0]
	v_add_f32_dpp v64, v64, v64 row_mirror row_mask:0xf bank_mask:0xf bound_ctrl:1
	v_fma_mix_f32 v84, -v64, v60, v84 op_sel:[0,0,0] op_sel_hi:[0,1,0]
	v_fma_mix_f32 v85, -v64, v60, v85 op_sel:[0,1,0] op_sel_hi:[0,1,0]
	v_fma_mix_f32 v86, -v64, v61, v86 op_sel:[0,0,0] op_sel_hi:[0,1,0]
	v_fma_mix_f32 v87, -v64, v61, v87 op_sel:[0,1,0] op_sel_hi:[0,1,0]
	v_fma_mix_f32 v53, v84, v46, 0 op_sel:[0,0,0] op_sel_hi:[0,1,0]
	v_fma_mix_f32 v59, v84, v40, 0 op_sel:[0,0,0] op_sel_hi:[0,1,0]
	v_fma_mix_f32 v53, v85, v46, v53 op_sel:[0,1,0] op_sel_hi:[0,1,0]
	v_fma_mix_f32 v40, v85, v40, v59 op_sel:[0,1,0] op_sel_hi:[0,1,0]
	v_fma_mix_f32 v53, v86, v47, v53 op_sel:[0,0,0] op_sel_hi:[0,1,0]
	v_fma_mix_f32 v40, v86, v41, v40 op_sel:[0,0,0] op_sel_hi:[0,1,0]
	v_fma_mix_f32 v53, v87, v47, v53 op_sel:[0,1,0] op_sel_hi:[0,1,0]
	v_fma_mix_f32 v40, v87, v41, v40 op_sel:[0,1,0] op_sel_hi:[0,1,0]
	v_fma_mix_f32 v55, v93, v50, 0 op_sel:[1,0,0] op_sel_hi:[1,1,0]
	v_fma_mix_f32 v58, v93, v50, 0 op_sel:[1,1,0] op_sel_hi:[1,1,0]
	v_add_f32_dpp v53, v53, v53 quad_perm:[1,0,3,2] row_mask:0xf bank_mask:0xf bound_ctrl:1
	v_fma_mix_f32 v59, v93, v51, 0 op_sel:[1,0,0] op_sel_hi:[1,1,0]
	v_fma_mix_f32 v60, v93, v51, 0 op_sel:[1,1,0] op_sel_hi:[1,1,0]
	v_add_f32_dpp v53, v53, v53 quad_perm:[2,3,0,1] row_mask:0xf bank_mask:0xf bound_ctrl:1
	v_fma_mix_f32 v84, v84, v44, v55 op_sel:[0,0,0] op_sel_hi:[0,1,0]
	v_fma_mix_f32 v85, v85, v44, v58 op_sel:[0,1,0] op_sel_hi:[0,1,0]
	v_add_f32_dpp v53, v53, v53 row_half_mirror row_mask:0xf bank_mask:0xf bound_ctrl:1
	v_fma_mix_f32 v86, v86, v45, v59 op_sel:[0,0,0] op_sel_hi:[0,1,0]
	v_fma_mix_f32 v87, v87, v45, v60 op_sel:[0,1,0] op_sel_hi:[0,1,0]
	v_add_f32_dpp v53, v53, v53 row_mirror row_mask:0xf bank_mask:0xf bound_ctrl:1
	v_fma_mix_f32 v84, -v53, v48, v84 op_sel:[0,0,0] op_sel_hi:[0,1,0]
	v_fma_mix_f32 v85, -v53, v48, v85 op_sel:[0,1,0] op_sel_hi:[0,1,0]
	v_fma_mix_f32 v86, -v53, v49, v86 op_sel:[0,0,0] op_sel_hi:[0,1,0]
	v_fma_mix_f32 v87, -v53, v49, v87 op_sel:[0,1,0] op_sel_hi:[0,1,0]
	v_fma_mix_f32 v41, v84, v42, 0 op_sel:[0,0,0] op_sel_hi:[0,1,0]
	v_add_u32_e32 v173, 16, v193
	v_fma_mix_f32 v41, v85, v42, v41 op_sel:[0,1,0] op_sel_hi:[0,1,0]
	ds_write_b32 v172, v173 offset:49216
	v_fma_mix_f32 v41, v86, v43, v41 op_sel:[0,0,0] op_sel_hi:[0,1,0]
	v_cndmask_b32_e64 v187, v57, v56, s[38:39]
	v_fma_mix_f32 v41, v87, v43, v41 op_sel:[0,1,0] op_sel_hi:[0,1,0]
	v_cndmask_b32_e64 v188, v56, v57, s[38:39]
	v_cndmask_b32_e64 v189, v41, v40, s[38:39]
	v_cndmask_b32_e64 v190, v40, v41, s[38:39]
	s_waitcnt lgkmcnt(1)
	v_fma_mix_f32 v98, v84, v6, 0 op_sel:[0,0,0] op_sel_hi:[0,1,0]
	v_fma_mix_f32 v98, v85, v6, v98 op_sel:[0,1,0] op_sel_hi:[0,1,0]
	v_add_f32_dpp v188, v188, v187 quad_perm:[1,0,3,2] row_mask:0xf bank_mask:0xf bound_ctrl:1
	v_add_f32_dpp v189, v190, v189 quad_perm:[1,0,3,2] row_mask:0xf bank_mask:0xf bound_ctrl:1
	v_fma_mix_f32 v98, v86, v7, v98 op_sel:[0,0,0] op_sel_hi:[0,1,0]
	v_fma_mix_f32 v98, v87, v7, v98 op_sel:[0,1,0] op_sel_hi:[0,1,0]
	v_cndmask_b32_e64 v191, v189, v188, s[40:41]
	v_cndmask_b32_e64 v192, v188, v189, s[40:41]
	v_fma_mix_f32 v100, v88, v14, 0 op_sel:[0,0,0] op_sel_hi:[1,1,0]
	v_fma_mix_f32 v101, v88, v14, 0 op_sel:[0,1,0] op_sel_hi:[1,1,0]
	v_add_f32_dpp v192, v192, v191 quad_perm:[2,3,0,1] row_mask:0xf bank_mask:0xf bound_ctrl:1
	v_add_f32_dpp v98, v98, v98 quad_perm:[1,0,3,2] row_mask:0xf bank_mask:0xf bound_ctrl:1
	v_fma_mix_f32 v102, v88, v15, 0 op_sel:[0,0,0] op_sel_hi:[1,1,0]
	v_add_f32_dpp v192, v192, v192 row_ror:4 row_mask:0xf bank_mask:0xf bound_ctrl:1
	v_fma_mix_f32 v103, v88, v15, 0 op_sel:[0,1,0] op_sel_hi:[1,1,0]
	v_add_f32_dpp v98, v98, v98 quad_perm:[2,3,0,1] row_mask:0xf bank_mask:0xf bound_ctrl:1
	v_add_f32_dpp v192, v192, v192 row_ror:8 row_mask:0xf bank_mask:0xf bound_ctrl:1
	v_cvt_f16_f32_e32 v192, v192
	global_store_short v83, v192, s[36:37]
	s_add_u32 s36, s36, s44
	s_addc_u32 s37, s37, s45
	ds_read_b128 v[56:59], v194 offset:5120
	ds_read_b128 v[72:75], v194 offset:3072
	ds_read_b128 v[64:67], v194 offset:3328
	ds_read_b128 v[76:79], v194 offset:4096
	ds_read_b128 v[68:71], v194 offset:4352
	ds_read_b128 v[40:43], v194 offset:5376
	ds_read_b128 v[52:55], v194 offset:3584
	ds_read_b128 v[44:47], v194 offset:3840
	ds_read_b128 v[60:63], v194 offset:4608
	ds_read_b128 v[48:51], v194 offset:4864
	ds_read_b64 v[92:93], v195 offset:5632
	s_add_i32 s33, s33, 16
	s_sub_i32 s35, s35, 16
	v_mov_b32_e32 v193, s33
	s_cmp_eq_u32 s33, 64
	s_cbranch_scc1 .Lc_fix

.Lc_fix:
	s_mov_b64 s[36:37], s[88:89]
	s_branch .Lc_fixret
.Lc_poll_A0:
.Lc_pollx_A0:
	ds_read_b32 v173, v161 offset:49152
	s_waitcnt lgkmcnt(0)
	v_readfirstlane_b32 s0, v173
	s_sub_i32 s35, s0, s33
	s_cmp_gt_i32 s35, 3
	s_cbranch_scc1 .Lc_ret_A0
	s_sleep 1
	s_branch .Lc_pollx_A0
.Lc_poll_A1:
.Lc_pollx_A1:
	ds_read_b32 v173, v161 offset:49152
	s_waitcnt lgkmcnt(0)
	v_readfirstlane_b32 s0, v173
	s_sub_i32 s35, s0, s33
	s_cmp_gt_i32 s35, 5
	s_cbranch_scc1 .Lc_ret_A1
	s_sleep 1
	s_branch .Lc_pollx_A1
.Lc_poll_A2:
.Lc_pollx_A2:
	ds_read_b32 v173, v161 offset:49152
	s_waitcnt lgkmcnt(0)
	v_readfirstlane_b32 s0, v173
	s_sub_i32 s35, s0, s33
	s_cmp_gt_i32 s35, 7
	s_cbranch_scc1 .Lc_ret_A2
	s_sleep 1
	s_branch .Lc_pollx_A2
.Lc_poll_A3:
.Lc_pollx_A3:
	ds_read_b32 v173, v161 offset:49152
	s_waitcnt lgkmcnt(0)
	v_readfirstlane_b32 s0, v173
	s_sub_i32 s35, s0, s33
	s_cmp_gt_i32 s35, 9
	s_cbranch_scc1 .Lc_ret_A3
	s_sleep 1
	s_branch .Lc_pollx_A3
.Lc_poll_A4:
.Lc_pollx_A4:
	ds_read_b32 v173, v161 offset:49152
	s_waitcnt lgkmcnt(0)
	v_readfirstlane_b32 s0, v173
	s_sub_i32 s35, s0, s33
	s_cmp_gt_i32 s35, 11
	s_cbranch_scc1 .Lc_ret_A4
	s_sleep 1
	s_branch .Lc_pollx_A4
.Lc_poll_A5:
.Lc_pollx_A5:
	ds_read_b32 v173, v161 offset:49152
	s_waitcnt lgkmcnt(0)
	v_readfirstlane_b32 s0, v173
	s_sub_i32 s35, s0, s33
	s_cmp_gt_i32 s35, 13
	s_cbranch_scc1 .Lc_ret_A5
	s_sleep 1
	s_branch .Lc_pollx_A5
.Lc_poll_A6:
.Lc_pollx_A6:
	ds_read_b32 v173, v161 offset:49152
	s_waitcnt lgkmcnt(0)
	v_readfirstlane_b32 s0, v173
	s_sub_i32 s35, s0, s33
	s_cmp_gt_i32 s35, 15
	s_cbranch_scc1 .Lc_ret_A6
	s_sleep 1
	s_branch .Lc_pollx_A6
